# ada_item and bias2_item k-loops: 16-load prefetch ring (8 trips lookahead) instead of wait-per-trip; plus G6 pipelined epilogue
# speedup vs baseline: 1.0171x; 1.0171x over previous
; #define LAS __attribute__((address_space(3)))
; #define LDS_WAIT() asm volatile("s_waitcnt lgkmcnt(0)" ::: "memory")
; DI float sigmoidf_(float v) { return __builtin_amdgcn_rcpf(1.0f + __expf(-v)); }
; DI void ada_item(const float* c, const float* wada, const float* bada, float* ada, LAS float* scr, int item, int lane) {
;     const int cb = item % 96, kc = item / 96;
; #pragma unroll 4
;     for (int i = 0; i < 64; ++i) { const int idx = i * 64 + lane, k = idx >> 5, b = idx & 31; const float v = c[b * 1024 + kc * 128 + k]; scr[idx] = v * sigmoidf_(v); }
;     LDS_WAIT(); asm volatile("" ::: "memory");
;     float acc[32];
; #pragma unroll
;     for (int b = 0; b < 32; ++b) acc[b] = 0.f;
;     const float* wp = wada + (size_t)(kc * 128) * 6144 + cb * 64 + lane;
; #pragma unroll 2
;     for (int k = 0; k < 128; ++k) { const float w = wp[(size_t)k * 6144];
; #pragma unroll
;         for (int b4 = 0; b4 < 8; ++b4) { const f32x4 sv = *(const LAS f32x4*)(scr + k * 32 + b4 * 4);
;             acc[4 * b4] += sv[0] * w; acc[4 * b4 + 1] += sv[1] * w; acc[4 * b4 + 2] += sv[2] * w; acc[4 * b4 + 3] += sv[3] * w; } }
.LBB0_61:
	v_add_u32_e32 v44, s3, v42
	v_add_u32_e32 v46, s3, v41
	v_add_u32_e32 v48, s3, v39
	v_add_u32_e32 v50, s3, v6
	v_ashrrev_i32_e32 v45, 31, v44
	v_ashrrev_i32_e32 v47, 31, v46
	v_ashrrev_i32_e32 v49, 31, v48
	v_ashrrev_i32_e32 v51, 31, v50
	v_lshl_add_u64 v[44:45], v[44:45], 2, s[54:55]
	v_lshl_add_u64 v[46:47], v[46:47], 2, s[54:55]
	v_lshl_add_u64 v[48:49], v[48:49], 2, s[54:55]
	v_lshl_add_u64 v[50:51], v[50:51], 2, s[54:55]
	global_load_dword v44, v[44:45], off
	s_nop 0
	global_load_dword v45, v[46:47], off
	s_nop 0
	global_load_dword v46, v[48:49], off
	global_load_dword v47, v[50:51], off
	s_add_i32 s3, s3, 8
	s_cmpk_eq_i32 s3, 0x80
	s_waitcnt vmcnt(3)
	v_mul_f32_e32 v48, 0xbfb8aa3b, v44
	s_waitcnt vmcnt(2)
	v_mul_f32_e32 v49, 0xbfb8aa3b, v45
	s_waitcnt vmcnt(1)
	v_mul_f32_e32 v50, 0xbfb8aa3b, v46
	s_waitcnt vmcnt(0)
	v_mul_f32_e32 v51, 0xbfb8aa3b, v47
	v_exp_f32_e32 v48, v48
	v_exp_f32_e32 v49, v49
	v_exp_f32_e32 v50, v50
	v_exp_f32_e32 v51, v51
	v_add_f32_e32 v48, 1.0, v48
	v_add_f32_e32 v49, 1.0, v49
	v_add_f32_e32 v50, 1.0, v50
	v_add_f32_e32 v51, 1.0, v51
	v_rcp_f32_e32 v48, v48
	v_rcp_f32_e32 v49, v49
	v_rcp_f32_e32 v50, v50
	v_rcp_f32_e32 v51, v51
	v_mul_f32_e32 v44, v44, v48
	v_mul_f32_e32 v45, v45, v49
	v_mul_f32_e32 v46, v46, v50
	v_mul_f32_e32 v47, v47, v51
	ds_write2st64_b32 v43, v44, v45 offset1:1
	ds_write2st64_b32 v43, v46, v47 offset0:2 offset1:3
	v_add_u32_e32 v43, 0x400, v43
	s_cbranch_scc0 .LBB0_61
	s_mulk_i32 s2, 0x60
	s_sub_i32 s2, s12, s2
	s_mul_hi_i32 s3, s0, 0x6000
	s_mulk_i32 s0, 0x6000
	s_add_u32 s0, s56, s0
	s_addc_u32 s25, s57, s3
	s_lshl_b32 s2, s2, 6
	s_ashr_i32 s3, s2, 31
	s_waitcnt lgkmcnt(0)
	s_lshl_b64 s[26:27], s[2:3], 2
	s_add_u32 s26, s0, s26
	s_addc_u32 s27, s25, s27
	v_mov_b32_e32 v41, v7
	v_mov_b32_e32 v42, 0
	v_lshl_add_u64 v[74:75], s[26:27], 0, v[40:41]
	s_mov_b32 s0, 0
	v_mov_b32_e32 v43, v42
	v_mov_b32_e32 v72, v42
	v_mov_b32_e32 v73, v42
	v_mov_b32_e32 v70, v42
	v_mov_b32_e32 v71, v42
	v_mov_b32_e32 v68, v42
	v_mov_b32_e32 v69, v42
	v_mov_b32_e32 v66, v42
	v_mov_b32_e32 v67, v42
	v_mov_b32_e32 v64, v42
	v_mov_b32_e32 v65, v42
	v_mov_b32_e32 v62, v42
	v_mov_b32_e32 v63, v42
	v_mov_b32_e32 v60, v42
	v_mov_b32_e32 v61, v42
	v_mov_b32_e32 v58, v42
	v_mov_b32_e32 v59, v42
	v_mov_b32_e32 v56, v42
	v_mov_b32_e32 v57, v42
	v_mov_b32_e32 v54, v42
	v_mov_b32_e32 v55, v42
	v_mov_b32_e32 v52, v42
	v_mov_b32_e32 v53, v42
	v_mov_b32_e32 v50, v42
	v_mov_b32_e32 v51, v42
	v_mov_b32_e32 v48, v42
	v_mov_b32_e32 v49, v42
	v_mov_b32_e32 v46, v42
	v_mov_b32_e32 v47, v42
	v_mov_b32_e32 v44, v42
	v_mov_b32_e32 v45, v42
	v_mov_b32_e32 v184, v74
	v_mov_b32_e32 v185, v75
	global_load_dword v152, v[184:185], off
	v_add_co_u32_e32 v186, vcc, s23, v184
	s_nop 1
	v_addc_co_u32_e32 v187, vcc, 0, v185, vcc
	global_load_dword v154, v[186:187], off
	v_lshl_add_u64 v[184:185], v[184:185], 0, s[8:9]
	global_load_dword v156, v[184:185], off
	v_add_co_u32_e32 v186, vcc, s23, v184
	s_nop 1
	v_addc_co_u32_e32 v187, vcc, 0, v185, vcc
	global_load_dword v158, v[186:187], off
	v_lshl_add_u64 v[184:185], v[184:185], 0, s[8:9]
	global_load_dword v160, v[184:185], off
	v_add_co_u32_e32 v186, vcc, s23, v184
	s_nop 1
	v_addc_co_u32_e32 v187, vcc, 0, v185, vcc
	global_load_dword v162, v[186:187], off
	v_lshl_add_u64 v[184:185], v[184:185], 0, s[8:9]
	global_load_dword v164, v[184:185], off
	v_add_co_u32_e32 v186, vcc, s23, v184
	s_nop 1
	v_addc_co_u32_e32 v187, vcc, 0, v185, vcc
	global_load_dword v166, v[186:187], off
	v_lshl_add_u64 v[184:185], v[184:185], 0, s[8:9]
	global_load_dword v168, v[184:185], off
	v_add_co_u32_e32 v186, vcc, s23, v184
	s_nop 1
	v_addc_co_u32_e32 v187, vcc, 0, v185, vcc
	global_load_dword v170, v[186:187], off
	v_lshl_add_u64 v[184:185], v[184:185], 0, s[8:9]
	global_load_dword v172, v[184:185], off
	v_add_co_u32_e32 v186, vcc, s23, v184
	s_nop 1
	v_addc_co_u32_e32 v187, vcc, 0, v185, vcc
	global_load_dword v174, v[186:187], off
	v_lshl_add_u64 v[184:185], v[184:185], 0, s[8:9]
	global_load_dword v176, v[184:185], off
	v_add_co_u32_e32 v186, vcc, s23, v184
	s_nop 1
	v_addc_co_u32_e32 v187, vcc, 0, v185, vcc
	global_load_dword v178, v[186:187], off
	v_lshl_add_u64 v[184:185], v[184:185], 0, s[8:9]
	global_load_dword v180, v[184:185], off
	v_add_co_u32_e32 v186, vcc, s23, v184
	s_nop 1
	v_addc_co_u32_e32 v187, vcc, 0, v185, vcc
	global_load_dword v182, v[186:187], off
	v_lshl_add_u64 v[184:185], v[184:185], 0, s[8:9]
; #define LAS __attribute__((address_space(3)))
; DI void ada_item(const float* c, const float* wada, const float* bada, float* ada, LAS float* scr, int item, int lane) {
;     ...
; #pragma unroll 2
;     for (int k = 0; k < 128; ++k) { const float w = wp[(size_t)k * 6144];
; #pragma unroll
;         for (int b4 = 0; b4 < 8; ++b4) { const f32x4 sv = *(const LAS f32x4*)(scr + k * 32 + b4 * 4);
;             acc[4 * b4] += sv[0] * w; acc[4 * b4 + 1] += sv[1] * w; acc[4 * b4 + 2] += sv[2] * w; acc[4 * b4 + 3] += sv[3] * w; } }
.LBB0_63:
	s_add_i32 s3, s13, s0
	v_mov_b32_e32 v39, s3
	ds_read_b128 v[86:89], v39
	ds_read_b128 v[90:93], v39 offset:16
	ds_read_b128 v[94:97], v39 offset:32
	ds_read_b128 v[98:101], v39 offset:48
	ds_read_b128 v[102:105], v39 offset:64
	ds_read_b128 v[106:109], v39 offset:80
	ds_read_b128 v[110:113], v39 offset:96
	ds_read_b128 v[114:117], v39 offset:112
	ds_read_b128 v[118:121], v39 offset:128
	ds_read_b128 v[122:125], v39 offset:144
	ds_read_b128 v[126:129], v39 offset:160
	ds_read_b128 v[130:133], v39 offset:176
	ds_read_b128 v[134:137], v39 offset:192
	ds_read_b128 v[138:141], v39 offset:208
	ds_read_b128 v[142:145], v39 offset:224
	ds_read_b128 v[146:149], v39 offset:240
	s_addk_i32 s0, 0x100
	v_lshl_add_u64 v[74:75], v[74:75], 0, s[8:9]
	s_waitcnt vmcnt(14) lgkmcnt(14)
	v_pk_fma_f32 v[72:73], v[152:153], v[86:87], v[72:73] op_sel_hi:[0,1,1]
	v_pk_fma_f32 v[70:71], v[152:153], v[88:89], v[70:71] op_sel_hi:[0,1,1]
	v_pk_fma_f32 v[68:69], v[152:153], v[90:91], v[68:69] op_sel_hi:[0,1,1]
	v_pk_fma_f32 v[66:67], v[152:153], v[92:93], v[66:67] op_sel_hi:[0,1,1]
	s_waitcnt lgkmcnt(13)
	v_pk_fma_f32 v[64:65], v[152:153], v[94:95], v[64:65] op_sel_hi:[0,1,1]
	v_pk_fma_f32 v[62:63], v[152:153], v[96:97], v[62:63] op_sel_hi:[0,1,1]
	s_waitcnt lgkmcnt(12)
	v_pk_fma_f32 v[60:61], v[152:153], v[98:99], v[60:61] op_sel_hi:[0,1,1]
	v_pk_fma_f32 v[58:59], v[152:153], v[100:101], v[58:59] op_sel_hi:[0,1,1]
	s_waitcnt lgkmcnt(11)
	v_pk_fma_f32 v[56:57], v[152:153], v[102:103], v[56:57] op_sel_hi:[0,1,1]
	v_pk_fma_f32 v[54:55], v[152:153], v[104:105], v[54:55] op_sel_hi:[0,1,1]
	s_waitcnt lgkmcnt(10)
	v_pk_fma_f32 v[52:53], v[152:153], v[106:107], v[52:53] op_sel_hi:[0,1,1]
	v_pk_fma_f32 v[50:51], v[152:153], v[108:109], v[50:51] op_sel_hi:[0,1,1]
	s_waitcnt lgkmcnt(9)
	v_pk_fma_f32 v[48:49], v[152:153], v[110:111], v[48:49] op_sel_hi:[0,1,1]
	v_pk_fma_f32 v[46:47], v[152:153], v[112:113], v[46:47] op_sel_hi:[0,1,1]
	s_waitcnt lgkmcnt(8)
	v_pk_fma_f32 v[44:45], v[152:153], v[114:115], v[44:45] op_sel_hi:[0,1,1]
	v_pk_fma_f32 v[42:43], v[152:153], v[116:117], v[42:43] op_sel_hi:[0,1,1]
	s_waitcnt lgkmcnt(7)
	v_pk_fma_f32 v[72:73], v[154:155], v[118:119], v[72:73] op_sel_hi:[0,1,1]
	v_pk_fma_f32 v[70:71], v[154:155], v[120:121], v[70:71] op_sel_hi:[0,1,1]
	s_waitcnt lgkmcnt(6)
	v_pk_fma_f32 v[68:69], v[154:155], v[122:123], v[68:69] op_sel_hi:[0,1,1]
	v_pk_fma_f32 v[66:67], v[154:155], v[124:125], v[66:67] op_sel_hi:[0,1,1]
	s_waitcnt lgkmcnt(5)
	v_pk_fma_f32 v[64:65], v[154:155], v[126:127], v[64:65] op_sel_hi:[0,1,1]
	v_pk_fma_f32 v[62:63], v[154:155], v[128:129], v[62:63] op_sel_hi:[0,1,1]
	s_waitcnt lgkmcnt(4)
	v_pk_fma_f32 v[60:61], v[154:155], v[130:131], v[60:61] op_sel_hi:[0,1,1]
	v_pk_fma_f32 v[58:59], v[154:155], v[132:133], v[58:59] op_sel_hi:[0,1,1]
	s_waitcnt lgkmcnt(3)
	v_pk_fma_f32 v[56:57], v[154:155], v[134:135], v[56:57] op_sel_hi:[0,1,1]
	v_pk_fma_f32 v[54:55], v[154:155], v[136:137], v[54:55] op_sel_hi:[0,1,1]
	s_waitcnt lgkmcnt(2)
	v_pk_fma_f32 v[52:53], v[154:155], v[138:139], v[52:53] op_sel_hi:[0,1,1]
	v_pk_fma_f32 v[50:51], v[154:155], v[140:141], v[50:51] op_sel_hi:[0,1,1]
	s_waitcnt lgkmcnt(1)
	v_pk_fma_f32 v[48:49], v[154:155], v[142:143], v[48:49] op_sel_hi:[0,1,1]
	v_pk_fma_f32 v[46:47], v[154:155], v[144:145], v[46:47] op_sel_hi:[0,1,1]
	s_waitcnt lgkmcnt(0)
	v_pk_fma_f32 v[44:45], v[154:155], v[146:147], v[44:45] op_sel_hi:[0,1,1]
	v_pk_fma_f32 v[42:43], v[154:155], v[148:149], v[42:43] op_sel_hi:[0,1,1]
	global_load_dword v152, v[184:185], off
	v_add_co_u32_e32 v186, vcc, s23, v184
	s_nop 1
	v_addc_co_u32_e32 v187, vcc, 0, v185, vcc
	global_load_dword v154, v[186:187], off
	v_lshl_add_u64 v[184:185], v[184:185], 0, s[8:9]
	s_add_i32 s3, s13, s0
	v_mov_b32_e32 v39, s3
	ds_read_b128 v[86:89], v39
	ds_read_b128 v[90:93], v39 offset:16
	ds_read_b128 v[94:97], v39 offset:32
	ds_read_b128 v[98:101], v39 offset:48
	ds_read_b128 v[102:105], v39 offset:64
	ds_read_b128 v[106:109], v39 offset:80
	ds_read_b128 v[110:113], v39 offset:96
	ds_read_b128 v[114:117], v39 offset:112
	ds_read_b128 v[118:121], v39 offset:128
	ds_read_b128 v[122:125], v39 offset:144
	ds_read_b128 v[126:129], v39 offset:160
	ds_read_b128 v[130:133], v39 offset:176
	ds_read_b128 v[134:137], v39 offset:192
	ds_read_b128 v[138:141], v39 offset:208
	ds_read_b128 v[142:145], v39 offset:224
	ds_read_b128 v[146:149], v39 offset:240
	s_addk_i32 s0, 0x100
	v_lshl_add_u64 v[74:75], v[74:75], 0, s[8:9]
	s_waitcnt vmcnt(14) lgkmcnt(14)
	v_pk_fma_f32 v[72:73], v[156:157], v[86:87], v[72:73] op_sel_hi:[0,1,1]
	v_pk_fma_f32 v[70:71], v[156:157], v[88:89], v[70:71] op_sel_hi:[0,1,1]
	v_pk_fma_f32 v[68:69], v[156:157], v[90:91], v[68:69] op_sel_hi:[0,1,1]
	v_pk_fma_f32 v[66:67], v[156:157], v[92:93], v[66:67] op_sel_hi:[0,1,1]
	s_waitcnt lgkmcnt(13)
	v_pk_fma_f32 v[64:65], v[156:157], v[94:95], v[64:65] op_sel_hi:[0,1,1]
	v_pk_fma_f32 v[62:63], v[156:157], v[96:97], v[62:63] op_sel_hi:[0,1,1]
	s_waitcnt lgkmcnt(12)
	v_pk_fma_f32 v[60:61], v[156:157], v[98:99], v[60:61] op_sel_hi:[0,1,1]
	v_pk_fma_f32 v[58:59], v[156:157], v[100:101], v[58:59] op_sel_hi:[0,1,1]
	s_waitcnt lgkmcnt(11)
	v_pk_fma_f32 v[56:57], v[156:157], v[102:103], v[56:57] op_sel_hi:[0,1,1]
	v_pk_fma_f32 v[54:55], v[156:157], v[104:105], v[54:55] op_sel_hi:[0,1,1]
	s_waitcnt lgkmcnt(10)
	v_pk_fma_f32 v[52:53], v[156:157], v[106:107], v[52:53] op_sel_hi:[0,1,1]
	v_pk_fma_f32 v[50:51], v[156:157], v[108:109], v[50:51] op_sel_hi:[0,1,1]
	s_waitcnt lgkmcnt(9)
	v_pk_fma_f32 v[48:49], v[156:157], v[110:111], v[48:49] op_sel_hi:[0,1,1]
	v_pk_fma_f32 v[46:47], v[156:157], v[112:113], v[46:47] op_sel_hi:[0,1,1]
	s_waitcnt lgkmcnt(8)
; #define LAS __attribute__((address_space(3)))
; DI void ada_item(const float* c, const float* wada, const float* bada, float* ada, LAS float* scr, int item, int lane) {
;     ...
; #pragma unroll 2
;     for (int k = 0; k < 128; ++k) { const float w = wp[(size_t)k * 6144];
; #pragma unroll
;         for (int b4 = 0; b4 < 8; ++b4) { const f32x4 sv = *(const LAS f32x4*)(scr + k * 32 + b4 * 4);
;             acc[4 * b4] += sv[0] * w; acc[4 * b4 + 1] += sv[1] * w; acc[4 * b4 + 2] += sv[2] * w; acc[4 * b4 + 3] += sv[3] * w; } }
	v_pk_fma_f32 v[44:45], v[156:157], v[114:115], v[44:45] op_sel_hi:[0,1,1]
	v_pk_fma_f32 v[42:43], v[156:157], v[116:117], v[42:43] op_sel_hi:[0,1,1]
	s_waitcnt lgkmcnt(7)
	v_pk_fma_f32 v[72:73], v[158:159], v[118:119], v[72:73] op_sel_hi:[0,1,1]
	v_pk_fma_f32 v[70:71], v[158:159], v[120:121], v[70:71] op_sel_hi:[0,1,1]
	s_waitcnt lgkmcnt(6)
	v_pk_fma_f32 v[68:69], v[158:159], v[122:123], v[68:69] op_sel_hi:[0,1,1]
	v_pk_fma_f32 v[66:67], v[158:159], v[124:125], v[66:67] op_sel_hi:[0,1,1]
	s_waitcnt lgkmcnt(5)
	v_pk_fma_f32 v[64:65], v[158:159], v[126:127], v[64:65] op_sel_hi:[0,1,1]
	v_pk_fma_f32 v[62:63], v[158:159], v[128:129], v[62:63] op_sel_hi:[0,1,1]
	s_waitcnt lgkmcnt(4)
	v_pk_fma_f32 v[60:61], v[158:159], v[130:131], v[60:61] op_sel_hi:[0,1,1]
	v_pk_fma_f32 v[58:59], v[158:159], v[132:133], v[58:59] op_sel_hi:[0,1,1]
	s_waitcnt lgkmcnt(3)
	v_pk_fma_f32 v[56:57], v[158:159], v[134:135], v[56:57] op_sel_hi:[0,1,1]
	v_pk_fma_f32 v[54:55], v[158:159], v[136:137], v[54:55] op_sel_hi:[0,1,1]
	s_waitcnt lgkmcnt(2)
	v_pk_fma_f32 v[52:53], v[158:159], v[138:139], v[52:53] op_sel_hi:[0,1,1]
	v_pk_fma_f32 v[50:51], v[158:159], v[140:141], v[50:51] op_sel_hi:[0,1,1]
	s_waitcnt lgkmcnt(1)
	v_pk_fma_f32 v[48:49], v[158:159], v[142:143], v[48:49] op_sel_hi:[0,1,1]
	v_pk_fma_f32 v[46:47], v[158:159], v[144:145], v[46:47] op_sel_hi:[0,1,1]
	s_waitcnt lgkmcnt(0)
	v_pk_fma_f32 v[44:45], v[158:159], v[146:147], v[44:45] op_sel_hi:[0,1,1]
	v_pk_fma_f32 v[42:43], v[158:159], v[148:149], v[42:43] op_sel_hi:[0,1,1]
	global_load_dword v156, v[184:185], off
	v_add_co_u32_e32 v186, vcc, s23, v184
	s_nop 1
	v_addc_co_u32_e32 v187, vcc, 0, v185, vcc
	global_load_dword v158, v[186:187], off
	v_lshl_add_u64 v[184:185], v[184:185], 0, s[8:9]
	s_add_i32 s3, s13, s0
	v_mov_b32_e32 v39, s3
	ds_read_b128 v[86:89], v39
	ds_read_b128 v[90:93], v39 offset:16
	ds_read_b128 v[94:97], v39 offset:32
	ds_read_b128 v[98:101], v39 offset:48
	ds_read_b128 v[102:105], v39 offset:64
	ds_read_b128 v[106:109], v39 offset:80
	ds_read_b128 v[110:113], v39 offset:96
	ds_read_b128 v[114:117], v39 offset:112
	ds_read_b128 v[118:121], v39 offset:128
	ds_read_b128 v[122:125], v39 offset:144
	ds_read_b128 v[126:129], v39 offset:160
	ds_read_b128 v[130:133], v39 offset:176
	ds_read_b128 v[134:137], v39 offset:192
	ds_read_b128 v[138:141], v39 offset:208
	ds_read_b128 v[142:145], v39 offset:224
	ds_read_b128 v[146:149], v39 offset:240
	s_addk_i32 s0, 0x100
	v_lshl_add_u64 v[74:75], v[74:75], 0, s[8:9]
	s_waitcnt vmcnt(14) lgkmcnt(14)
	v_pk_fma_f32 v[72:73], v[160:161], v[86:87], v[72:73] op_sel_hi:[0,1,1]
	v_pk_fma_f32 v[70:71], v[160:161], v[88:89], v[70:71] op_sel_hi:[0,1,1]
	v_pk_fma_f32 v[68:69], v[160:161], v[90:91], v[68:69] op_sel_hi:[0,1,1]
	v_pk_fma_f32 v[66:67], v[160:161], v[92:93], v[66:67] op_sel_hi:[0,1,1]
	s_waitcnt lgkmcnt(13)
	v_pk_fma_f32 v[64:65], v[160:161], v[94:95], v[64:65] op_sel_hi:[0,1,1]
	v_pk_fma_f32 v[62:63], v[160:161], v[96:97], v[62:63] op_sel_hi:[0,1,1]
	s_waitcnt lgkmcnt(12)
	v_pk_fma_f32 v[60:61], v[160:161], v[98:99], v[60:61] op_sel_hi:[0,1,1]
	v_pk_fma_f32 v[58:59], v[160:161], v[100:101], v[58:59] op_sel_hi:[0,1,1]
	s_waitcnt lgkmcnt(11)
	v_pk_fma_f32 v[56:57], v[160:161], v[102:103], v[56:57] op_sel_hi:[0,1,1]
	v_pk_fma_f32 v[54:55], v[160:161], v[104:105], v[54:55] op_sel_hi:[0,1,1]
	s_waitcnt lgkmcnt(10)
	v_pk_fma_f32 v[52:53], v[160:161], v[106:107], v[52:53] op_sel_hi:[0,1,1]
	v_pk_fma_f32 v[50:51], v[160:161], v[108:109], v[50:51] op_sel_hi:[0,1,1]
	s_waitcnt lgkmcnt(9)
	v_pk_fma_f32 v[48:49], v[160:161], v[110:111], v[48:49] op_sel_hi:[0,1,1]
	v_pk_fma_f32 v[46:47], v[160:161], v[112:113], v[46:47] op_sel_hi:[0,1,1]
	s_waitcnt lgkmcnt(8)
	v_pk_fma_f32 v[44:45], v[160:161], v[114:115], v[44:45] op_sel_hi:[0,1,1]
	v_pk_fma_f32 v[42:43], v[160:161], v[116:117], v[42:43] op_sel_hi:[0,1,1]
	s_waitcnt lgkmcnt(7)
	v_pk_fma_f32 v[72:73], v[162:163], v[118:119], v[72:73] op_sel_hi:[0,1,1]
	v_pk_fma_f32 v[70:71], v[162:163], v[120:121], v[70:71] op_sel_hi:[0,1,1]
	s_waitcnt lgkmcnt(6)
	v_pk_fma_f32 v[68:69], v[162:163], v[122:123], v[68:69] op_sel_hi:[0,1,1]
	v_pk_fma_f32 v[66:67], v[162:163], v[124:125], v[66:67] op_sel_hi:[0,1,1]
	s_waitcnt lgkmcnt(5)
	v_pk_fma_f32 v[64:65], v[162:163], v[126:127], v[64:65] op_sel_hi:[0,1,1]
	v_pk_fma_f32 v[62:63], v[162:163], v[128:129], v[62:63] op_sel_hi:[0,1,1]
	s_waitcnt lgkmcnt(4)
	v_pk_fma_f32 v[60:61], v[162:163], v[130:131], v[60:61] op_sel_hi:[0,1,1]
	v_pk_fma_f32 v[58:59], v[162:163], v[132:133], v[58:59] op_sel_hi:[0,1,1]
	s_waitcnt lgkmcnt(3)
	v_pk_fma_f32 v[56:57], v[162:163], v[134:135], v[56:57] op_sel_hi:[0,1,1]
	v_pk_fma_f32 v[54:55], v[162:163], v[136:137], v[54:55] op_sel_hi:[0,1,1]
	s_waitcnt lgkmcnt(2)
	v_pk_fma_f32 v[52:53], v[162:163], v[138:139], v[52:53] op_sel_hi:[0,1,1]
	v_pk_fma_f32 v[50:51], v[162:163], v[140:141], v[50:51] op_sel_hi:[0,1,1]
	s_waitcnt lgkmcnt(1)
	v_pk_fma_f32 v[48:49], v[162:163], v[142:143], v[48:49] op_sel_hi:[0,1,1]
	v_pk_fma_f32 v[46:47], v[162:163], v[144:145], v[46:47] op_sel_hi:[0,1,1]
	s_waitcnt lgkmcnt(0)
; #define LAS __attribute__((address_space(3)))
; DI void ada_item(const float* c, const float* wada, const float* bada, float* ada, LAS float* scr, int item, int lane) {
;     ...
; #pragma unroll 2
;     for (int k = 0; k < 128; ++k) { const float w = wp[(size_t)k * 6144];
; #pragma unroll
;         for (int b4 = 0; b4 < 8; ++b4) { const f32x4 sv = *(const LAS f32x4*)(scr + k * 32 + b4 * 4);
;             acc[4 * b4] += sv[0] * w; acc[4 * b4 + 1] += sv[1] * w; acc[4 * b4 + 2] += sv[2] * w; acc[4 * b4 + 3] += sv[3] * w; } }
	v_pk_fma_f32 v[44:45], v[162:163], v[146:147], v[44:45] op_sel_hi:[0,1,1]
	v_pk_fma_f32 v[42:43], v[162:163], v[148:149], v[42:43] op_sel_hi:[0,1,1]
	global_load_dword v160, v[184:185], off
	v_add_co_u32_e32 v186, vcc, s23, v184
	s_nop 1
	v_addc_co_u32_e32 v187, vcc, 0, v185, vcc
	global_load_dword v162, v[186:187], off
	v_lshl_add_u64 v[184:185], v[184:185], 0, s[8:9]
	s_add_i32 s3, s13, s0
	v_mov_b32_e32 v39, s3
	ds_read_b128 v[86:89], v39
	ds_read_b128 v[90:93], v39 offset:16
	ds_read_b128 v[94:97], v39 offset:32
	ds_read_b128 v[98:101], v39 offset:48
	ds_read_b128 v[102:105], v39 offset:64
	ds_read_b128 v[106:109], v39 offset:80
	ds_read_b128 v[110:113], v39 offset:96
	ds_read_b128 v[114:117], v39 offset:112
	ds_read_b128 v[118:121], v39 offset:128
	ds_read_b128 v[122:125], v39 offset:144
	ds_read_b128 v[126:129], v39 offset:160
	ds_read_b128 v[130:133], v39 offset:176
	ds_read_b128 v[134:137], v39 offset:192
	ds_read_b128 v[138:141], v39 offset:208
	ds_read_b128 v[142:145], v39 offset:224
	ds_read_b128 v[146:149], v39 offset:240
	s_addk_i32 s0, 0x100
	v_lshl_add_u64 v[74:75], v[74:75], 0, s[8:9]
	s_waitcnt vmcnt(14) lgkmcnt(14)
	v_pk_fma_f32 v[72:73], v[164:165], v[86:87], v[72:73] op_sel_hi:[0,1,1]
	v_pk_fma_f32 v[70:71], v[164:165], v[88:89], v[70:71] op_sel_hi:[0,1,1]
	v_pk_fma_f32 v[68:69], v[164:165], v[90:91], v[68:69] op_sel_hi:[0,1,1]
	v_pk_fma_f32 v[66:67], v[164:165], v[92:93], v[66:67] op_sel_hi:[0,1,1]
	s_waitcnt lgkmcnt(13)
	v_pk_fma_f32 v[64:65], v[164:165], v[94:95], v[64:65] op_sel_hi:[0,1,1]
	v_pk_fma_f32 v[62:63], v[164:165], v[96:97], v[62:63] op_sel_hi:[0,1,1]
	s_waitcnt lgkmcnt(12)
	v_pk_fma_f32 v[60:61], v[164:165], v[98:99], v[60:61] op_sel_hi:[0,1,1]
	v_pk_fma_f32 v[58:59], v[164:165], v[100:101], v[58:59] op_sel_hi:[0,1,1]
	s_waitcnt lgkmcnt(11)
	v_pk_fma_f32 v[56:57], v[164:165], v[102:103], v[56:57] op_sel_hi:[0,1,1]
	v_pk_fma_f32 v[54:55], v[164:165], v[104:105], v[54:55] op_sel_hi:[0,1,1]
	s_waitcnt lgkmcnt(10)
	v_pk_fma_f32 v[52:53], v[164:165], v[106:107], v[52:53] op_sel_hi:[0,1,1]
	v_pk_fma_f32 v[50:51], v[164:165], v[108:109], v[50:51] op_sel_hi:[0,1,1]
	s_waitcnt lgkmcnt(9)
	v_pk_fma_f32 v[48:49], v[164:165], v[110:111], v[48:49] op_sel_hi:[0,1,1]
	v_pk_fma_f32 v[46:47], v[164:165], v[112:113], v[46:47] op_sel_hi:[0,1,1]
	s_waitcnt lgkmcnt(8)
	v_pk_fma_f32 v[44:45], v[164:165], v[114:115], v[44:45] op_sel_hi:[0,1,1]
	v_pk_fma_f32 v[42:43], v[164:165], v[116:117], v[42:43] op_sel_hi:[0,1,1]
	s_waitcnt lgkmcnt(7)
	v_pk_fma_f32 v[72:73], v[166:167], v[118:119], v[72:73] op_sel_hi:[0,1,1]
	v_pk_fma_f32 v[70:71], v[166:167], v[120:121], v[70:71] op_sel_hi:[0,1,1]
	s_waitcnt lgkmcnt(6)
	v_pk_fma_f32 v[68:69], v[166:167], v[122:123], v[68:69] op_sel_hi:[0,1,1]
	v_pk_fma_f32 v[66:67], v[166:167], v[124:125], v[66:67] op_sel_hi:[0,1,1]
	s_waitcnt lgkmcnt(5)
	v_pk_fma_f32 v[64:65], v[166:167], v[126:127], v[64:65] op_sel_hi:[0,1,1]
	v_pk_fma_f32 v[62:63], v[166:167], v[128:129], v[62:63] op_sel_hi:[0,1,1]
	s_waitcnt lgkmcnt(4)
	v_pk_fma_f32 v[60:61], v[166:167], v[130:131], v[60:61] op_sel_hi:[0,1,1]
	v_pk_fma_f32 v[58:59], v[166:167], v[132:133], v[58:59] op_sel_hi:[0,1,1]
	s_waitcnt lgkmcnt(3)
	v_pk_fma_f32 v[56:57], v[166:167], v[134:135], v[56:57] op_sel_hi:[0,1,1]
	v_pk_fma_f32 v[54:55], v[166:167], v[136:137], v[54:55] op_sel_hi:[0,1,1]
	s_waitcnt lgkmcnt(2)
	v_pk_fma_f32 v[52:53], v[166:167], v[138:139], v[52:53] op_sel_hi:[0,1,1]
	v_pk_fma_f32 v[50:51], v[166:167], v[140:141], v[50:51] op_sel_hi:[0,1,1]
	s_waitcnt lgkmcnt(1)
	v_pk_fma_f32 v[48:49], v[166:167], v[142:143], v[48:49] op_sel_hi:[0,1,1]
	v_pk_fma_f32 v[46:47], v[166:167], v[144:145], v[46:47] op_sel_hi:[0,1,1]
	s_waitcnt lgkmcnt(0)
	v_pk_fma_f32 v[44:45], v[166:167], v[146:147], v[44:45] op_sel_hi:[0,1,1]
	v_pk_fma_f32 v[42:43], v[166:167], v[148:149], v[42:43] op_sel_hi:[0,1,1]
	global_load_dword v164, v[184:185], off
	v_add_co_u32_e32 v186, vcc, s23, v184
	s_nop 1
	v_addc_co_u32_e32 v187, vcc, 0, v185, vcc
	global_load_dword v166, v[186:187], off
	v_lshl_add_u64 v[184:185], v[184:185], 0, s[8:9]
	s_add_i32 s3, s13, s0
	v_mov_b32_e32 v39, s3
	ds_read_b128 v[86:89], v39
	ds_read_b128 v[90:93], v39 offset:16
	ds_read_b128 v[94:97], v39 offset:32
	ds_read_b128 v[98:101], v39 offset:48
	ds_read_b128 v[102:105], v39 offset:64
	ds_read_b128 v[106:109], v39 offset:80
	ds_read_b128 v[110:113], v39 offset:96
	ds_read_b128 v[114:117], v39 offset:112
	ds_read_b128 v[118:121], v39 offset:128
	ds_read_b128 v[122:125], v39 offset:144
	ds_read_b128 v[126:129], v39 offset:160
	ds_read_b128 v[130:133], v39 offset:176
	ds_read_b128 v[134:137], v39 offset:192
	ds_read_b128 v[138:141], v39 offset:208
	ds_read_b128 v[142:145], v39 offset:224
	ds_read_b128 v[146:149], v39 offset:240
	s_addk_i32 s0, 0x100
	v_lshl_add_u64 v[74:75], v[74:75], 0, s[8:9]
	s_waitcnt vmcnt(14) lgkmcnt(14)
	v_pk_fma_f32 v[72:73], v[168:169], v[86:87], v[72:73] op_sel_hi:[0,1,1]
	v_pk_fma_f32 v[70:71], v[168:169], v[88:89], v[70:71] op_sel_hi:[0,1,1]
	v_pk_fma_f32 v[68:69], v[168:169], v[90:91], v[68:69] op_sel_hi:[0,1,1]
	v_pk_fma_f32 v[66:67], v[168:169], v[92:93], v[66:67] op_sel_hi:[0,1,1]
	s_waitcnt lgkmcnt(13)
	v_pk_fma_f32 v[64:65], v[168:169], v[94:95], v[64:65] op_sel_hi:[0,1,1]
	v_pk_fma_f32 v[62:63], v[168:169], v[96:97], v[62:63] op_sel_hi:[0,1,1]
	s_waitcnt lgkmcnt(12)
	v_pk_fma_f32 v[60:61], v[168:169], v[98:99], v[60:61] op_sel_hi:[0,1,1]
	v_pk_fma_f32 v[58:59], v[168:169], v[100:101], v[58:59] op_sel_hi:[0,1,1]
	s_waitcnt lgkmcnt(11)
	v_pk_fma_f32 v[56:57], v[168:169], v[102:103], v[56:57] op_sel_hi:[0,1,1]
	v_pk_fma_f32 v[54:55], v[168:169], v[104:105], v[54:55] op_sel_hi:[0,1,1]
	s_waitcnt lgkmcnt(10)
; #define LAS __attribute__((address_space(3)))
; DI void ada_item(const float* c, const float* wada, const float* bada, float* ada, LAS float* scr, int item, int lane) {
;     ...
; #pragma unroll 2
;     for (int k = 0; k < 128; ++k) { const float w = wp[(size_t)k * 6144];
; #pragma unroll
;         for (int b4 = 0; b4 < 8; ++b4) { const f32x4 sv = *(const LAS f32x4*)(scr + k * 32 + b4 * 4);
;             acc[4 * b4] += sv[0] * w; acc[4 * b4 + 1] += sv[1] * w; acc[4 * b4 + 2] += sv[2] * w; acc[4 * b4 + 3] += sv[3] * w; } }
	v_pk_fma_f32 v[52:53], v[168:169], v[106:107], v[52:53] op_sel_hi:[0,1,1]
	v_pk_fma_f32 v[50:51], v[168:169], v[108:109], v[50:51] op_sel_hi:[0,1,1]
	s_waitcnt lgkmcnt(9)
	v_pk_fma_f32 v[48:49], v[168:169], v[110:111], v[48:49] op_sel_hi:[0,1,1]
	v_pk_fma_f32 v[46:47], v[168:169], v[112:113], v[46:47] op_sel_hi:[0,1,1]
	s_waitcnt lgkmcnt(8)
	v_pk_fma_f32 v[44:45], v[168:169], v[114:115], v[44:45] op_sel_hi:[0,1,1]
	v_pk_fma_f32 v[42:43], v[168:169], v[116:117], v[42:43] op_sel_hi:[0,1,1]
	s_waitcnt lgkmcnt(7)
	v_pk_fma_f32 v[72:73], v[170:171], v[118:119], v[72:73] op_sel_hi:[0,1,1]
	v_pk_fma_f32 v[70:71], v[170:171], v[120:121], v[70:71] op_sel_hi:[0,1,1]
	s_waitcnt lgkmcnt(6)
	v_pk_fma_f32 v[68:69], v[170:171], v[122:123], v[68:69] op_sel_hi:[0,1,1]
	v_pk_fma_f32 v[66:67], v[170:171], v[124:125], v[66:67] op_sel_hi:[0,1,1]
	s_waitcnt lgkmcnt(5)
	v_pk_fma_f32 v[64:65], v[170:171], v[126:127], v[64:65] op_sel_hi:[0,1,1]
	v_pk_fma_f32 v[62:63], v[170:171], v[128:129], v[62:63] op_sel_hi:[0,1,1]
	s_waitcnt lgkmcnt(4)
	v_pk_fma_f32 v[60:61], v[170:171], v[130:131], v[60:61] op_sel_hi:[0,1,1]
	v_pk_fma_f32 v[58:59], v[170:171], v[132:133], v[58:59] op_sel_hi:[0,1,1]
	s_waitcnt lgkmcnt(3)
	v_pk_fma_f32 v[56:57], v[170:171], v[134:135], v[56:57] op_sel_hi:[0,1,1]
	v_pk_fma_f32 v[54:55], v[170:171], v[136:137], v[54:55] op_sel_hi:[0,1,1]
	s_waitcnt lgkmcnt(2)
	v_pk_fma_f32 v[52:53], v[170:171], v[138:139], v[52:53] op_sel_hi:[0,1,1]
	v_pk_fma_f32 v[50:51], v[170:171], v[140:141], v[50:51] op_sel_hi:[0,1,1]
	s_waitcnt lgkmcnt(1)
	v_pk_fma_f32 v[48:49], v[170:171], v[142:143], v[48:49] op_sel_hi:[0,1,1]
	v_pk_fma_f32 v[46:47], v[170:171], v[144:145], v[46:47] op_sel_hi:[0,1,1]
	s_waitcnt lgkmcnt(0)
	v_pk_fma_f32 v[44:45], v[170:171], v[146:147], v[44:45] op_sel_hi:[0,1,1]
	v_pk_fma_f32 v[42:43], v[170:171], v[148:149], v[42:43] op_sel_hi:[0,1,1]
	global_load_dword v168, v[184:185], off
	v_add_co_u32_e32 v186, vcc, s23, v184
	s_nop 1
	v_addc_co_u32_e32 v187, vcc, 0, v185, vcc
	global_load_dword v170, v[186:187], off
	v_lshl_add_u64 v[184:185], v[184:185], 0, s[8:9]
	s_add_i32 s3, s13, s0
	v_mov_b32_e32 v39, s3
	ds_read_b128 v[86:89], v39
	ds_read_b128 v[90:93], v39 offset:16
	ds_read_b128 v[94:97], v39 offset:32
	ds_read_b128 v[98:101], v39 offset:48
	ds_read_b128 v[102:105], v39 offset:64
	ds_read_b128 v[106:109], v39 offset:80
	ds_read_b128 v[110:113], v39 offset:96
	ds_read_b128 v[114:117], v39 offset:112
	ds_read_b128 v[118:121], v39 offset:128
	ds_read_b128 v[122:125], v39 offset:144
	ds_read_b128 v[126:129], v39 offset:160
	ds_read_b128 v[130:133], v39 offset:176
	ds_read_b128 v[134:137], v39 offset:192
	ds_read_b128 v[138:141], v39 offset:208
	ds_read_b128 v[142:145], v39 offset:224
	ds_read_b128 v[146:149], v39 offset:240
	s_addk_i32 s0, 0x100
	v_lshl_add_u64 v[74:75], v[74:75], 0, s[8:9]
	s_waitcnt vmcnt(14) lgkmcnt(14)
	v_pk_fma_f32 v[72:73], v[172:173], v[86:87], v[72:73] op_sel_hi:[0,1,1]
	v_pk_fma_f32 v[70:71], v[172:173], v[88:89], v[70:71] op_sel_hi:[0,1,1]
	v_pk_fma_f32 v[68:69], v[172:173], v[90:91], v[68:69] op_sel_hi:[0,1,1]
	v_pk_fma_f32 v[66:67], v[172:173], v[92:93], v[66:67] op_sel_hi:[0,1,1]
	s_waitcnt lgkmcnt(13)
	v_pk_fma_f32 v[64:65], v[172:173], v[94:95], v[64:65] op_sel_hi:[0,1,1]
	v_pk_fma_f32 v[62:63], v[172:173], v[96:97], v[62:63] op_sel_hi:[0,1,1]
	s_waitcnt lgkmcnt(12)
	v_pk_fma_f32 v[60:61], v[172:173], v[98:99], v[60:61] op_sel_hi:[0,1,1]
	v_pk_fma_f32 v[58:59], v[172:173], v[100:101], v[58:59] op_sel_hi:[0,1,1]
	s_waitcnt lgkmcnt(11)
	v_pk_fma_f32 v[56:57], v[172:173], v[102:103], v[56:57] op_sel_hi:[0,1,1]
	v_pk_fma_f32 v[54:55], v[172:173], v[104:105], v[54:55] op_sel_hi:[0,1,1]
	s_waitcnt lgkmcnt(10)
	v_pk_fma_f32 v[52:53], v[172:173], v[106:107], v[52:53] op_sel_hi:[0,1,1]
	v_pk_fma_f32 v[50:51], v[172:173], v[108:109], v[50:51] op_sel_hi:[0,1,1]
	s_waitcnt lgkmcnt(9)
	v_pk_fma_f32 v[48:49], v[172:173], v[110:111], v[48:49] op_sel_hi:[0,1,1]
	v_pk_fma_f32 v[46:47], v[172:173], v[112:113], v[46:47] op_sel_hi:[0,1,1]
	s_waitcnt lgkmcnt(8)
	v_pk_fma_f32 v[44:45], v[172:173], v[114:115], v[44:45] op_sel_hi:[0,1,1]
	v_pk_fma_f32 v[42:43], v[172:173], v[116:117], v[42:43] op_sel_hi:[0,1,1]
	s_waitcnt lgkmcnt(7)
	v_pk_fma_f32 v[72:73], v[174:175], v[118:119], v[72:73] op_sel_hi:[0,1,1]
	v_pk_fma_f32 v[70:71], v[174:175], v[120:121], v[70:71] op_sel_hi:[0,1,1]
	s_waitcnt lgkmcnt(6)
	v_pk_fma_f32 v[68:69], v[174:175], v[122:123], v[68:69] op_sel_hi:[0,1,1]
	v_pk_fma_f32 v[66:67], v[174:175], v[124:125], v[66:67] op_sel_hi:[0,1,1]
	s_waitcnt lgkmcnt(5)
	v_pk_fma_f32 v[64:65], v[174:175], v[126:127], v[64:65] op_sel_hi:[0,1,1]
	v_pk_fma_f32 v[62:63], v[174:175], v[128:129], v[62:63] op_sel_hi:[0,1,1]
	s_waitcnt lgkmcnt(4)
	v_pk_fma_f32 v[60:61], v[174:175], v[130:131], v[60:61] op_sel_hi:[0,1,1]
	v_pk_fma_f32 v[58:59], v[174:175], v[132:133], v[58:59] op_sel_hi:[0,1,1]
	s_waitcnt lgkmcnt(3)
	v_pk_fma_f32 v[56:57], v[174:175], v[134:135], v[56:57] op_sel_hi:[0,1,1]
	v_pk_fma_f32 v[54:55], v[174:175], v[136:137], v[54:55] op_sel_hi:[0,1,1]
	s_waitcnt lgkmcnt(2)
	v_pk_fma_f32 v[52:53], v[174:175], v[138:139], v[52:53] op_sel_hi:[0,1,1]
	v_pk_fma_f32 v[50:51], v[174:175], v[140:141], v[50:51] op_sel_hi:[0,1,1]
	s_waitcnt lgkmcnt(1)
	v_pk_fma_f32 v[48:49], v[174:175], v[142:143], v[48:49] op_sel_hi:[0,1,1]
	v_pk_fma_f32 v[46:47], v[174:175], v[144:145], v[46:47] op_sel_hi:[0,1,1]
	s_waitcnt lgkmcnt(0)
; #define LAS __attribute__((address_space(3)))
; DI void ada_item(const float* c, const float* wada, const float* bada, float* ada, LAS float* scr, int item, int lane) {
;     ...
; #pragma unroll 2
;     for (int k = 0; k < 128; ++k) { const float w = wp[(size_t)k * 6144];
; #pragma unroll
;         for (int b4 = 0; b4 < 8; ++b4) { const f32x4 sv = *(const LAS f32x4*)(scr + k * 32 + b4 * 4);
;             acc[4 * b4] += sv[0] * w; acc[4 * b4 + 1] += sv[1] * w; acc[4 * b4 + 2] += sv[2] * w; acc[4 * b4 + 3] += sv[3] * w; } }
	v_pk_fma_f32 v[44:45], v[174:175], v[146:147], v[44:45] op_sel_hi:[0,1,1]
	v_pk_fma_f32 v[42:43], v[174:175], v[148:149], v[42:43] op_sel_hi:[0,1,1]
	global_load_dword v172, v[184:185], off
	v_add_co_u32_e32 v186, vcc, s23, v184
	s_nop 1
	v_addc_co_u32_e32 v187, vcc, 0, v185, vcc
	global_load_dword v174, v[186:187], off
	v_lshl_add_u64 v[184:185], v[184:185], 0, s[8:9]
	s_add_i32 s3, s13, s0
	v_mov_b32_e32 v39, s3
	ds_read_b128 v[86:89], v39
	ds_read_b128 v[90:93], v39 offset:16
	ds_read_b128 v[94:97], v39 offset:32
	ds_read_b128 v[98:101], v39 offset:48
	ds_read_b128 v[102:105], v39 offset:64
	ds_read_b128 v[106:109], v39 offset:80
	ds_read_b128 v[110:113], v39 offset:96
	ds_read_b128 v[114:117], v39 offset:112
	ds_read_b128 v[118:121], v39 offset:128
	ds_read_b128 v[122:125], v39 offset:144
	ds_read_b128 v[126:129], v39 offset:160
	ds_read_b128 v[130:133], v39 offset:176
	ds_read_b128 v[134:137], v39 offset:192
	ds_read_b128 v[138:141], v39 offset:208
	ds_read_b128 v[142:145], v39 offset:224
	ds_read_b128 v[146:149], v39 offset:240
	s_addk_i32 s0, 0x100
	v_lshl_add_u64 v[74:75], v[74:75], 0, s[8:9]
	s_waitcnt vmcnt(14) lgkmcnt(14)
	v_pk_fma_f32 v[72:73], v[176:177], v[86:87], v[72:73] op_sel_hi:[0,1,1]
	v_pk_fma_f32 v[70:71], v[176:177], v[88:89], v[70:71] op_sel_hi:[0,1,1]
	v_pk_fma_f32 v[68:69], v[176:177], v[90:91], v[68:69] op_sel_hi:[0,1,1]
	v_pk_fma_f32 v[66:67], v[176:177], v[92:93], v[66:67] op_sel_hi:[0,1,1]
	s_waitcnt lgkmcnt(13)
	v_pk_fma_f32 v[64:65], v[176:177], v[94:95], v[64:65] op_sel_hi:[0,1,1]
	v_pk_fma_f32 v[62:63], v[176:177], v[96:97], v[62:63] op_sel_hi:[0,1,1]
	s_waitcnt lgkmcnt(12)
	v_pk_fma_f32 v[60:61], v[176:177], v[98:99], v[60:61] op_sel_hi:[0,1,1]
	v_pk_fma_f32 v[58:59], v[176:177], v[100:101], v[58:59] op_sel_hi:[0,1,1]
	s_waitcnt lgkmcnt(11)
	v_pk_fma_f32 v[56:57], v[176:177], v[102:103], v[56:57] op_sel_hi:[0,1,1]
	v_pk_fma_f32 v[54:55], v[176:177], v[104:105], v[54:55] op_sel_hi:[0,1,1]
	s_waitcnt lgkmcnt(10)
	v_pk_fma_f32 v[52:53], v[176:177], v[106:107], v[52:53] op_sel_hi:[0,1,1]
	v_pk_fma_f32 v[50:51], v[176:177], v[108:109], v[50:51] op_sel_hi:[0,1,1]
	s_waitcnt lgkmcnt(9)
	v_pk_fma_f32 v[48:49], v[176:177], v[110:111], v[48:49] op_sel_hi:[0,1,1]
	v_pk_fma_f32 v[46:47], v[176:177], v[112:113], v[46:47] op_sel_hi:[0,1,1]
	s_waitcnt lgkmcnt(8)
	v_pk_fma_f32 v[44:45], v[176:177], v[114:115], v[44:45] op_sel_hi:[0,1,1]
	v_pk_fma_f32 v[42:43], v[176:177], v[116:117], v[42:43] op_sel_hi:[0,1,1]
	s_waitcnt lgkmcnt(7)
	v_pk_fma_f32 v[72:73], v[178:179], v[118:119], v[72:73] op_sel_hi:[0,1,1]
	v_pk_fma_f32 v[70:71], v[178:179], v[120:121], v[70:71] op_sel_hi:[0,1,1]
	s_waitcnt lgkmcnt(6)
	v_pk_fma_f32 v[68:69], v[178:179], v[122:123], v[68:69] op_sel_hi:[0,1,1]
	v_pk_fma_f32 v[66:67], v[178:179], v[124:125], v[66:67] op_sel_hi:[0,1,1]
	s_waitcnt lgkmcnt(5)
	v_pk_fma_f32 v[64:65], v[178:179], v[126:127], v[64:65] op_sel_hi:[0,1,1]
	v_pk_fma_f32 v[62:63], v[178:179], v[128:129], v[62:63] op_sel_hi:[0,1,1]
	s_waitcnt lgkmcnt(4)
	v_pk_fma_f32 v[60:61], v[178:179], v[130:131], v[60:61] op_sel_hi:[0,1,1]
	v_pk_fma_f32 v[58:59], v[178:179], v[132:133], v[58:59] op_sel_hi:[0,1,1]
	s_waitcnt lgkmcnt(3)
	v_pk_fma_f32 v[56:57], v[178:179], v[134:135], v[56:57] op_sel_hi:[0,1,1]
	v_pk_fma_f32 v[54:55], v[178:179], v[136:137], v[54:55] op_sel_hi:[0,1,1]
	s_waitcnt lgkmcnt(2)
	v_pk_fma_f32 v[52:53], v[178:179], v[138:139], v[52:53] op_sel_hi:[0,1,1]
	v_pk_fma_f32 v[50:51], v[178:179], v[140:141], v[50:51] op_sel_hi:[0,1,1]
	s_waitcnt lgkmcnt(1)
	v_pk_fma_f32 v[48:49], v[178:179], v[142:143], v[48:49] op_sel_hi:[0,1,1]
	v_pk_fma_f32 v[46:47], v[178:179], v[144:145], v[46:47] op_sel_hi:[0,1,1]
	s_waitcnt lgkmcnt(0)
	v_pk_fma_f32 v[44:45], v[178:179], v[146:147], v[44:45] op_sel_hi:[0,1,1]
	v_pk_fma_f32 v[42:43], v[178:179], v[148:149], v[42:43] op_sel_hi:[0,1,1]
	global_load_dword v176, v[184:185], off
	v_add_co_u32_e32 v186, vcc, s23, v184
	s_nop 1
	v_addc_co_u32_e32 v187, vcc, 0, v185, vcc
	global_load_dword v178, v[186:187], off
	v_lshl_add_u64 v[184:185], v[184:185], 0, s[8:9]
	s_add_i32 s3, s13, s0
	v_mov_b32_e32 v39, s3
	ds_read_b128 v[86:89], v39
	ds_read_b128 v[90:93], v39 offset:16
	ds_read_b128 v[94:97], v39 offset:32
	ds_read_b128 v[98:101], v39 offset:48
	ds_read_b128 v[102:105], v39 offset:64
	ds_read_b128 v[106:109], v39 offset:80
	ds_read_b128 v[110:113], v39 offset:96
	ds_read_b128 v[114:117], v39 offset:112
	ds_read_b128 v[118:121], v39 offset:128
	ds_read_b128 v[122:125], v39 offset:144
	ds_read_b128 v[126:129], v39 offset:160
	ds_read_b128 v[130:133], v39 offset:176
	ds_read_b128 v[134:137], v39 offset:192
	ds_read_b128 v[138:141], v39 offset:208
	ds_read_b128 v[142:145], v39 offset:224
	ds_read_b128 v[146:149], v39 offset:240
	s_addk_i32 s0, 0x100
	v_lshl_add_u64 v[74:75], v[74:75], 0, s[8:9]
	s_waitcnt vmcnt(14) lgkmcnt(14)
	v_pk_fma_f32 v[72:73], v[180:181], v[86:87], v[72:73] op_sel_hi:[0,1,1]
	v_pk_fma_f32 v[70:71], v[180:181], v[88:89], v[70:71] op_sel_hi:[0,1,1]
	v_pk_fma_f32 v[68:69], v[180:181], v[90:91], v[68:69] op_sel_hi:[0,1,1]
	v_pk_fma_f32 v[66:67], v[180:181], v[92:93], v[66:67] op_sel_hi:[0,1,1]
	s_waitcnt lgkmcnt(13)
	v_pk_fma_f32 v[64:65], v[180:181], v[94:95], v[64:65] op_sel_hi:[0,1,1]
	v_pk_fma_f32 v[62:63], v[180:181], v[96:97], v[62:63] op_sel_hi:[0,1,1]
	s_waitcnt lgkmcnt(12)
	v_pk_fma_f32 v[60:61], v[180:181], v[98:99], v[60:61] op_sel_hi:[0,1,1]
	v_pk_fma_f32 v[58:59], v[180:181], v[100:101], v[58:59] op_sel_hi:[0,1,1]
	s_waitcnt lgkmcnt(11)
	v_pk_fma_f32 v[56:57], v[180:181], v[102:103], v[56:57] op_sel_hi:[0,1,1]
	v_pk_fma_f32 v[54:55], v[180:181], v[104:105], v[54:55] op_sel_hi:[0,1,1]
	s_waitcnt lgkmcnt(10)
; #define LAS __attribute__((address_space(3)))
; DI void ada_item(const float* c, const float* wada, const float* bada, float* ada, LAS float* scr, int item, int lane) {
;     ...
; #pragma unroll 2
;     for (int k = 0; k < 128; ++k) { const float w = wp[(size_t)k * 6144];
; #pragma unroll
;         for (int b4 = 0; b4 < 8; ++b4) { const f32x4 sv = *(const LAS f32x4*)(scr + k * 32 + b4 * 4);
;             acc[4 * b4] += sv[0] * w; acc[4 * b4 + 1] += sv[1] * w; acc[4 * b4 + 2] += sv[2] * w; acc[4 * b4 + 3] += sv[3] * w; } }
	v_pk_fma_f32 v[52:53], v[180:181], v[106:107], v[52:53] op_sel_hi:[0,1,1]
	v_pk_fma_f32 v[50:51], v[180:181], v[108:109], v[50:51] op_sel_hi:[0,1,1]
	s_waitcnt lgkmcnt(9)
	v_pk_fma_f32 v[48:49], v[180:181], v[110:111], v[48:49] op_sel_hi:[0,1,1]
	v_pk_fma_f32 v[46:47], v[180:181], v[112:113], v[46:47] op_sel_hi:[0,1,1]
	s_waitcnt lgkmcnt(8)
	v_pk_fma_f32 v[44:45], v[180:181], v[114:115], v[44:45] op_sel_hi:[0,1,1]
	v_pk_fma_f32 v[42:43], v[180:181], v[116:117], v[42:43] op_sel_hi:[0,1,1]
	s_waitcnt lgkmcnt(7)
	v_pk_fma_f32 v[72:73], v[182:183], v[118:119], v[72:73] op_sel_hi:[0,1,1]
	v_pk_fma_f32 v[70:71], v[182:183], v[120:121], v[70:71] op_sel_hi:[0,1,1]
	s_waitcnt lgkmcnt(6)
	v_pk_fma_f32 v[68:69], v[182:183], v[122:123], v[68:69] op_sel_hi:[0,1,1]
	v_pk_fma_f32 v[66:67], v[182:183], v[124:125], v[66:67] op_sel_hi:[0,1,1]
	s_waitcnt lgkmcnt(5)
	v_pk_fma_f32 v[64:65], v[182:183], v[126:127], v[64:65] op_sel_hi:[0,1,1]
	v_pk_fma_f32 v[62:63], v[182:183], v[128:129], v[62:63] op_sel_hi:[0,1,1]
	s_waitcnt lgkmcnt(4)
	v_pk_fma_f32 v[60:61], v[182:183], v[130:131], v[60:61] op_sel_hi:[0,1,1]
	v_pk_fma_f32 v[58:59], v[182:183], v[132:133], v[58:59] op_sel_hi:[0,1,1]
	s_waitcnt lgkmcnt(3)
	v_pk_fma_f32 v[56:57], v[182:183], v[134:135], v[56:57] op_sel_hi:[0,1,1]
	v_pk_fma_f32 v[54:55], v[182:183], v[136:137], v[54:55] op_sel_hi:[0,1,1]
	s_waitcnt lgkmcnt(2)
	v_pk_fma_f32 v[52:53], v[182:183], v[138:139], v[52:53] op_sel_hi:[0,1,1]
	v_pk_fma_f32 v[50:51], v[182:183], v[140:141], v[50:51] op_sel_hi:[0,1,1]
	s_waitcnt lgkmcnt(1)
	v_pk_fma_f32 v[48:49], v[182:183], v[142:143], v[48:49] op_sel_hi:[0,1,1]
	v_pk_fma_f32 v[46:47], v[182:183], v[144:145], v[46:47] op_sel_hi:[0,1,1]
	s_waitcnt lgkmcnt(0)
	v_pk_fma_f32 v[44:45], v[182:183], v[146:147], v[44:45] op_sel_hi:[0,1,1]
	v_pk_fma_f32 v[42:43], v[182:183], v[148:149], v[42:43] op_sel_hi:[0,1,1]
	global_load_dword v180, v[184:185], off
	v_add_co_u32_e32 v186, vcc, s23, v184
	s_nop 1
	v_addc_co_u32_e32 v187, vcc, 0, v185, vcc
	global_load_dword v182, v[186:187], off
	v_lshl_add_u64 v[184:185], v[184:185], 0, s[8:9]
	s_cmpk_lg_i32 s0, 0x3800
	s_cbranch_scc1 .LBB0_63
	s_add_i32 s3, s13, s0
	v_mov_b32_e32 v39, s3
	ds_read_b128 v[86:89], v39
	ds_read_b128 v[90:93], v39 offset:16
	ds_read_b128 v[94:97], v39 offset:32
	ds_read_b128 v[98:101], v39 offset:48
	ds_read_b128 v[102:105], v39 offset:64
	ds_read_b128 v[106:109], v39 offset:80
	ds_read_b128 v[110:113], v39 offset:96
	ds_read_b128 v[114:117], v39 offset:112
	ds_read_b128 v[118:121], v39 offset:128
	ds_read_b128 v[122:125], v39 offset:144
	ds_read_b128 v[126:129], v39 offset:160
	ds_read_b128 v[130:133], v39 offset:176
	ds_read_b128 v[134:137], v39 offset:192
	ds_read_b128 v[138:141], v39 offset:208
	ds_read_b128 v[142:145], v39 offset:224
	ds_read_b128 v[146:149], v39 offset:240
	s_addk_i32 s0, 0x100
	v_lshl_add_u64 v[74:75], v[74:75], 0, s[8:9]
	s_waitcnt vmcnt(14) lgkmcnt(14)
	v_pk_fma_f32 v[72:73], v[152:153], v[86:87], v[72:73] op_sel_hi:[0,1,1]
	v_pk_fma_f32 v[70:71], v[152:153], v[88:89], v[70:71] op_sel_hi:[0,1,1]
	v_pk_fma_f32 v[68:69], v[152:153], v[90:91], v[68:69] op_sel_hi:[0,1,1]
	v_pk_fma_f32 v[66:67], v[152:153], v[92:93], v[66:67] op_sel_hi:[0,1,1]
	s_waitcnt lgkmcnt(13)
	v_pk_fma_f32 v[64:65], v[152:153], v[94:95], v[64:65] op_sel_hi:[0,1,1]
	v_pk_fma_f32 v[62:63], v[152:153], v[96:97], v[62:63] op_sel_hi:[0,1,1]
	s_waitcnt lgkmcnt(12)
	v_pk_fma_f32 v[60:61], v[152:153], v[98:99], v[60:61] op_sel_hi:[0,1,1]
	v_pk_fma_f32 v[58:59], v[152:153], v[100:101], v[58:59] op_sel_hi:[0,1,1]
	s_waitcnt lgkmcnt(11)
	v_pk_fma_f32 v[56:57], v[152:153], v[102:103], v[56:57] op_sel_hi:[0,1,1]
	v_pk_fma_f32 v[54:55], v[152:153], v[104:105], v[54:55] op_sel_hi:[0,1,1]
	s_waitcnt lgkmcnt(10)
	v_pk_fma_f32 v[52:53], v[152:153], v[106:107], v[52:53] op_sel_hi:[0,1,1]
	v_pk_fma_f32 v[50:51], v[152:153], v[108:109], v[50:51] op_sel_hi:[0,1,1]
	s_waitcnt lgkmcnt(9)
	v_pk_fma_f32 v[48:49], v[152:153], v[110:111], v[48:49] op_sel_hi:[0,1,1]
	v_pk_fma_f32 v[46:47], v[152:153], v[112:113], v[46:47] op_sel_hi:[0,1,1]
	s_waitcnt lgkmcnt(8)
	v_pk_fma_f32 v[44:45], v[152:153], v[114:115], v[44:45] op_sel_hi:[0,1,1]
	v_pk_fma_f32 v[42:43], v[152:153], v[116:117], v[42:43] op_sel_hi:[0,1,1]
	s_waitcnt lgkmcnt(7)
	v_pk_fma_f32 v[72:73], v[154:155], v[118:119], v[72:73] op_sel_hi:[0,1,1]
	v_pk_fma_f32 v[70:71], v[154:155], v[120:121], v[70:71] op_sel_hi:[0,1,1]
	s_waitcnt lgkmcnt(6)
	v_pk_fma_f32 v[68:69], v[154:155], v[122:123], v[68:69] op_sel_hi:[0,1,1]
	v_pk_fma_f32 v[66:67], v[154:155], v[124:125], v[66:67] op_sel_hi:[0,1,1]
	s_waitcnt lgkmcnt(5)
	v_pk_fma_f32 v[64:65], v[154:155], v[126:127], v[64:65] op_sel_hi:[0,1,1]
	v_pk_fma_f32 v[62:63], v[154:155], v[128:129], v[62:63] op_sel_hi:[0,1,1]
	s_waitcnt lgkmcnt(4)
	v_pk_fma_f32 v[60:61], v[154:155], v[130:131], v[60:61] op_sel_hi:[0,1,1]
	v_pk_fma_f32 v[58:59], v[154:155], v[132:133], v[58:59] op_sel_hi:[0,1,1]
	s_waitcnt lgkmcnt(3)
	v_pk_fma_f32 v[56:57], v[154:155], v[134:135], v[56:57] op_sel_hi:[0,1,1]
	v_pk_fma_f32 v[54:55], v[154:155], v[136:137], v[54:55] op_sel_hi:[0,1,1]
	s_waitcnt lgkmcnt(2)
	v_pk_fma_f32 v[52:53], v[154:155], v[138:139], v[52:53] op_sel_hi:[0,1,1]
	v_pk_fma_f32 v[50:51], v[154:155], v[140:141], v[50:51] op_sel_hi:[0,1,1]
	s_waitcnt lgkmcnt(1)
	v_pk_fma_f32 v[48:49], v[154:155], v[142:143], v[48:49] op_sel_hi:[0,1,1]
	v_pk_fma_f32 v[46:47], v[154:155], v[144:145], v[46:47] op_sel_hi:[0,1,1]
	s_waitcnt lgkmcnt(0)
; #define LAS __attribute__((address_space(3)))
; DI void ada_item(const float* c, const float* wada, const float* bada, float* ada, LAS float* scr, int item, int lane) {
;     ...
; #pragma unroll 2
;     for (int k = 0; k < 128; ++k) { const float w = wp[(size_t)k * 6144];
; #pragma unroll
;         for (int b4 = 0; b4 < 8; ++b4) { const f32x4 sv = *(const LAS f32x4*)(scr + k * 32 + b4 * 4);
;             acc[4 * b4] += sv[0] * w; acc[4 * b4 + 1] += sv[1] * w; acc[4 * b4 + 2] += sv[2] * w; acc[4 * b4 + 3] += sv[3] * w; } }
	v_pk_fma_f32 v[44:45], v[154:155], v[146:147], v[44:45] op_sel_hi:[0,1,1]
	v_pk_fma_f32 v[42:43], v[154:155], v[148:149], v[42:43] op_sel_hi:[0,1,1]
	s_add_i32 s3, s13, s0
	v_mov_b32_e32 v39, s3
	ds_read_b128 v[86:89], v39
	ds_read_b128 v[90:93], v39 offset:16
	ds_read_b128 v[94:97], v39 offset:32
	ds_read_b128 v[98:101], v39 offset:48
	ds_read_b128 v[102:105], v39 offset:64
	ds_read_b128 v[106:109], v39 offset:80
	ds_read_b128 v[110:113], v39 offset:96
	ds_read_b128 v[114:117], v39 offset:112
	ds_read_b128 v[118:121], v39 offset:128
	ds_read_b128 v[122:125], v39 offset:144
	ds_read_b128 v[126:129], v39 offset:160
	ds_read_b128 v[130:133], v39 offset:176
	ds_read_b128 v[134:137], v39 offset:192
	ds_read_b128 v[138:141], v39 offset:208
	ds_read_b128 v[142:145], v39 offset:224
	ds_read_b128 v[146:149], v39 offset:240
	s_addk_i32 s0, 0x100
	v_lshl_add_u64 v[74:75], v[74:75], 0, s[8:9]
	s_waitcnt vmcnt(12) lgkmcnt(14)
	v_pk_fma_f32 v[72:73], v[156:157], v[86:87], v[72:73] op_sel_hi:[0,1,1]
	v_pk_fma_f32 v[70:71], v[156:157], v[88:89], v[70:71] op_sel_hi:[0,1,1]
	v_pk_fma_f32 v[68:69], v[156:157], v[90:91], v[68:69] op_sel_hi:[0,1,1]
	v_pk_fma_f32 v[66:67], v[156:157], v[92:93], v[66:67] op_sel_hi:[0,1,1]
	s_waitcnt lgkmcnt(13)
	v_pk_fma_f32 v[64:65], v[156:157], v[94:95], v[64:65] op_sel_hi:[0,1,1]
	v_pk_fma_f32 v[62:63], v[156:157], v[96:97], v[62:63] op_sel_hi:[0,1,1]
	s_waitcnt lgkmcnt(12)
	v_pk_fma_f32 v[60:61], v[156:157], v[98:99], v[60:61] op_sel_hi:[0,1,1]
	v_pk_fma_f32 v[58:59], v[156:157], v[100:101], v[58:59] op_sel_hi:[0,1,1]
	s_waitcnt lgkmcnt(11)
	v_pk_fma_f32 v[56:57], v[156:157], v[102:103], v[56:57] op_sel_hi:[0,1,1]
	v_pk_fma_f32 v[54:55], v[156:157], v[104:105], v[54:55] op_sel_hi:[0,1,1]
	s_waitcnt lgkmcnt(10)
	v_pk_fma_f32 v[52:53], v[156:157], v[106:107], v[52:53] op_sel_hi:[0,1,1]
	v_pk_fma_f32 v[50:51], v[156:157], v[108:109], v[50:51] op_sel_hi:[0,1,1]
	s_waitcnt lgkmcnt(9)
	v_pk_fma_f32 v[48:49], v[156:157], v[110:111], v[48:49] op_sel_hi:[0,1,1]
	v_pk_fma_f32 v[46:47], v[156:157], v[112:113], v[46:47] op_sel_hi:[0,1,1]
	s_waitcnt lgkmcnt(8)
	v_pk_fma_f32 v[44:45], v[156:157], v[114:115], v[44:45] op_sel_hi:[0,1,1]
	v_pk_fma_f32 v[42:43], v[156:157], v[116:117], v[42:43] op_sel_hi:[0,1,1]
	s_waitcnt lgkmcnt(7)
	v_pk_fma_f32 v[72:73], v[158:159], v[118:119], v[72:73] op_sel_hi:[0,1,1]
	v_pk_fma_f32 v[70:71], v[158:159], v[120:121], v[70:71] op_sel_hi:[0,1,1]
	s_waitcnt lgkmcnt(6)
	v_pk_fma_f32 v[68:69], v[158:159], v[122:123], v[68:69] op_sel_hi:[0,1,1]
	v_pk_fma_f32 v[66:67], v[158:159], v[124:125], v[66:67] op_sel_hi:[0,1,1]
	s_waitcnt lgkmcnt(5)
	v_pk_fma_f32 v[64:65], v[158:159], v[126:127], v[64:65] op_sel_hi:[0,1,1]
	v_pk_fma_f32 v[62:63], v[158:159], v[128:129], v[62:63] op_sel_hi:[0,1,1]
	s_waitcnt lgkmcnt(4)
	v_pk_fma_f32 v[60:61], v[158:159], v[130:131], v[60:61] op_sel_hi:[0,1,1]
	v_pk_fma_f32 v[58:59], v[158:159], v[132:133], v[58:59] op_sel_hi:[0,1,1]
	s_waitcnt lgkmcnt(3)
	v_pk_fma_f32 v[56:57], v[158:159], v[134:135], v[56:57] op_sel_hi:[0,1,1]
	v_pk_fma_f32 v[54:55], v[158:159], v[136:137], v[54:55] op_sel_hi:[0,1,1]
	s_waitcnt lgkmcnt(2)
	v_pk_fma_f32 v[52:53], v[158:159], v[138:139], v[52:53] op_sel_hi:[0,1,1]
	v_pk_fma_f32 v[50:51], v[158:159], v[140:141], v[50:51] op_sel_hi:[0,1,1]
	s_waitcnt lgkmcnt(1)
	v_pk_fma_f32 v[48:49], v[158:159], v[142:143], v[48:49] op_sel_hi:[0,1,1]
	v_pk_fma_f32 v[46:47], v[158:159], v[144:145], v[46:47] op_sel_hi:[0,1,1]
	s_waitcnt lgkmcnt(0)
	v_pk_fma_f32 v[44:45], v[158:159], v[146:147], v[44:45] op_sel_hi:[0,1,1]
	v_pk_fma_f32 v[42:43], v[158:159], v[148:149], v[42:43] op_sel_hi:[0,1,1]
	s_add_i32 s3, s13, s0
	v_mov_b32_e32 v39, s3
	ds_read_b128 v[86:89], v39
	ds_read_b128 v[90:93], v39 offset:16
	ds_read_b128 v[94:97], v39 offset:32
	ds_read_b128 v[98:101], v39 offset:48
	ds_read_b128 v[102:105], v39 offset:64
	ds_read_b128 v[106:109], v39 offset:80
	ds_read_b128 v[110:113], v39 offset:96
	ds_read_b128 v[114:117], v39 offset:112
	ds_read_b128 v[118:121], v39 offset:128
	ds_read_b128 v[122:125], v39 offset:144
	ds_read_b128 v[126:129], v39 offset:160
	ds_read_b128 v[130:133], v39 offset:176
	ds_read_b128 v[134:137], v39 offset:192
	ds_read_b128 v[138:141], v39 offset:208
	ds_read_b128 v[142:145], v39 offset:224
	ds_read_b128 v[146:149], v39 offset:240
	s_addk_i32 s0, 0x100
	v_lshl_add_u64 v[74:75], v[74:75], 0, s[8:9]
	s_waitcnt vmcnt(10) lgkmcnt(14)
	v_pk_fma_f32 v[72:73], v[160:161], v[86:87], v[72:73] op_sel_hi:[0,1,1]
	v_pk_fma_f32 v[70:71], v[160:161], v[88:89], v[70:71] op_sel_hi:[0,1,1]
	v_pk_fma_f32 v[68:69], v[160:161], v[90:91], v[68:69] op_sel_hi:[0,1,1]
	v_pk_fma_f32 v[66:67], v[160:161], v[92:93], v[66:67] op_sel_hi:[0,1,1]
	s_waitcnt lgkmcnt(13)
	v_pk_fma_f32 v[64:65], v[160:161], v[94:95], v[64:65] op_sel_hi:[0,1,1]
	v_pk_fma_f32 v[62:63], v[160:161], v[96:97], v[62:63] op_sel_hi:[0,1,1]
	s_waitcnt lgkmcnt(12)
	v_pk_fma_f32 v[60:61], v[160:161], v[98:99], v[60:61] op_sel_hi:[0,1,1]
	v_pk_fma_f32 v[58:59], v[160:161], v[100:101], v[58:59] op_sel_hi:[0,1,1]
	s_waitcnt lgkmcnt(11)
	v_pk_fma_f32 v[56:57], v[160:161], v[102:103], v[56:57] op_sel_hi:[0,1,1]
	v_pk_fma_f32 v[54:55], v[160:161], v[104:105], v[54:55] op_sel_hi:[0,1,1]
	s_waitcnt lgkmcnt(10)
	v_pk_fma_f32 v[52:53], v[160:161], v[106:107], v[52:53] op_sel_hi:[0,1,1]
	v_pk_fma_f32 v[50:51], v[160:161], v[108:109], v[50:51] op_sel_hi:[0,1,1]
	s_waitcnt lgkmcnt(9)
	v_pk_fma_f32 v[48:49], v[160:161], v[110:111], v[48:49] op_sel_hi:[0,1,1]
	v_pk_fma_f32 v[46:47], v[160:161], v[112:113], v[46:47] op_sel_hi:[0,1,1]
	s_waitcnt lgkmcnt(8)
; #define LAS __attribute__((address_space(3)))
; DI void ada_item(const float* c, const float* wada, const float* bada, float* ada, LAS float* scr, int item, int lane) {
;     ...
; #pragma unroll 2
;     for (int k = 0; k < 128; ++k) { const float w = wp[(size_t)k * 6144];
; #pragma unroll
;         for (int b4 = 0; b4 < 8; ++b4) { const f32x4 sv = *(const LAS f32x4*)(scr + k * 32 + b4 * 4);
;             acc[4 * b4] += sv[0] * w; acc[4 * b4 + 1] += sv[1] * w; acc[4 * b4 + 2] += sv[2] * w; acc[4 * b4 + 3] += sv[3] * w; } }
	v_pk_fma_f32 v[44:45], v[160:161], v[114:115], v[44:45] op_sel_hi:[0,1,1]
	v_pk_fma_f32 v[42:43], v[160:161], v[116:117], v[42:43] op_sel_hi:[0,1,1]
	s_waitcnt lgkmcnt(7)
	v_pk_fma_f32 v[72:73], v[162:163], v[118:119], v[72:73] op_sel_hi:[0,1,1]
	v_pk_fma_f32 v[70:71], v[162:163], v[120:121], v[70:71] op_sel_hi:[0,1,1]
	s_waitcnt lgkmcnt(6)
	v_pk_fma_f32 v[68:69], v[162:163], v[122:123], v[68:69] op_sel_hi:[0,1,1]
	v_pk_fma_f32 v[66:67], v[162:163], v[124:125], v[66:67] op_sel_hi:[0,1,1]
	s_waitcnt lgkmcnt(5)
	v_pk_fma_f32 v[64:65], v[162:163], v[126:127], v[64:65] op_sel_hi:[0,1,1]
	v_pk_fma_f32 v[62:63], v[162:163], v[128:129], v[62:63] op_sel_hi:[0,1,1]
	s_waitcnt lgkmcnt(4)
	v_pk_fma_f32 v[60:61], v[162:163], v[130:131], v[60:61] op_sel_hi:[0,1,1]
	v_pk_fma_f32 v[58:59], v[162:163], v[132:133], v[58:59] op_sel_hi:[0,1,1]
	s_waitcnt lgkmcnt(3)
	v_pk_fma_f32 v[56:57], v[162:163], v[134:135], v[56:57] op_sel_hi:[0,1,1]
	v_pk_fma_f32 v[54:55], v[162:163], v[136:137], v[54:55] op_sel_hi:[0,1,1]
	s_waitcnt lgkmcnt(2)
	v_pk_fma_f32 v[52:53], v[162:163], v[138:139], v[52:53] op_sel_hi:[0,1,1]
	v_pk_fma_f32 v[50:51], v[162:163], v[140:141], v[50:51] op_sel_hi:[0,1,1]
	s_waitcnt lgkmcnt(1)
	v_pk_fma_f32 v[48:49], v[162:163], v[142:143], v[48:49] op_sel_hi:[0,1,1]
	v_pk_fma_f32 v[46:47], v[162:163], v[144:145], v[46:47] op_sel_hi:[0,1,1]
	s_waitcnt lgkmcnt(0)
	v_pk_fma_f32 v[44:45], v[162:163], v[146:147], v[44:45] op_sel_hi:[0,1,1]
	v_pk_fma_f32 v[42:43], v[162:163], v[148:149], v[42:43] op_sel_hi:[0,1,1]
	s_add_i32 s3, s13, s0
	v_mov_b32_e32 v39, s3
	ds_read_b128 v[86:89], v39
	ds_read_b128 v[90:93], v39 offset:16
	ds_read_b128 v[94:97], v39 offset:32
	ds_read_b128 v[98:101], v39 offset:48
	ds_read_b128 v[102:105], v39 offset:64
	ds_read_b128 v[106:109], v39 offset:80
	ds_read_b128 v[110:113], v39 offset:96
	ds_read_b128 v[114:117], v39 offset:112
	ds_read_b128 v[118:121], v39 offset:128
	ds_read_b128 v[122:125], v39 offset:144
	ds_read_b128 v[126:129], v39 offset:160
	ds_read_b128 v[130:133], v39 offset:176
	ds_read_b128 v[134:137], v39 offset:192
	ds_read_b128 v[138:141], v39 offset:208
	ds_read_b128 v[142:145], v39 offset:224
	ds_read_b128 v[146:149], v39 offset:240
	s_addk_i32 s0, 0x100
	v_lshl_add_u64 v[74:75], v[74:75], 0, s[8:9]
	s_waitcnt vmcnt(8) lgkmcnt(14)
	v_pk_fma_f32 v[72:73], v[164:165], v[86:87], v[72:73] op_sel_hi:[0,1,1]
	v_pk_fma_f32 v[70:71], v[164:165], v[88:89], v[70:71] op_sel_hi:[0,1,1]
	v_pk_fma_f32 v[68:69], v[164:165], v[90:91], v[68:69] op_sel_hi:[0,1,1]
	v_pk_fma_f32 v[66:67], v[164:165], v[92:93], v[66:67] op_sel_hi:[0,1,1]
	s_waitcnt lgkmcnt(13)
	v_pk_fma_f32 v[64:65], v[164:165], v[94:95], v[64:65] op_sel_hi:[0,1,1]
	v_pk_fma_f32 v[62:63], v[164:165], v[96:97], v[62:63] op_sel_hi:[0,1,1]
	s_waitcnt lgkmcnt(12)
	v_pk_fma_f32 v[60:61], v[164:165], v[98:99], v[60:61] op_sel_hi:[0,1,1]
	v_pk_fma_f32 v[58:59], v[164:165], v[100:101], v[58:59] op_sel_hi:[0,1,1]
	s_waitcnt lgkmcnt(11)
	v_pk_fma_f32 v[56:57], v[164:165], v[102:103], v[56:57] op_sel_hi:[0,1,1]
	v_pk_fma_f32 v[54:55], v[164:165], v[104:105], v[54:55] op_sel_hi:[0,1,1]
	s_waitcnt lgkmcnt(10)
	v_pk_fma_f32 v[52:53], v[164:165], v[106:107], v[52:53] op_sel_hi:[0,1,1]
	v_pk_fma_f32 v[50:51], v[164:165], v[108:109], v[50:51] op_sel_hi:[0,1,1]
	s_waitcnt lgkmcnt(9)
	v_pk_fma_f32 v[48:49], v[164:165], v[110:111], v[48:49] op_sel_hi:[0,1,1]
	v_pk_fma_f32 v[46:47], v[164:165], v[112:113], v[46:47] op_sel_hi:[0,1,1]
	s_waitcnt lgkmcnt(8)
	v_pk_fma_f32 v[44:45], v[164:165], v[114:115], v[44:45] op_sel_hi:[0,1,1]
	v_pk_fma_f32 v[42:43], v[164:165], v[116:117], v[42:43] op_sel_hi:[0,1,1]
	s_waitcnt lgkmcnt(7)
	v_pk_fma_f32 v[72:73], v[166:167], v[118:119], v[72:73] op_sel_hi:[0,1,1]
	v_pk_fma_f32 v[70:71], v[166:167], v[120:121], v[70:71] op_sel_hi:[0,1,1]
	s_waitcnt lgkmcnt(6)
	v_pk_fma_f32 v[68:69], v[166:167], v[122:123], v[68:69] op_sel_hi:[0,1,1]
	v_pk_fma_f32 v[66:67], v[166:167], v[124:125], v[66:67] op_sel_hi:[0,1,1]
	s_waitcnt lgkmcnt(5)
	v_pk_fma_f32 v[64:65], v[166:167], v[126:127], v[64:65] op_sel_hi:[0,1,1]
	v_pk_fma_f32 v[62:63], v[166:167], v[128:129], v[62:63] op_sel_hi:[0,1,1]
	s_waitcnt lgkmcnt(4)
	v_pk_fma_f32 v[60:61], v[166:167], v[130:131], v[60:61] op_sel_hi:[0,1,1]
	v_pk_fma_f32 v[58:59], v[166:167], v[132:133], v[58:59] op_sel_hi:[0,1,1]
	s_waitcnt lgkmcnt(3)
	v_pk_fma_f32 v[56:57], v[166:167], v[134:135], v[56:57] op_sel_hi:[0,1,1]
	v_pk_fma_f32 v[54:55], v[166:167], v[136:137], v[54:55] op_sel_hi:[0,1,1]
	s_waitcnt lgkmcnt(2)
	v_pk_fma_f32 v[52:53], v[166:167], v[138:139], v[52:53] op_sel_hi:[0,1,1]
	v_pk_fma_f32 v[50:51], v[166:167], v[140:141], v[50:51] op_sel_hi:[0,1,1]
	s_waitcnt lgkmcnt(1)
	v_pk_fma_f32 v[48:49], v[166:167], v[142:143], v[48:49] op_sel_hi:[0,1,1]
	v_pk_fma_f32 v[46:47], v[166:167], v[144:145], v[46:47] op_sel_hi:[0,1,1]
	s_waitcnt lgkmcnt(0)
	v_pk_fma_f32 v[44:45], v[166:167], v[146:147], v[44:45] op_sel_hi:[0,1,1]
	v_pk_fma_f32 v[42:43], v[166:167], v[148:149], v[42:43] op_sel_hi:[0,1,1]
	s_add_i32 s3, s13, s0
	v_mov_b32_e32 v39, s3
	ds_read_b128 v[86:89], v39
	ds_read_b128 v[90:93], v39 offset:16
	ds_read_b128 v[94:97], v39 offset:32
	ds_read_b128 v[98:101], v39 offset:48
	ds_read_b128 v[102:105], v39 offset:64
	ds_read_b128 v[106:109], v39 offset:80
	ds_read_b128 v[110:113], v39 offset:96
	ds_read_b128 v[114:117], v39 offset:112
	ds_read_b128 v[118:121], v39 offset:128
	ds_read_b128 v[122:125], v39 offset:144
	ds_read_b128 v[126:129], v39 offset:160
	ds_read_b128 v[130:133], v39 offset:176
	ds_read_b128 v[134:137], v39 offset:192
	ds_read_b128 v[138:141], v39 offset:208
	ds_read_b128 v[142:145], v39 offset:224
	ds_read_b128 v[146:149], v39 offset:240
	s_addk_i32 s0, 0x100
	v_lshl_add_u64 v[74:75], v[74:75], 0, s[8:9]
	s_waitcnt vmcnt(6) lgkmcnt(14)
; #define LAS __attribute__((address_space(3)))
; DI void ada_item(const float* c, const float* wada, const float* bada, float* ada, LAS float* scr, int item, int lane) {
;     ...
; #pragma unroll 2
;     for (int k = 0; k < 128; ++k) { const float w = wp[(size_t)k * 6144];
; #pragma unroll
;         for (int b4 = 0; b4 < 8; ++b4) { const f32x4 sv = *(const LAS f32x4*)(scr + k * 32 + b4 * 4);
;             acc[4 * b4] += sv[0] * w; acc[4 * b4 + 1] += sv[1] * w; acc[4 * b4 + 2] += sv[2] * w; acc[4 * b4 + 3] += sv[3] * w; } }
	v_pk_fma_f32 v[72:73], v[168:169], v[86:87], v[72:73] op_sel_hi:[0,1,1]
	v_pk_fma_f32 v[70:71], v[168:169], v[88:89], v[70:71] op_sel_hi:[0,1,1]
	v_pk_fma_f32 v[68:69], v[168:169], v[90:91], v[68:69] op_sel_hi:[0,1,1]
	v_pk_fma_f32 v[66:67], v[168:169], v[92:93], v[66:67] op_sel_hi:[0,1,1]
	s_waitcnt lgkmcnt(13)
	v_pk_fma_f32 v[64:65], v[168:169], v[94:95], v[64:65] op_sel_hi:[0,1,1]
	v_pk_fma_f32 v[62:63], v[168:169], v[96:97], v[62:63] op_sel_hi:[0,1,1]
	s_waitcnt lgkmcnt(12)
	v_pk_fma_f32 v[60:61], v[168:169], v[98:99], v[60:61] op_sel_hi:[0,1,1]
	v_pk_fma_f32 v[58:59], v[168:169], v[100:101], v[58:59] op_sel_hi:[0,1,1]
	s_waitcnt lgkmcnt(11)
	v_pk_fma_f32 v[56:57], v[168:169], v[102:103], v[56:57] op_sel_hi:[0,1,1]
	v_pk_fma_f32 v[54:55], v[168:169], v[104:105], v[54:55] op_sel_hi:[0,1,1]
	s_waitcnt lgkmcnt(10)
	v_pk_fma_f32 v[52:53], v[168:169], v[106:107], v[52:53] op_sel_hi:[0,1,1]
	v_pk_fma_f32 v[50:51], v[168:169], v[108:109], v[50:51] op_sel_hi:[0,1,1]
	s_waitcnt lgkmcnt(9)
	v_pk_fma_f32 v[48:49], v[168:169], v[110:111], v[48:49] op_sel_hi:[0,1,1]
	v_pk_fma_f32 v[46:47], v[168:169], v[112:113], v[46:47] op_sel_hi:[0,1,1]
	s_waitcnt lgkmcnt(8)
	v_pk_fma_f32 v[44:45], v[168:169], v[114:115], v[44:45] op_sel_hi:[0,1,1]
	v_pk_fma_f32 v[42:43], v[168:169], v[116:117], v[42:43] op_sel_hi:[0,1,1]
	s_waitcnt lgkmcnt(7)
	v_pk_fma_f32 v[72:73], v[170:171], v[118:119], v[72:73] op_sel_hi:[0,1,1]
	v_pk_fma_f32 v[70:71], v[170:171], v[120:121], v[70:71] op_sel_hi:[0,1,1]
	s_waitcnt lgkmcnt(6)
	v_pk_fma_f32 v[68:69], v[170:171], v[122:123], v[68:69] op_sel_hi:[0,1,1]
	v_pk_fma_f32 v[66:67], v[170:171], v[124:125], v[66:67] op_sel_hi:[0,1,1]
	s_waitcnt lgkmcnt(5)
	v_pk_fma_f32 v[64:65], v[170:171], v[126:127], v[64:65] op_sel_hi:[0,1,1]
	v_pk_fma_f32 v[62:63], v[170:171], v[128:129], v[62:63] op_sel_hi:[0,1,1]
	s_waitcnt lgkmcnt(4)
	v_pk_fma_f32 v[60:61], v[170:171], v[130:131], v[60:61] op_sel_hi:[0,1,1]
	v_pk_fma_f32 v[58:59], v[170:171], v[132:133], v[58:59] op_sel_hi:[0,1,1]
	s_waitcnt lgkmcnt(3)
	v_pk_fma_f32 v[56:57], v[170:171], v[134:135], v[56:57] op_sel_hi:[0,1,1]
	v_pk_fma_f32 v[54:55], v[170:171], v[136:137], v[54:55] op_sel_hi:[0,1,1]
	s_waitcnt lgkmcnt(2)
	v_pk_fma_f32 v[52:53], v[170:171], v[138:139], v[52:53] op_sel_hi:[0,1,1]
	v_pk_fma_f32 v[50:51], v[170:171], v[140:141], v[50:51] op_sel_hi:[0,1,1]
	s_waitcnt lgkmcnt(1)
	v_pk_fma_f32 v[48:49], v[170:171], v[142:143], v[48:49] op_sel_hi:[0,1,1]
	v_pk_fma_f32 v[46:47], v[170:171], v[144:145], v[46:47] op_sel_hi:[0,1,1]
	s_waitcnt lgkmcnt(0)
	v_pk_fma_f32 v[44:45], v[170:171], v[146:147], v[44:45] op_sel_hi:[0,1,1]
	v_pk_fma_f32 v[42:43], v[170:171], v[148:149], v[42:43] op_sel_hi:[0,1,1]
	s_add_i32 s3, s13, s0
	v_mov_b32_e32 v39, s3
	ds_read_b128 v[86:89], v39
	ds_read_b128 v[90:93], v39 offset:16
	ds_read_b128 v[94:97], v39 offset:32
	ds_read_b128 v[98:101], v39 offset:48
	ds_read_b128 v[102:105], v39 offset:64
	ds_read_b128 v[106:109], v39 offset:80
	ds_read_b128 v[110:113], v39 offset:96
	ds_read_b128 v[114:117], v39 offset:112
	ds_read_b128 v[118:121], v39 offset:128
	ds_read_b128 v[122:125], v39 offset:144
	ds_read_b128 v[126:129], v39 offset:160
	ds_read_b128 v[130:133], v39 offset:176
	ds_read_b128 v[134:137], v39 offset:192
	ds_read_b128 v[138:141], v39 offset:208
	ds_read_b128 v[142:145], v39 offset:224
	ds_read_b128 v[146:149], v39 offset:240
	s_addk_i32 s0, 0x100
	v_lshl_add_u64 v[74:75], v[74:75], 0, s[8:9]
	s_waitcnt vmcnt(4) lgkmcnt(14)
	v_pk_fma_f32 v[72:73], v[172:173], v[86:87], v[72:73] op_sel_hi:[0,1,1]
	v_pk_fma_f32 v[70:71], v[172:173], v[88:89], v[70:71] op_sel_hi:[0,1,1]
	v_pk_fma_f32 v[68:69], v[172:173], v[90:91], v[68:69] op_sel_hi:[0,1,1]
	v_pk_fma_f32 v[66:67], v[172:173], v[92:93], v[66:67] op_sel_hi:[0,1,1]
	s_waitcnt lgkmcnt(13)
	v_pk_fma_f32 v[64:65], v[172:173], v[94:95], v[64:65] op_sel_hi:[0,1,1]
	v_pk_fma_f32 v[62:63], v[172:173], v[96:97], v[62:63] op_sel_hi:[0,1,1]
	s_waitcnt lgkmcnt(12)
	v_pk_fma_f32 v[60:61], v[172:173], v[98:99], v[60:61] op_sel_hi:[0,1,1]
	v_pk_fma_f32 v[58:59], v[172:173], v[100:101], v[58:59] op_sel_hi:[0,1,1]
	s_waitcnt lgkmcnt(11)
	v_pk_fma_f32 v[56:57], v[172:173], v[102:103], v[56:57] op_sel_hi:[0,1,1]
	v_pk_fma_f32 v[54:55], v[172:173], v[104:105], v[54:55] op_sel_hi:[0,1,1]
	s_waitcnt lgkmcnt(10)
	v_pk_fma_f32 v[52:53], v[172:173], v[106:107], v[52:53] op_sel_hi:[0,1,1]
	v_pk_fma_f32 v[50:51], v[172:173], v[108:109], v[50:51] op_sel_hi:[0,1,1]
	s_waitcnt lgkmcnt(9)
	v_pk_fma_f32 v[48:49], v[172:173], v[110:111], v[48:49] op_sel_hi:[0,1,1]
	v_pk_fma_f32 v[46:47], v[172:173], v[112:113], v[46:47] op_sel_hi:[0,1,1]
	s_waitcnt lgkmcnt(8)
	v_pk_fma_f32 v[44:45], v[172:173], v[114:115], v[44:45] op_sel_hi:[0,1,1]
	v_pk_fma_f32 v[42:43], v[172:173], v[116:117], v[42:43] op_sel_hi:[0,1,1]
	s_waitcnt lgkmcnt(7)
	v_pk_fma_f32 v[72:73], v[174:175], v[118:119], v[72:73] op_sel_hi:[0,1,1]
	v_pk_fma_f32 v[70:71], v[174:175], v[120:121], v[70:71] op_sel_hi:[0,1,1]
	s_waitcnt lgkmcnt(6)
	v_pk_fma_f32 v[68:69], v[174:175], v[122:123], v[68:69] op_sel_hi:[0,1,1]
	v_pk_fma_f32 v[66:67], v[174:175], v[124:125], v[66:67] op_sel_hi:[0,1,1]
	s_waitcnt lgkmcnt(5)
	v_pk_fma_f32 v[64:65], v[174:175], v[126:127], v[64:65] op_sel_hi:[0,1,1]
	v_pk_fma_f32 v[62:63], v[174:175], v[128:129], v[62:63] op_sel_hi:[0,1,1]
	s_waitcnt lgkmcnt(4)
	v_pk_fma_f32 v[60:61], v[174:175], v[130:131], v[60:61] op_sel_hi:[0,1,1]
	v_pk_fma_f32 v[58:59], v[174:175], v[132:133], v[58:59] op_sel_hi:[0,1,1]
	s_waitcnt lgkmcnt(3)
	v_pk_fma_f32 v[56:57], v[174:175], v[134:135], v[56:57] op_sel_hi:[0,1,1]
	v_pk_fma_f32 v[54:55], v[174:175], v[136:137], v[54:55] op_sel_hi:[0,1,1]
	s_waitcnt lgkmcnt(2)
; #define LAS __attribute__((address_space(3)))
; DI void ada_item(const float* c, const float* wada, const float* bada, float* ada, LAS float* scr, int item, int lane) {
;     ...
; #pragma unroll 2
;     for (int k = 0; k < 128; ++k) { const float w = wp[(size_t)k * 6144];
; #pragma unroll
;         for (int b4 = 0; b4 < 8; ++b4) { const f32x4 sv = *(const LAS f32x4*)(scr + k * 32 + b4 * 4);
;             acc[4 * b4] += sv[0] * w; acc[4 * b4 + 1] += sv[1] * w; acc[4 * b4 + 2] += sv[2] * w; acc[4 * b4 + 3] += sv[3] * w; } }
	v_pk_fma_f32 v[52:53], v[174:175], v[138:139], v[52:53] op_sel_hi:[0,1,1]
	v_pk_fma_f32 v[50:51], v[174:175], v[140:141], v[50:51] op_sel_hi:[0,1,1]
	s_waitcnt lgkmcnt(1)
	v_pk_fma_f32 v[48:49], v[174:175], v[142:143], v[48:49] op_sel_hi:[0,1,1]
	v_pk_fma_f32 v[46:47], v[174:175], v[144:145], v[46:47] op_sel_hi:[0,1,1]
	s_waitcnt lgkmcnt(0)
	v_pk_fma_f32 v[44:45], v[174:175], v[146:147], v[44:45] op_sel_hi:[0,1,1]
	v_pk_fma_f32 v[42:43], v[174:175], v[148:149], v[42:43] op_sel_hi:[0,1,1]
	s_add_i32 s3, s13, s0
	v_mov_b32_e32 v39, s3
	ds_read_b128 v[86:89], v39
	ds_read_b128 v[90:93], v39 offset:16
	ds_read_b128 v[94:97], v39 offset:32
	ds_read_b128 v[98:101], v39 offset:48
	ds_read_b128 v[102:105], v39 offset:64
	ds_read_b128 v[106:109], v39 offset:80
	ds_read_b128 v[110:113], v39 offset:96
	ds_read_b128 v[114:117], v39 offset:112
	ds_read_b128 v[118:121], v39 offset:128
	ds_read_b128 v[122:125], v39 offset:144
	ds_read_b128 v[126:129], v39 offset:160
	ds_read_b128 v[130:133], v39 offset:176
	ds_read_b128 v[134:137], v39 offset:192
	ds_read_b128 v[138:141], v39 offset:208
	ds_read_b128 v[142:145], v39 offset:224
	ds_read_b128 v[146:149], v39 offset:240
	s_addk_i32 s0, 0x100
	v_lshl_add_u64 v[74:75], v[74:75], 0, s[8:9]
	s_waitcnt vmcnt(2) lgkmcnt(14)
	v_pk_fma_f32 v[72:73], v[176:177], v[86:87], v[72:73] op_sel_hi:[0,1,1]
	v_pk_fma_f32 v[70:71], v[176:177], v[88:89], v[70:71] op_sel_hi:[0,1,1]
	v_pk_fma_f32 v[68:69], v[176:177], v[90:91], v[68:69] op_sel_hi:[0,1,1]
	v_pk_fma_f32 v[66:67], v[176:177], v[92:93], v[66:67] op_sel_hi:[0,1,1]
	s_waitcnt lgkmcnt(13)
	v_pk_fma_f32 v[64:65], v[176:177], v[94:95], v[64:65] op_sel_hi:[0,1,1]
	v_pk_fma_f32 v[62:63], v[176:177], v[96:97], v[62:63] op_sel_hi:[0,1,1]
	s_waitcnt lgkmcnt(12)
	v_pk_fma_f32 v[60:61], v[176:177], v[98:99], v[60:61] op_sel_hi:[0,1,1]
	v_pk_fma_f32 v[58:59], v[176:177], v[100:101], v[58:59] op_sel_hi:[0,1,1]
	s_waitcnt lgkmcnt(11)
	v_pk_fma_f32 v[56:57], v[176:177], v[102:103], v[56:57] op_sel_hi:[0,1,1]
	v_pk_fma_f32 v[54:55], v[176:177], v[104:105], v[54:55] op_sel_hi:[0,1,1]
	s_waitcnt lgkmcnt(10)
	v_pk_fma_f32 v[52:53], v[176:177], v[106:107], v[52:53] op_sel_hi:[0,1,1]
	v_pk_fma_f32 v[50:51], v[176:177], v[108:109], v[50:51] op_sel_hi:[0,1,1]
	s_waitcnt lgkmcnt(9)
	v_pk_fma_f32 v[48:49], v[176:177], v[110:111], v[48:49] op_sel_hi:[0,1,1]
	v_pk_fma_f32 v[46:47], v[176:177], v[112:113], v[46:47] op_sel_hi:[0,1,1]
	s_waitcnt lgkmcnt(8)
	v_pk_fma_f32 v[44:45], v[176:177], v[114:115], v[44:45] op_sel_hi:[0,1,1]
	v_pk_fma_f32 v[42:43], v[176:177], v[116:117], v[42:43] op_sel_hi:[0,1,1]
	s_waitcnt lgkmcnt(7)
	v_pk_fma_f32 v[72:73], v[178:179], v[118:119], v[72:73] op_sel_hi:[0,1,1]
	v_pk_fma_f32 v[70:71], v[178:179], v[120:121], v[70:71] op_sel_hi:[0,1,1]
	s_waitcnt lgkmcnt(6)
	v_pk_fma_f32 v[68:69], v[178:179], v[122:123], v[68:69] op_sel_hi:[0,1,1]
	v_pk_fma_f32 v[66:67], v[178:179], v[124:125], v[66:67] op_sel_hi:[0,1,1]
	s_waitcnt lgkmcnt(5)
	v_pk_fma_f32 v[64:65], v[178:179], v[126:127], v[64:65] op_sel_hi:[0,1,1]
	v_pk_fma_f32 v[62:63], v[178:179], v[128:129], v[62:63] op_sel_hi:[0,1,1]
	s_waitcnt lgkmcnt(4)
	v_pk_fma_f32 v[60:61], v[178:179], v[130:131], v[60:61] op_sel_hi:[0,1,1]
	v_pk_fma_f32 v[58:59], v[178:179], v[132:133], v[58:59] op_sel_hi:[0,1,1]
	s_waitcnt lgkmcnt(3)
	v_pk_fma_f32 v[56:57], v[178:179], v[134:135], v[56:57] op_sel_hi:[0,1,1]
	v_pk_fma_f32 v[54:55], v[178:179], v[136:137], v[54:55] op_sel_hi:[0,1,1]
	s_waitcnt lgkmcnt(2)
	v_pk_fma_f32 v[52:53], v[178:179], v[138:139], v[52:53] op_sel_hi:[0,1,1]
	v_pk_fma_f32 v[50:51], v[178:179], v[140:141], v[50:51] op_sel_hi:[0,1,1]
	s_waitcnt lgkmcnt(1)
	v_pk_fma_f32 v[48:49], v[178:179], v[142:143], v[48:49] op_sel_hi:[0,1,1]
	v_pk_fma_f32 v[46:47], v[178:179], v[144:145], v[46:47] op_sel_hi:[0,1,1]
	s_waitcnt lgkmcnt(0)
; #define LAS __attribute__((address_space(3)))
; DI void ada_item(const float* c, const float* wada, const float* bada, float* ada, LAS float* scr, int item, int lane) {
;     ...
;     for (int k = 0; k < 128; ++k) { const float w = wp[(size_t)k * 6144];
; #pragma unroll
;         for (int b4 = 0; b4 < 8; ++b4) { const f32x4 sv = *(const LAS f32x4*)(scr + k * 32 + b4 * 4);
;             acc[4 * b4] += sv[0] * w; acc[4 * b4 + 1] += sv[1] * w; acc[4 * b4 + 2] += sv[2] * w; acc[4 * b4 + 3] += sv[3] * w; } }
;     const int col = cb * 64 + lane; const float bias = (kc == 0) ? bada[col] : 0.f;
	v_pk_fma_f32 v[44:45], v[178:179], v[146:147], v[44:45] op_sel_hi:[0,1,1]
	v_pk_fma_f32 v[42:43], v[178:179], v[148:149], v[42:43] op_sel_hi:[0,1,1]
	s_add_i32 s3, s13, s0
	v_mov_b32_e32 v39, s3
	ds_read_b128 v[86:89], v39
	ds_read_b128 v[90:93], v39 offset:16
	ds_read_b128 v[94:97], v39 offset:32
	ds_read_b128 v[98:101], v39 offset:48
	ds_read_b128 v[102:105], v39 offset:64
	ds_read_b128 v[106:109], v39 offset:80
	ds_read_b128 v[110:113], v39 offset:96
	ds_read_b128 v[114:117], v39 offset:112
	ds_read_b128 v[118:121], v39 offset:128
	ds_read_b128 v[122:125], v39 offset:144
	ds_read_b128 v[126:129], v39 offset:160
	ds_read_b128 v[130:133], v39 offset:176
	ds_read_b128 v[134:137], v39 offset:192
	ds_read_b128 v[138:141], v39 offset:208
	ds_read_b128 v[142:145], v39 offset:224
	ds_read_b128 v[146:149], v39 offset:240
	s_addk_i32 s0, 0x100
	v_lshl_add_u64 v[74:75], v[74:75], 0, s[8:9]
	s_waitcnt vmcnt(0) lgkmcnt(14)
	v_pk_fma_f32 v[72:73], v[180:181], v[86:87], v[72:73] op_sel_hi:[0,1,1]
	v_pk_fma_f32 v[70:71], v[180:181], v[88:89], v[70:71] op_sel_hi:[0,1,1]
	v_pk_fma_f32 v[68:69], v[180:181], v[90:91], v[68:69] op_sel_hi:[0,1,1]
	v_pk_fma_f32 v[66:67], v[180:181], v[92:93], v[66:67] op_sel_hi:[0,1,1]
	s_waitcnt lgkmcnt(13)
	v_pk_fma_f32 v[64:65], v[180:181], v[94:95], v[64:65] op_sel_hi:[0,1,1]
	v_pk_fma_f32 v[62:63], v[180:181], v[96:97], v[62:63] op_sel_hi:[0,1,1]
	s_waitcnt lgkmcnt(12)
	v_pk_fma_f32 v[60:61], v[180:181], v[98:99], v[60:61] op_sel_hi:[0,1,1]
	v_pk_fma_f32 v[58:59], v[180:181], v[100:101], v[58:59] op_sel_hi:[0,1,1]
	s_waitcnt lgkmcnt(11)
	v_pk_fma_f32 v[56:57], v[180:181], v[102:103], v[56:57] op_sel_hi:[0,1,1]
	v_pk_fma_f32 v[54:55], v[180:181], v[104:105], v[54:55] op_sel_hi:[0,1,1]
	s_waitcnt lgkmcnt(10)
	v_pk_fma_f32 v[52:53], v[180:181], v[106:107], v[52:53] op_sel_hi:[0,1,1]
	v_pk_fma_f32 v[50:51], v[180:181], v[108:109], v[50:51] op_sel_hi:[0,1,1]
	s_waitcnt lgkmcnt(9)
	v_pk_fma_f32 v[48:49], v[180:181], v[110:111], v[48:49] op_sel_hi:[0,1,1]
	v_pk_fma_f32 v[46:47], v[180:181], v[112:113], v[46:47] op_sel_hi:[0,1,1]
	s_waitcnt lgkmcnt(8)
	v_pk_fma_f32 v[44:45], v[180:181], v[114:115], v[44:45] op_sel_hi:[0,1,1]
	v_pk_fma_f32 v[42:43], v[180:181], v[116:117], v[42:43] op_sel_hi:[0,1,1]
	s_waitcnt lgkmcnt(7)
	v_pk_fma_f32 v[72:73], v[182:183], v[118:119], v[72:73] op_sel_hi:[0,1,1]
	v_pk_fma_f32 v[70:71], v[182:183], v[120:121], v[70:71] op_sel_hi:[0,1,1]
	s_waitcnt lgkmcnt(6)
	v_pk_fma_f32 v[68:69], v[182:183], v[122:123], v[68:69] op_sel_hi:[0,1,1]
	v_pk_fma_f32 v[66:67], v[182:183], v[124:125], v[66:67] op_sel_hi:[0,1,1]
	s_waitcnt lgkmcnt(5)
	v_pk_fma_f32 v[64:65], v[182:183], v[126:127], v[64:65] op_sel_hi:[0,1,1]
	v_pk_fma_f32 v[62:63], v[182:183], v[128:129], v[62:63] op_sel_hi:[0,1,1]
	s_waitcnt lgkmcnt(4)
	v_pk_fma_f32 v[60:61], v[182:183], v[130:131], v[60:61] op_sel_hi:[0,1,1]
	v_pk_fma_f32 v[58:59], v[182:183], v[132:133], v[58:59] op_sel_hi:[0,1,1]
	s_waitcnt lgkmcnt(3)
	v_pk_fma_f32 v[56:57], v[182:183], v[134:135], v[56:57] op_sel_hi:[0,1,1]
	v_pk_fma_f32 v[54:55], v[182:183], v[136:137], v[54:55] op_sel_hi:[0,1,1]
	s_waitcnt lgkmcnt(2)
	v_pk_fma_f32 v[52:53], v[182:183], v[138:139], v[52:53] op_sel_hi:[0,1,1]
	v_pk_fma_f32 v[50:51], v[182:183], v[140:141], v[50:51] op_sel_hi:[0,1,1]
	s_waitcnt lgkmcnt(1)
	v_pk_fma_f32 v[48:49], v[182:183], v[142:143], v[48:49] op_sel_hi:[0,1,1]
	v_pk_fma_f32 v[46:47], v[182:183], v[144:145], v[46:47] op_sel_hi:[0,1,1]
	s_waitcnt lgkmcnt(0)
	v_pk_fma_f32 v[44:45], v[182:183], v[146:147], v[44:45] op_sel_hi:[0,1,1]
	v_pk_fma_f32 v[42:43], v[182:183], v[148:149], v[42:43] op_sel_hi:[0,1,1]
	v_or_b32_e32 v74, s2, v2
	s_add_i32 s0, s12, 0x5f
	s_cmpk_lt_u32 s0, 0xbf
	v_ashrrev_i32_e32 v75, 31, v74
	v_mov_b32_e32 v6, 0
	s_cbranch_scc0 .LBB0_7
	v_lshl_add_u64 v[86:87], v[74:75], 2, s[58:59]
	global_load_dword v6, v[86:87], off
	s_branch .LBB0_7

; #define LDS_WAIT() asm volatile("s_waitcnt lgkmcnt(0)" ::: "memory")
; DI void bias2_item(const float* ada, const float* w1, float* bias2, LAS float* scr, int item, int lane) {
;     const int cb = item % 64, kc = item / 64;
; #pragma unroll 4
;     for (int i = 0; i < 64; ++i) { const int idx = i * 64 + lane, k = idx >> 5, b = idx & 31; scr[idx] = ada[(size_t)b * 6144 + 3072 + kc * 128 + k]; }
;     LDS_WAIT(); asm volatile("" ::: "memory");
;     float acc[32];
; #pragma unroll
;     for (int b = 0; b < 32; ++b) acc[b] = 0.f;
;     const float* wp = w1 + (size_t)(kc * 128) * 4096 + cb * 64 + lane;
; #pragma unroll 2
;     for (int k = 0; k < 128; ++k) { const float w = wp[(size_t)k * 4096];
.LBB0_79:
	s_lshl_b32 s14, s12, 6
	s_lshl_b32 s13, s9, 6
	v_or_b32_e32 v14, s14, v16
	v_or_b32_e32 v4, s13, v5
	s_add_i32 s16, s14, 0x80
	v_lshrrev_b32_e32 v0, 3, v14
	s_add_i32 s15, s13, 0x80
	v_lshrrev_b32_e32 v12, 3, v4
	v_or_b32_e32 v17, s16, v16
	v_and_b32_e32 v0, 0x1ffffffc, v0
	s_add_i32 s18, s14, 0x100
	v_or_b32_e32 v15, s15, v5
	v_lshrrev_b32_e32 v22, 3, v17
	v_lshl_add_u64 v[10:11], v[8:9], 0, v[0:1]
	v_and_b32_e32 v0, 0x1ffffffc, v12
	s_add_i32 s17, s13, 0x100
	v_or_b32_e32 v19, s18, v16
	v_lshrrev_b32_e32 v23, 3, v15
	v_lshl_add_u64 v[12:13], v[8:9], 0, v[0:1]
	v_and_b32_e32 v0, 0x1ffffffc, v22
	s_addk_i32 s14, 0x180
	v_or_b32_e32 v18, s17, v5
	v_lshrrev_b32_e32 v24, 3, v19
	global_load_dword v22, v[10:11], off
	global_load_dword v28, v[12:13], off
	v_lshl_add_u64 v[10:11], v[8:9], 0, v[0:1]
	v_and_b32_e32 v0, 0x1ffffffc, v23
	s_addk_i32 s13, 0x180
	v_or_b32_e32 v21, s14, v16
	v_lshrrev_b32_e32 v25, 3, v18
	v_lshl_add_u64 v[12:13], v[8:9], 0, v[0:1]
	v_and_b32_e32 v0, 0x1ffffffc, v24
	v_or_b32_e32 v20, s13, v5
	v_lshrrev_b32_e32 v26, 3, v21
	global_load_dword v23, v[10:11], off
	global_load_dword v24, v[12:13], off
	v_lshl_add_u64 v[10:11], v[8:9], 0, v[0:1]
	v_and_b32_e32 v0, 0x1ffffffc, v25
	v_lshrrev_b32_e32 v27, 3, v20
	v_lshl_add_u64 v[12:13], v[8:9], 0, v[0:1]
	v_and_b32_e32 v0, 0x1ffffffc, v26
	global_load_dword v25, v[10:11], off
	global_load_dword v26, v[12:13], off
	v_lshl_add_u64 v[10:11], v[8:9], 0, v[0:1]
	v_and_b32_e32 v0, 0x1ffffffc, v27
	v_lshl_add_u64 v[12:13], v[8:9], 0, v[0:1]
	global_load_dword v0, v[10:11], off
	s_nop 0
	global_load_dword v10, v[12:13], off
	s_add_i32 s12, s12, 8
	s_add_i32 s9, s9, 8
	s_add_i32 s11, s11, -8
	v_lshl_add_u32 v11, v14, 2, s5
	s_cmp_lg_u32 s11, 0
	v_lshl_add_u32 v4, v4, 2, s5
	v_lshl_add_u32 v12, v17, 2, s5
	v_lshl_add_u32 v13, v15, 2, s5
	v_lshl_add_u32 v14, v19, 2, s5
	v_lshl_add_u32 v15, v18, 2, s5
	v_lshl_add_u32 v17, v21, 2, s5
	v_lshl_add_u32 v18, v20, 2, s5
	s_waitcnt vmcnt(7)
	ds_write_b32 v11, v22
	s_waitcnt vmcnt(6)
	ds_write_b32 v4, v28
	s_waitcnt vmcnt(5)
	ds_write_b32 v12, v23
	s_waitcnt vmcnt(4)
	ds_write_b32 v13, v24
	s_waitcnt vmcnt(3)
	ds_write_b32 v14, v25
	s_waitcnt vmcnt(2)
	ds_write_b32 v15, v26
	s_waitcnt vmcnt(1)
	ds_write_b32 v17, v0
	s_waitcnt vmcnt(0)
	ds_write_b32 v18, v10
	s_cbranch_scc1 .LBB0_79
	s_lshl_b32 s8, s8, 6
	v_readlane_b32 s12, v251, 0
	s_sub_i32 s8, s7, s8
	s_lshl_b64 s[2:3], s[2:3], 14
	v_readlane_b32 s14, v251, 2
	v_readlane_b32 s15, v251, 3
	s_add_u32 s11, s14, s2
	s_addc_u32 s12, s15, s3
	s_lshl_b32 s2, s8, 6
	s_ashr_i32 s3, s2, 31
	s_waitcnt lgkmcnt(0)
	s_lshl_b64 s[8:9], s[2:3], 2
	s_add_u32 s8, s11, s8
	s_addc_u32 s9, s12, s9
	v_mov_b32_e32 v8, 0
	v_lshl_add_u64 v[40:41], s[8:9], 0, v[6:7]
	s_mov_b32 s3, 0
	v_mov_b32_e32 v9, v8
	v_mov_b32_e32 v42, v8
	v_mov_b32_e32 v43, v8
	v_mov_b32_e32 v38, v8
	v_mov_b32_e32 v39, v8
	v_mov_b32_e32 v36, v8
	v_mov_b32_e32 v37, v8
	v_mov_b32_e32 v34, v8
	v_mov_b32_e32 v35, v8
	v_mov_b32_e32 v32, v8
	v_mov_b32_e32 v33, v8
	v_mov_b32_e32 v30, v8
	v_mov_b32_e32 v31, v8
	v_mov_b32_e32 v28, v8
	v_mov_b32_e32 v29, v8
	v_mov_b32_e32 v26, v8
	v_mov_b32_e32 v27, v8
	v_mov_b32_e32 v24, v8
	v_mov_b32_e32 v25, v8
	v_mov_b32_e32 v22, v8
	v_mov_b32_e32 v23, v8
	v_mov_b32_e32 v20, v8
	v_mov_b32_e32 v21, v8
	v_mov_b32_e32 v18, v8
	v_mov_b32_e32 v19, v8
	v_mov_b32_e32 v14, v8
	v_mov_b32_e32 v15, v8
	v_mov_b32_e32 v12, v8
	v_mov_b32_e32 v13, v8
	v_mov_b32_e32 v10, v8
	v_mov_b32_e32 v11, v8
	v_readlane_b32 s13, v251, 1
	v_readlane_b32 s16, v251, 4
	v_readlane_b32 s17, v251, 5
	v_readlane_b32 s18, v251, 6
	v_readlane_b32 s19, v251, 7
	v_mov_b32_e32 v184, v40
	v_mov_b32_e32 v185, v41
	global_load_dword v152, v[184:185], off
	v_add_co_u32_e32 v186, vcc, s6, v184
	s_nop 1
	v_addc_co_u32_e32 v187, vcc, 0, v185, vcc
	global_load_dword v154, v[186:187], off
	v_lshl_add_u64 v[184:185], v[184:185], 0, s[0:1]
	global_load_dword v156, v[184:185], off
	v_add_co_u32_e32 v186, vcc, s6, v184
	s_nop 1
	v_addc_co_u32_e32 v187, vcc, 0, v185, vcc
	global_load_dword v158, v[186:187], off
	v_lshl_add_u64 v[184:185], v[184:185], 0, s[0:1]
	global_load_dword v160, v[184:185], off
	v_add_co_u32_e32 v186, vcc, s6, v184
	s_nop 1
	v_addc_co_u32_e32 v187, vcc, 0, v185, vcc
	global_load_dword v162, v[186:187], off
	v_lshl_add_u64 v[184:185], v[184:185], 0, s[0:1]
	global_load_dword v164, v[184:185], off
	v_add_co_u32_e32 v186, vcc, s6, v184
	s_nop 1
	v_addc_co_u32_e32 v187, vcc, 0, v185, vcc
	global_load_dword v166, v[186:187], off
	v_lshl_add_u64 v[184:185], v[184:185], 0, s[0:1]
	global_load_dword v168, v[184:185], off
	v_add_co_u32_e32 v186, vcc, s6, v184
	s_nop 1
	v_addc_co_u32_e32 v187, vcc, 0, v185, vcc
	global_load_dword v170, v[186:187], off
	v_lshl_add_u64 v[184:185], v[184:185], 0, s[0:1]
	global_load_dword v172, v[184:185], off
	v_add_co_u32_e32 v186, vcc, s6, v184
	s_nop 1
	v_addc_co_u32_e32 v187, vcc, 0, v185, vcc
	global_load_dword v174, v[186:187], off
	v_lshl_add_u64 v[184:185], v[184:185], 0, s[0:1]
	global_load_dword v176, v[184:185], off
	v_add_co_u32_e32 v186, vcc, s6, v184
	s_nop 1
	v_addc_co_u32_e32 v187, vcc, 0, v185, vcc
	global_load_dword v178, v[186:187], off
	v_lshl_add_u64 v[184:185], v[184:185], 0, s[0:1]
	global_load_dword v180, v[184:185], off
	v_add_co_u32_e32 v186, vcc, s6, v184
	s_nop 1
	v_addc_co_u32_e32 v187, vcc, 0, v185, vcc
	global_load_dword v182, v[186:187], off
	v_lshl_add_u64 v[184:185], v[184:185], 0, s[0:1]
; #define LAS __attribute__((address_space(3)))
; DI void bias2_item(const float* ada, const float* w1, float* bias2, LAS float* scr, int item, int lane) {
;     ...
;     for (int k = 0; k < 128; ++k) { const float w = wp[(size_t)k * 4096];
; #pragma unroll
;         for (int b4 = 0; b4 < 8; ++b4) { const f32x4 sv = *(const LAS f32x4*)(scr + k * 32 + b4 * 4);
;             acc[4 * b4] += sv[0] * w; acc[4 * b4 + 1] += sv[1] * w; acc[4 * b4 + 2] += sv[2] * w; acc[4 * b4 + 3] += sv[3] * w; } }
.LBB0_81:
	s_add_i32 s8, s5, s3
	v_mov_b32_e32 v17, s8
	ds_read_b128 v[44:47], v17
	ds_read_b128 v[48:51], v17 offset:16
	ds_read_b128 v[52:55], v17 offset:32
	ds_read_b128 v[56:59], v17 offset:48
	ds_read_b128 v[60:63], v17 offset:64
	ds_read_b128 v[64:67], v17 offset:80
	ds_read_b128 v[68:71], v17 offset:96
	ds_read_b128 v[72:75], v17 offset:112
	ds_read_b128 v[76:79], v17 offset:128
	ds_read_b128 v[80:83], v17 offset:144
	ds_read_b128 v[84:87], v17 offset:160
	ds_read_b128 v[88:91], v17 offset:176
	ds_read_b128 v[92:95], v17 offset:192
	ds_read_b128 v[96:99], v17 offset:208
	ds_read_b128 v[100:103], v17 offset:224
	ds_read_b128 v[104:107], v17 offset:240
	s_addk_i32 s3, 0x100
	v_lshl_add_u64 v[40:41], v[40:41], 0, s[0:1]
	s_waitcnt vmcnt(14) lgkmcnt(14)
	v_pk_fma_f32 v[42:43], v[152:153], v[44:45], v[42:43] op_sel_hi:[0,1,1]
	v_pk_fma_f32 v[38:39], v[152:153], v[46:47], v[38:39] op_sel_hi:[0,1,1]
	v_pk_fma_f32 v[36:37], v[152:153], v[48:49], v[36:37] op_sel_hi:[0,1,1]
	v_pk_fma_f32 v[34:35], v[152:153], v[50:51], v[34:35] op_sel_hi:[0,1,1]
	s_waitcnt lgkmcnt(13)
	v_pk_fma_f32 v[32:33], v[152:153], v[52:53], v[32:33] op_sel_hi:[0,1,1]
	v_pk_fma_f32 v[30:31], v[152:153], v[54:55], v[30:31] op_sel_hi:[0,1,1]
	s_waitcnt lgkmcnt(12)
	v_pk_fma_f32 v[28:29], v[152:153], v[56:57], v[28:29] op_sel_hi:[0,1,1]
	v_pk_fma_f32 v[26:27], v[152:153], v[58:59], v[26:27] op_sel_hi:[0,1,1]
	s_waitcnt lgkmcnt(11)
	v_pk_fma_f32 v[24:25], v[152:153], v[60:61], v[24:25] op_sel_hi:[0,1,1]
	v_pk_fma_f32 v[22:23], v[152:153], v[62:63], v[22:23] op_sel_hi:[0,1,1]
	s_waitcnt lgkmcnt(10)
	v_pk_fma_f32 v[20:21], v[152:153], v[64:65], v[20:21] op_sel_hi:[0,1,1]
	v_pk_fma_f32 v[18:19], v[152:153], v[66:67], v[18:19] op_sel_hi:[0,1,1]
	s_waitcnt lgkmcnt(9)
	v_pk_fma_f32 v[14:15], v[152:153], v[68:69], v[14:15] op_sel_hi:[0,1,1]
	v_pk_fma_f32 v[12:13], v[152:153], v[70:71], v[12:13] op_sel_hi:[0,1,1]
	s_waitcnt lgkmcnt(8)
	v_pk_fma_f32 v[10:11], v[152:153], v[72:73], v[10:11] op_sel_hi:[0,1,1]
	v_pk_fma_f32 v[8:9], v[152:153], v[74:75], v[8:9] op_sel_hi:[0,1,1]
	s_waitcnt lgkmcnt(7)
	v_pk_fma_f32 v[42:43], v[154:155], v[76:77], v[42:43] op_sel_hi:[0,1,1]
	v_pk_fma_f32 v[38:39], v[154:155], v[78:79], v[38:39] op_sel_hi:[0,1,1]
	s_waitcnt lgkmcnt(6)
	v_pk_fma_f32 v[36:37], v[154:155], v[80:81], v[36:37] op_sel_hi:[0,1,1]
	v_pk_fma_f32 v[34:35], v[154:155], v[82:83], v[34:35] op_sel_hi:[0,1,1]
	s_waitcnt lgkmcnt(5)
	v_pk_fma_f32 v[32:33], v[154:155], v[84:85], v[32:33] op_sel_hi:[0,1,1]
	v_pk_fma_f32 v[30:31], v[154:155], v[86:87], v[30:31] op_sel_hi:[0,1,1]
	s_waitcnt lgkmcnt(4)
	v_pk_fma_f32 v[28:29], v[154:155], v[88:89], v[28:29] op_sel_hi:[0,1,1]
	v_pk_fma_f32 v[26:27], v[154:155], v[90:91], v[26:27] op_sel_hi:[0,1,1]
	s_waitcnt lgkmcnt(3)
	v_pk_fma_f32 v[24:25], v[154:155], v[92:93], v[24:25] op_sel_hi:[0,1,1]
	v_pk_fma_f32 v[22:23], v[154:155], v[94:95], v[22:23] op_sel_hi:[0,1,1]
	s_waitcnt lgkmcnt(2)
	v_pk_fma_f32 v[20:21], v[154:155], v[96:97], v[20:21] op_sel_hi:[0,1,1]
	v_pk_fma_f32 v[18:19], v[154:155], v[98:99], v[18:19] op_sel_hi:[0,1,1]
	s_waitcnt lgkmcnt(1)
	v_pk_fma_f32 v[14:15], v[154:155], v[100:101], v[14:15] op_sel_hi:[0,1,1]
	v_pk_fma_f32 v[12:13], v[154:155], v[102:103], v[12:13] op_sel_hi:[0,1,1]
	s_waitcnt lgkmcnt(0)
	v_pk_fma_f32 v[10:11], v[154:155], v[104:105], v[10:11] op_sel_hi:[0,1,1]
	v_pk_fma_f32 v[8:9], v[154:155], v[106:107], v[8:9] op_sel_hi:[0,1,1]
	global_load_dword v152, v[184:185], off
	v_add_co_u32_e32 v186, vcc, s6, v184
	s_nop 1
	v_addc_co_u32_e32 v187, vcc, 0, v185, vcc
	global_load_dword v154, v[186:187], off
	v_lshl_add_u64 v[184:185], v[184:185], 0, s[0:1]
	s_add_i32 s8, s5, s3
	v_mov_b32_e32 v17, s8
	ds_read_b128 v[44:47], v17
	ds_read_b128 v[48:51], v17 offset:16
	ds_read_b128 v[52:55], v17 offset:32
	ds_read_b128 v[56:59], v17 offset:48
	ds_read_b128 v[60:63], v17 offset:64
	ds_read_b128 v[64:67], v17 offset:80
	ds_read_b128 v[68:71], v17 offset:96
	ds_read_b128 v[72:75], v17 offset:112
	ds_read_b128 v[76:79], v17 offset:128
	ds_read_b128 v[80:83], v17 offset:144
	ds_read_b128 v[84:87], v17 offset:160
	ds_read_b128 v[88:91], v17 offset:176
	ds_read_b128 v[92:95], v17 offset:192
	ds_read_b128 v[96:99], v17 offset:208
	ds_read_b128 v[100:103], v17 offset:224
	ds_read_b128 v[104:107], v17 offset:240
	s_addk_i32 s3, 0x100
	v_lshl_add_u64 v[40:41], v[40:41], 0, s[0:1]
	s_waitcnt vmcnt(14) lgkmcnt(14)
	v_pk_fma_f32 v[42:43], v[156:157], v[44:45], v[42:43] op_sel_hi:[0,1,1]
	v_pk_fma_f32 v[38:39], v[156:157], v[46:47], v[38:39] op_sel_hi:[0,1,1]
	v_pk_fma_f32 v[36:37], v[156:157], v[48:49], v[36:37] op_sel_hi:[0,1,1]
	v_pk_fma_f32 v[34:35], v[156:157], v[50:51], v[34:35] op_sel_hi:[0,1,1]
	s_waitcnt lgkmcnt(13)
	v_pk_fma_f32 v[32:33], v[156:157], v[52:53], v[32:33] op_sel_hi:[0,1,1]
	v_pk_fma_f32 v[30:31], v[156:157], v[54:55], v[30:31] op_sel_hi:[0,1,1]
	s_waitcnt lgkmcnt(12)
	v_pk_fma_f32 v[28:29], v[156:157], v[56:57], v[28:29] op_sel_hi:[0,1,1]
	v_pk_fma_f32 v[26:27], v[156:157], v[58:59], v[26:27] op_sel_hi:[0,1,1]
	s_waitcnt lgkmcnt(11)
	v_pk_fma_f32 v[24:25], v[156:157], v[60:61], v[24:25] op_sel_hi:[0,1,1]
	v_pk_fma_f32 v[22:23], v[156:157], v[62:63], v[22:23] op_sel_hi:[0,1,1]
	s_waitcnt lgkmcnt(10)
	v_pk_fma_f32 v[20:21], v[156:157], v[64:65], v[20:21] op_sel_hi:[0,1,1]
	v_pk_fma_f32 v[18:19], v[156:157], v[66:67], v[18:19] op_sel_hi:[0,1,1]
	s_waitcnt lgkmcnt(9)
	v_pk_fma_f32 v[14:15], v[156:157], v[68:69], v[14:15] op_sel_hi:[0,1,1]
	v_pk_fma_f32 v[12:13], v[156:157], v[70:71], v[12:13] op_sel_hi:[0,1,1]
	s_waitcnt lgkmcnt(8)
	v_pk_fma_f32 v[10:11], v[156:157], v[72:73], v[10:11] op_sel_hi:[0,1,1]
	v_pk_fma_f32 v[8:9], v[156:157], v[74:75], v[8:9] op_sel_hi:[0,1,1]
	s_waitcnt lgkmcnt(7)
; #define LAS __attribute__((address_space(3)))
; DI void bias2_item(const float* ada, const float* w1, float* bias2, LAS float* scr, int item, int lane) {
;     ...
;     for (int k = 0; k < 128; ++k) { const float w = wp[(size_t)k * 4096];
; #pragma unroll
;         for (int b4 = 0; b4 < 8; ++b4) { const f32x4 sv = *(const LAS f32x4*)(scr + k * 32 + b4 * 4);
;             acc[4 * b4] += sv[0] * w; acc[4 * b4 + 1] += sv[1] * w; acc[4 * b4 + 2] += sv[2] * w; acc[4 * b4 + 3] += sv[3] * w; } }
	v_pk_fma_f32 v[42:43], v[158:159], v[76:77], v[42:43] op_sel_hi:[0,1,1]
	v_pk_fma_f32 v[38:39], v[158:159], v[78:79], v[38:39] op_sel_hi:[0,1,1]
	s_waitcnt lgkmcnt(6)
	v_pk_fma_f32 v[36:37], v[158:159], v[80:81], v[36:37] op_sel_hi:[0,1,1]
	v_pk_fma_f32 v[34:35], v[158:159], v[82:83], v[34:35] op_sel_hi:[0,1,1]
	s_waitcnt lgkmcnt(5)
	v_pk_fma_f32 v[32:33], v[158:159], v[84:85], v[32:33] op_sel_hi:[0,1,1]
	v_pk_fma_f32 v[30:31], v[158:159], v[86:87], v[30:31] op_sel_hi:[0,1,1]
	s_waitcnt lgkmcnt(4)
	v_pk_fma_f32 v[28:29], v[158:159], v[88:89], v[28:29] op_sel_hi:[0,1,1]
	v_pk_fma_f32 v[26:27], v[158:159], v[90:91], v[26:27] op_sel_hi:[0,1,1]
	s_waitcnt lgkmcnt(3)
	v_pk_fma_f32 v[24:25], v[158:159], v[92:93], v[24:25] op_sel_hi:[0,1,1]
	v_pk_fma_f32 v[22:23], v[158:159], v[94:95], v[22:23] op_sel_hi:[0,1,1]
	s_waitcnt lgkmcnt(2)
	v_pk_fma_f32 v[20:21], v[158:159], v[96:97], v[20:21] op_sel_hi:[0,1,1]
	v_pk_fma_f32 v[18:19], v[158:159], v[98:99], v[18:19] op_sel_hi:[0,1,1]
	s_waitcnt lgkmcnt(1)
	v_pk_fma_f32 v[14:15], v[158:159], v[100:101], v[14:15] op_sel_hi:[0,1,1]
	v_pk_fma_f32 v[12:13], v[158:159], v[102:103], v[12:13] op_sel_hi:[0,1,1]
	s_waitcnt lgkmcnt(0)
	v_pk_fma_f32 v[10:11], v[158:159], v[104:105], v[10:11] op_sel_hi:[0,1,1]
	v_pk_fma_f32 v[8:9], v[158:159], v[106:107], v[8:9] op_sel_hi:[0,1,1]
	global_load_dword v156, v[184:185], off
	v_add_co_u32_e32 v186, vcc, s6, v184
	s_nop 1
	v_addc_co_u32_e32 v187, vcc, 0, v185, vcc
	global_load_dword v158, v[186:187], off
	v_lshl_add_u64 v[184:185], v[184:185], 0, s[0:1]
	s_add_i32 s8, s5, s3
	v_mov_b32_e32 v17, s8
	ds_read_b128 v[44:47], v17
	ds_read_b128 v[48:51], v17 offset:16
	ds_read_b128 v[52:55], v17 offset:32
	ds_read_b128 v[56:59], v17 offset:48
	ds_read_b128 v[60:63], v17 offset:64
	ds_read_b128 v[64:67], v17 offset:80
	ds_read_b128 v[68:71], v17 offset:96
	ds_read_b128 v[72:75], v17 offset:112
	ds_read_b128 v[76:79], v17 offset:128
	ds_read_b128 v[80:83], v17 offset:144
	ds_read_b128 v[84:87], v17 offset:160
	ds_read_b128 v[88:91], v17 offset:176
	ds_read_b128 v[92:95], v17 offset:192
	ds_read_b128 v[96:99], v17 offset:208
	ds_read_b128 v[100:103], v17 offset:224
	ds_read_b128 v[104:107], v17 offset:240
	s_addk_i32 s3, 0x100
	v_lshl_add_u64 v[40:41], v[40:41], 0, s[0:1]
	s_waitcnt vmcnt(14) lgkmcnt(14)
	v_pk_fma_f32 v[42:43], v[160:161], v[44:45], v[42:43] op_sel_hi:[0,1,1]
	v_pk_fma_f32 v[38:39], v[160:161], v[46:47], v[38:39] op_sel_hi:[0,1,1]
	v_pk_fma_f32 v[36:37], v[160:161], v[48:49], v[36:37] op_sel_hi:[0,1,1]
	v_pk_fma_f32 v[34:35], v[160:161], v[50:51], v[34:35] op_sel_hi:[0,1,1]
	s_waitcnt lgkmcnt(13)
	v_pk_fma_f32 v[32:33], v[160:161], v[52:53], v[32:33] op_sel_hi:[0,1,1]
	v_pk_fma_f32 v[30:31], v[160:161], v[54:55], v[30:31] op_sel_hi:[0,1,1]
	s_waitcnt lgkmcnt(12)
	v_pk_fma_f32 v[28:29], v[160:161], v[56:57], v[28:29] op_sel_hi:[0,1,1]
	v_pk_fma_f32 v[26:27], v[160:161], v[58:59], v[26:27] op_sel_hi:[0,1,1]
	s_waitcnt lgkmcnt(11)
	v_pk_fma_f32 v[24:25], v[160:161], v[60:61], v[24:25] op_sel_hi:[0,1,1]
	v_pk_fma_f32 v[22:23], v[160:161], v[62:63], v[22:23] op_sel_hi:[0,1,1]
	s_waitcnt lgkmcnt(10)
	v_pk_fma_f32 v[20:21], v[160:161], v[64:65], v[20:21] op_sel_hi:[0,1,1]
	v_pk_fma_f32 v[18:19], v[160:161], v[66:67], v[18:19] op_sel_hi:[0,1,1]
	s_waitcnt lgkmcnt(9)
	v_pk_fma_f32 v[14:15], v[160:161], v[68:69], v[14:15] op_sel_hi:[0,1,1]
	v_pk_fma_f32 v[12:13], v[160:161], v[70:71], v[12:13] op_sel_hi:[0,1,1]
	s_waitcnt lgkmcnt(8)
	v_pk_fma_f32 v[10:11], v[160:161], v[72:73], v[10:11] op_sel_hi:[0,1,1]
	v_pk_fma_f32 v[8:9], v[160:161], v[74:75], v[8:9] op_sel_hi:[0,1,1]
	s_waitcnt lgkmcnt(7)
	v_pk_fma_f32 v[42:43], v[162:163], v[76:77], v[42:43] op_sel_hi:[0,1,1]
	v_pk_fma_f32 v[38:39], v[162:163], v[78:79], v[38:39] op_sel_hi:[0,1,1]
	s_waitcnt lgkmcnt(6)
	v_pk_fma_f32 v[36:37], v[162:163], v[80:81], v[36:37] op_sel_hi:[0,1,1]
	v_pk_fma_f32 v[34:35], v[162:163], v[82:83], v[34:35] op_sel_hi:[0,1,1]
	s_waitcnt lgkmcnt(5)
	v_pk_fma_f32 v[32:33], v[162:163], v[84:85], v[32:33] op_sel_hi:[0,1,1]
	v_pk_fma_f32 v[30:31], v[162:163], v[86:87], v[30:31] op_sel_hi:[0,1,1]
	s_waitcnt lgkmcnt(4)
	v_pk_fma_f32 v[28:29], v[162:163], v[88:89], v[28:29] op_sel_hi:[0,1,1]
	v_pk_fma_f32 v[26:27], v[162:163], v[90:91], v[26:27] op_sel_hi:[0,1,1]
	s_waitcnt lgkmcnt(3)
	v_pk_fma_f32 v[24:25], v[162:163], v[92:93], v[24:25] op_sel_hi:[0,1,1]
	v_pk_fma_f32 v[22:23], v[162:163], v[94:95], v[22:23] op_sel_hi:[0,1,1]
	s_waitcnt lgkmcnt(2)
	v_pk_fma_f32 v[20:21], v[162:163], v[96:97], v[20:21] op_sel_hi:[0,1,1]
	v_pk_fma_f32 v[18:19], v[162:163], v[98:99], v[18:19] op_sel_hi:[0,1,1]
	s_waitcnt lgkmcnt(1)
	v_pk_fma_f32 v[14:15], v[162:163], v[100:101], v[14:15] op_sel_hi:[0,1,1]
	v_pk_fma_f32 v[12:13], v[162:163], v[102:103], v[12:13] op_sel_hi:[0,1,1]
	s_waitcnt lgkmcnt(0)
	v_pk_fma_f32 v[10:11], v[162:163], v[104:105], v[10:11] op_sel_hi:[0,1,1]
	v_pk_fma_f32 v[8:9], v[162:163], v[106:107], v[8:9] op_sel_hi:[0,1,1]
	global_load_dword v160, v[184:185], off
	v_add_co_u32_e32 v186, vcc, s6, v184
	s_nop 1
	v_addc_co_u32_e32 v187, vcc, 0, v185, vcc
	global_load_dword v162, v[186:187], off
	v_lshl_add_u64 v[184:185], v[184:185], 0, s[0:1]
	s_add_i32 s8, s5, s3
	v_mov_b32_e32 v17, s8
	ds_read_b128 v[44:47], v17
	ds_read_b128 v[48:51], v17 offset:16
	ds_read_b128 v[52:55], v17 offset:32
	ds_read_b128 v[56:59], v17 offset:48
	ds_read_b128 v[60:63], v17 offset:64
	ds_read_b128 v[64:67], v17 offset:80
	ds_read_b128 v[68:71], v17 offset:96
	ds_read_b128 v[72:75], v17 offset:112
	ds_read_b128 v[76:79], v17 offset:128
	ds_read_b128 v[80:83], v17 offset:144
	ds_read_b128 v[84:87], v17 offset:160
	ds_read_b128 v[88:91], v17 offset:176
	ds_read_b128 v[92:95], v17 offset:192
	ds_read_b128 v[96:99], v17 offset:208
	ds_read_b128 v[100:103], v17 offset:224
	ds_read_b128 v[104:107], v17 offset:240
	s_addk_i32 s3, 0x100
	v_lshl_add_u64 v[40:41], v[40:41], 0, s[0:1]
	s_waitcnt vmcnt(14) lgkmcnt(14)
; #define LAS __attribute__((address_space(3)))
; DI void bias2_item(const float* ada, const float* w1, float* bias2, LAS float* scr, int item, int lane) {
;     ...
;     for (int k = 0; k < 128; ++k) { const float w = wp[(size_t)k * 4096];
; #pragma unroll
;         for (int b4 = 0; b4 < 8; ++b4) { const f32x4 sv = *(const LAS f32x4*)(scr + k * 32 + b4 * 4);
;             acc[4 * b4] += sv[0] * w; acc[4 * b4 + 1] += sv[1] * w; acc[4 * b4 + 2] += sv[2] * w; acc[4 * b4 + 3] += sv[3] * w; } }
	v_pk_fma_f32 v[42:43], v[164:165], v[44:45], v[42:43] op_sel_hi:[0,1,1]
	v_pk_fma_f32 v[38:39], v[164:165], v[46:47], v[38:39] op_sel_hi:[0,1,1]
	v_pk_fma_f32 v[36:37], v[164:165], v[48:49], v[36:37] op_sel_hi:[0,1,1]
	v_pk_fma_f32 v[34:35], v[164:165], v[50:51], v[34:35] op_sel_hi:[0,1,1]
	s_waitcnt lgkmcnt(13)
	v_pk_fma_f32 v[32:33], v[164:165], v[52:53], v[32:33] op_sel_hi:[0,1,1]
	v_pk_fma_f32 v[30:31], v[164:165], v[54:55], v[30:31] op_sel_hi:[0,1,1]
	s_waitcnt lgkmcnt(12)
	v_pk_fma_f32 v[28:29], v[164:165], v[56:57], v[28:29] op_sel_hi:[0,1,1]
	v_pk_fma_f32 v[26:27], v[164:165], v[58:59], v[26:27] op_sel_hi:[0,1,1]
	s_waitcnt lgkmcnt(11)
	v_pk_fma_f32 v[24:25], v[164:165], v[60:61], v[24:25] op_sel_hi:[0,1,1]
	v_pk_fma_f32 v[22:23], v[164:165], v[62:63], v[22:23] op_sel_hi:[0,1,1]
	s_waitcnt lgkmcnt(10)
	v_pk_fma_f32 v[20:21], v[164:165], v[64:65], v[20:21] op_sel_hi:[0,1,1]
	v_pk_fma_f32 v[18:19], v[164:165], v[66:67], v[18:19] op_sel_hi:[0,1,1]
	s_waitcnt lgkmcnt(9)
	v_pk_fma_f32 v[14:15], v[164:165], v[68:69], v[14:15] op_sel_hi:[0,1,1]
	v_pk_fma_f32 v[12:13], v[164:165], v[70:71], v[12:13] op_sel_hi:[0,1,1]
	s_waitcnt lgkmcnt(8)
	v_pk_fma_f32 v[10:11], v[164:165], v[72:73], v[10:11] op_sel_hi:[0,1,1]
	v_pk_fma_f32 v[8:9], v[164:165], v[74:75], v[8:9] op_sel_hi:[0,1,1]
	s_waitcnt lgkmcnt(7)
	v_pk_fma_f32 v[42:43], v[166:167], v[76:77], v[42:43] op_sel_hi:[0,1,1]
	v_pk_fma_f32 v[38:39], v[166:167], v[78:79], v[38:39] op_sel_hi:[0,1,1]
	s_waitcnt lgkmcnt(6)
	v_pk_fma_f32 v[36:37], v[166:167], v[80:81], v[36:37] op_sel_hi:[0,1,1]
	v_pk_fma_f32 v[34:35], v[166:167], v[82:83], v[34:35] op_sel_hi:[0,1,1]
	s_waitcnt lgkmcnt(5)
	v_pk_fma_f32 v[32:33], v[166:167], v[84:85], v[32:33] op_sel_hi:[0,1,1]
	v_pk_fma_f32 v[30:31], v[166:167], v[86:87], v[30:31] op_sel_hi:[0,1,1]
	s_waitcnt lgkmcnt(4)
	v_pk_fma_f32 v[28:29], v[166:167], v[88:89], v[28:29] op_sel_hi:[0,1,1]
	v_pk_fma_f32 v[26:27], v[166:167], v[90:91], v[26:27] op_sel_hi:[0,1,1]
	s_waitcnt lgkmcnt(3)
	v_pk_fma_f32 v[24:25], v[166:167], v[92:93], v[24:25] op_sel_hi:[0,1,1]
	v_pk_fma_f32 v[22:23], v[166:167], v[94:95], v[22:23] op_sel_hi:[0,1,1]
	s_waitcnt lgkmcnt(2)
	v_pk_fma_f32 v[20:21], v[166:167], v[96:97], v[20:21] op_sel_hi:[0,1,1]
	v_pk_fma_f32 v[18:19], v[166:167], v[98:99], v[18:19] op_sel_hi:[0,1,1]
	s_waitcnt lgkmcnt(1)
	v_pk_fma_f32 v[14:15], v[166:167], v[100:101], v[14:15] op_sel_hi:[0,1,1]
	v_pk_fma_f32 v[12:13], v[166:167], v[102:103], v[12:13] op_sel_hi:[0,1,1]
	s_waitcnt lgkmcnt(0)
	v_pk_fma_f32 v[10:11], v[166:167], v[104:105], v[10:11] op_sel_hi:[0,1,1]
	v_pk_fma_f32 v[8:9], v[166:167], v[106:107], v[8:9] op_sel_hi:[0,1,1]
	global_load_dword v164, v[184:185], off
	v_add_co_u32_e32 v186, vcc, s6, v184
	s_nop 1
	v_addc_co_u32_e32 v187, vcc, 0, v185, vcc
	global_load_dword v166, v[186:187], off
	v_lshl_add_u64 v[184:185], v[184:185], 0, s[0:1]
	s_add_i32 s8, s5, s3
	v_mov_b32_e32 v17, s8
	ds_read_b128 v[44:47], v17
	ds_read_b128 v[48:51], v17 offset:16
	ds_read_b128 v[52:55], v17 offset:32
	ds_read_b128 v[56:59], v17 offset:48
	ds_read_b128 v[60:63], v17 offset:64
	ds_read_b128 v[64:67], v17 offset:80
	ds_read_b128 v[68:71], v17 offset:96
	ds_read_b128 v[72:75], v17 offset:112
	ds_read_b128 v[76:79], v17 offset:128
	ds_read_b128 v[80:83], v17 offset:144
	ds_read_b128 v[84:87], v17 offset:160
	ds_read_b128 v[88:91], v17 offset:176
	ds_read_b128 v[92:95], v17 offset:192
	ds_read_b128 v[96:99], v17 offset:208
	ds_read_b128 v[100:103], v17 offset:224
	ds_read_b128 v[104:107], v17 offset:240
	s_addk_i32 s3, 0x100
	v_lshl_add_u64 v[40:41], v[40:41], 0, s[0:1]
	s_waitcnt vmcnt(14) lgkmcnt(14)
	v_pk_fma_f32 v[42:43], v[168:169], v[44:45], v[42:43] op_sel_hi:[0,1,1]
	v_pk_fma_f32 v[38:39], v[168:169], v[46:47], v[38:39] op_sel_hi:[0,1,1]
	v_pk_fma_f32 v[36:37], v[168:169], v[48:49], v[36:37] op_sel_hi:[0,1,1]
	v_pk_fma_f32 v[34:35], v[168:169], v[50:51], v[34:35] op_sel_hi:[0,1,1]
	s_waitcnt lgkmcnt(13)
	v_pk_fma_f32 v[32:33], v[168:169], v[52:53], v[32:33] op_sel_hi:[0,1,1]
	v_pk_fma_f32 v[30:31], v[168:169], v[54:55], v[30:31] op_sel_hi:[0,1,1]
	s_waitcnt lgkmcnt(12)
	v_pk_fma_f32 v[28:29], v[168:169], v[56:57], v[28:29] op_sel_hi:[0,1,1]
	v_pk_fma_f32 v[26:27], v[168:169], v[58:59], v[26:27] op_sel_hi:[0,1,1]
	s_waitcnt lgkmcnt(11)
	v_pk_fma_f32 v[24:25], v[168:169], v[60:61], v[24:25] op_sel_hi:[0,1,1]
	v_pk_fma_f32 v[22:23], v[168:169], v[62:63], v[22:23] op_sel_hi:[0,1,1]
	s_waitcnt lgkmcnt(10)
	v_pk_fma_f32 v[20:21], v[168:169], v[64:65], v[20:21] op_sel_hi:[0,1,1]
	v_pk_fma_f32 v[18:19], v[168:169], v[66:67], v[18:19] op_sel_hi:[0,1,1]
	s_waitcnt lgkmcnt(9)
	v_pk_fma_f32 v[14:15], v[168:169], v[68:69], v[14:15] op_sel_hi:[0,1,1]
	v_pk_fma_f32 v[12:13], v[168:169], v[70:71], v[12:13] op_sel_hi:[0,1,1]
	s_waitcnt lgkmcnt(8)
	v_pk_fma_f32 v[10:11], v[168:169], v[72:73], v[10:11] op_sel_hi:[0,1,1]
	v_pk_fma_f32 v[8:9], v[168:169], v[74:75], v[8:9] op_sel_hi:[0,1,1]
	s_waitcnt lgkmcnt(7)
	v_pk_fma_f32 v[42:43], v[170:171], v[76:77], v[42:43] op_sel_hi:[0,1,1]
	v_pk_fma_f32 v[38:39], v[170:171], v[78:79], v[38:39] op_sel_hi:[0,1,1]
	s_waitcnt lgkmcnt(6)
	v_pk_fma_f32 v[36:37], v[170:171], v[80:81], v[36:37] op_sel_hi:[0,1,1]
	v_pk_fma_f32 v[34:35], v[170:171], v[82:83], v[34:35] op_sel_hi:[0,1,1]
	s_waitcnt lgkmcnt(5)
	v_pk_fma_f32 v[32:33], v[170:171], v[84:85], v[32:33] op_sel_hi:[0,1,1]
	v_pk_fma_f32 v[30:31], v[170:171], v[86:87], v[30:31] op_sel_hi:[0,1,1]
	s_waitcnt lgkmcnt(4)
	v_pk_fma_f32 v[28:29], v[170:171], v[88:89], v[28:29] op_sel_hi:[0,1,1]
	v_pk_fma_f32 v[26:27], v[170:171], v[90:91], v[26:27] op_sel_hi:[0,1,1]
	s_waitcnt lgkmcnt(3)
; #define LAS __attribute__((address_space(3)))
; DI void bias2_item(const float* ada, const float* w1, float* bias2, LAS float* scr, int item, int lane) {
;     ...
;     for (int k = 0; k < 128; ++k) { const float w = wp[(size_t)k * 4096];
; #pragma unroll
;         for (int b4 = 0; b4 < 8; ++b4) { const f32x4 sv = *(const LAS f32x4*)(scr + k * 32 + b4 * 4);
;             acc[4 * b4] += sv[0] * w; acc[4 * b4 + 1] += sv[1] * w; acc[4 * b4 + 2] += sv[2] * w; acc[4 * b4 + 3] += sv[3] * w; } }
	v_pk_fma_f32 v[24:25], v[170:171], v[92:93], v[24:25] op_sel_hi:[0,1,1]
	v_pk_fma_f32 v[22:23], v[170:171], v[94:95], v[22:23] op_sel_hi:[0,1,1]
	s_waitcnt lgkmcnt(2)
	v_pk_fma_f32 v[20:21], v[170:171], v[96:97], v[20:21] op_sel_hi:[0,1,1]
	v_pk_fma_f32 v[18:19], v[170:171], v[98:99], v[18:19] op_sel_hi:[0,1,1]
	s_waitcnt lgkmcnt(1)
	v_pk_fma_f32 v[14:15], v[170:171], v[100:101], v[14:15] op_sel_hi:[0,1,1]
	v_pk_fma_f32 v[12:13], v[170:171], v[102:103], v[12:13] op_sel_hi:[0,1,1]
	s_waitcnt lgkmcnt(0)
	v_pk_fma_f32 v[10:11], v[170:171], v[104:105], v[10:11] op_sel_hi:[0,1,1]
	v_pk_fma_f32 v[8:9], v[170:171], v[106:107], v[8:9] op_sel_hi:[0,1,1]
	global_load_dword v168, v[184:185], off
	v_add_co_u32_e32 v186, vcc, s6, v184
	s_nop 1
	v_addc_co_u32_e32 v187, vcc, 0, v185, vcc
	global_load_dword v170, v[186:187], off
	v_lshl_add_u64 v[184:185], v[184:185], 0, s[0:1]
	s_add_i32 s8, s5, s3
	v_mov_b32_e32 v17, s8
	ds_read_b128 v[44:47], v17
	ds_read_b128 v[48:51], v17 offset:16
	ds_read_b128 v[52:55], v17 offset:32
	ds_read_b128 v[56:59], v17 offset:48
	ds_read_b128 v[60:63], v17 offset:64
	ds_read_b128 v[64:67], v17 offset:80
	ds_read_b128 v[68:71], v17 offset:96
	ds_read_b128 v[72:75], v17 offset:112
	ds_read_b128 v[76:79], v17 offset:128
	ds_read_b128 v[80:83], v17 offset:144
	ds_read_b128 v[84:87], v17 offset:160
	ds_read_b128 v[88:91], v17 offset:176
	ds_read_b128 v[92:95], v17 offset:192
	ds_read_b128 v[96:99], v17 offset:208
	ds_read_b128 v[100:103], v17 offset:224
	ds_read_b128 v[104:107], v17 offset:240
	s_addk_i32 s3, 0x100
	v_lshl_add_u64 v[40:41], v[40:41], 0, s[0:1]
	s_waitcnt vmcnt(14) lgkmcnt(14)
	v_pk_fma_f32 v[42:43], v[172:173], v[44:45], v[42:43] op_sel_hi:[0,1,1]
	v_pk_fma_f32 v[38:39], v[172:173], v[46:47], v[38:39] op_sel_hi:[0,1,1]
	v_pk_fma_f32 v[36:37], v[172:173], v[48:49], v[36:37] op_sel_hi:[0,1,1]
	v_pk_fma_f32 v[34:35], v[172:173], v[50:51], v[34:35] op_sel_hi:[0,1,1]
	s_waitcnt lgkmcnt(13)
	v_pk_fma_f32 v[32:33], v[172:173], v[52:53], v[32:33] op_sel_hi:[0,1,1]
	v_pk_fma_f32 v[30:31], v[172:173], v[54:55], v[30:31] op_sel_hi:[0,1,1]
	s_waitcnt lgkmcnt(12)
	v_pk_fma_f32 v[28:29], v[172:173], v[56:57], v[28:29] op_sel_hi:[0,1,1]
	v_pk_fma_f32 v[26:27], v[172:173], v[58:59], v[26:27] op_sel_hi:[0,1,1]
	s_waitcnt lgkmcnt(11)
	v_pk_fma_f32 v[24:25], v[172:173], v[60:61], v[24:25] op_sel_hi:[0,1,1]
	v_pk_fma_f32 v[22:23], v[172:173], v[62:63], v[22:23] op_sel_hi:[0,1,1]
	s_waitcnt lgkmcnt(10)
	v_pk_fma_f32 v[20:21], v[172:173], v[64:65], v[20:21] op_sel_hi:[0,1,1]
	v_pk_fma_f32 v[18:19], v[172:173], v[66:67], v[18:19] op_sel_hi:[0,1,1]
	s_waitcnt lgkmcnt(9)
	v_pk_fma_f32 v[14:15], v[172:173], v[68:69], v[14:15] op_sel_hi:[0,1,1]
	v_pk_fma_f32 v[12:13], v[172:173], v[70:71], v[12:13] op_sel_hi:[0,1,1]
	s_waitcnt lgkmcnt(8)
	v_pk_fma_f32 v[10:11], v[172:173], v[72:73], v[10:11] op_sel_hi:[0,1,1]
	v_pk_fma_f32 v[8:9], v[172:173], v[74:75], v[8:9] op_sel_hi:[0,1,1]
	s_waitcnt lgkmcnt(7)
	v_pk_fma_f32 v[42:43], v[174:175], v[76:77], v[42:43] op_sel_hi:[0,1,1]
	v_pk_fma_f32 v[38:39], v[174:175], v[78:79], v[38:39] op_sel_hi:[0,1,1]
	s_waitcnt lgkmcnt(6)
	v_pk_fma_f32 v[36:37], v[174:175], v[80:81], v[36:37] op_sel_hi:[0,1,1]
	v_pk_fma_f32 v[34:35], v[174:175], v[82:83], v[34:35] op_sel_hi:[0,1,1]
	s_waitcnt lgkmcnt(5)
	v_pk_fma_f32 v[32:33], v[174:175], v[84:85], v[32:33] op_sel_hi:[0,1,1]
	v_pk_fma_f32 v[30:31], v[174:175], v[86:87], v[30:31] op_sel_hi:[0,1,1]
	s_waitcnt lgkmcnt(4)
	v_pk_fma_f32 v[28:29], v[174:175], v[88:89], v[28:29] op_sel_hi:[0,1,1]
	v_pk_fma_f32 v[26:27], v[174:175], v[90:91], v[26:27] op_sel_hi:[0,1,1]
	s_waitcnt lgkmcnt(3)
	v_pk_fma_f32 v[24:25], v[174:175], v[92:93], v[24:25] op_sel_hi:[0,1,1]
	v_pk_fma_f32 v[22:23], v[174:175], v[94:95], v[22:23] op_sel_hi:[0,1,1]
	s_waitcnt lgkmcnt(2)
	v_pk_fma_f32 v[20:21], v[174:175], v[96:97], v[20:21] op_sel_hi:[0,1,1]
	v_pk_fma_f32 v[18:19], v[174:175], v[98:99], v[18:19] op_sel_hi:[0,1,1]
	s_waitcnt lgkmcnt(1)
	v_pk_fma_f32 v[14:15], v[174:175], v[100:101], v[14:15] op_sel_hi:[0,1,1]
	v_pk_fma_f32 v[12:13], v[174:175], v[102:103], v[12:13] op_sel_hi:[0,1,1]
	s_waitcnt lgkmcnt(0)
	v_pk_fma_f32 v[10:11], v[174:175], v[104:105], v[10:11] op_sel_hi:[0,1,1]
	v_pk_fma_f32 v[8:9], v[174:175], v[106:107], v[8:9] op_sel_hi:[0,1,1]
	global_load_dword v172, v[184:185], off
	v_add_co_u32_e32 v186, vcc, s6, v184
	s_nop 1
	v_addc_co_u32_e32 v187, vcc, 0, v185, vcc
	global_load_dword v174, v[186:187], off
	v_lshl_add_u64 v[184:185], v[184:185], 0, s[0:1]
	s_add_i32 s8, s5, s3
	v_mov_b32_e32 v17, s8
	ds_read_b128 v[44:47], v17
	ds_read_b128 v[48:51], v17 offset:16
	ds_read_b128 v[52:55], v17 offset:32
	ds_read_b128 v[56:59], v17 offset:48
	ds_read_b128 v[60:63], v17 offset:64
	ds_read_b128 v[64:67], v17 offset:80
	ds_read_b128 v[68:71], v17 offset:96
	ds_read_b128 v[72:75], v17 offset:112
	ds_read_b128 v[76:79], v17 offset:128
	ds_read_b128 v[80:83], v17 offset:144
	ds_read_b128 v[84:87], v17 offset:160
	ds_read_b128 v[88:91], v17 offset:176
	ds_read_b128 v[92:95], v17 offset:192
	ds_read_b128 v[96:99], v17 offset:208
	ds_read_b128 v[100:103], v17 offset:224
	ds_read_b128 v[104:107], v17 offset:240
	s_addk_i32 s3, 0x100
	v_lshl_add_u64 v[40:41], v[40:41], 0, s[0:1]
	s_waitcnt vmcnt(14) lgkmcnt(14)
	v_pk_fma_f32 v[42:43], v[176:177], v[44:45], v[42:43] op_sel_hi:[0,1,1]
	v_pk_fma_f32 v[38:39], v[176:177], v[46:47], v[38:39] op_sel_hi:[0,1,1]
	v_pk_fma_f32 v[36:37], v[176:177], v[48:49], v[36:37] op_sel_hi:[0,1,1]
	v_pk_fma_f32 v[34:35], v[176:177], v[50:51], v[34:35] op_sel_hi:[0,1,1]
	s_waitcnt lgkmcnt(13)
; #define LAS __attribute__((address_space(3)))
; DI void bias2_item(const float* ada, const float* w1, float* bias2, LAS float* scr, int item, int lane) {
;     ...
;     for (int k = 0; k < 128; ++k) { const float w = wp[(size_t)k * 4096];
; #pragma unroll
;         for (int b4 = 0; b4 < 8; ++b4) { const f32x4 sv = *(const LAS f32x4*)(scr + k * 32 + b4 * 4);
;             acc[4 * b4] += sv[0] * w; acc[4 * b4 + 1] += sv[1] * w; acc[4 * b4 + 2] += sv[2] * w; acc[4 * b4 + 3] += sv[3] * w; } }
	v_pk_fma_f32 v[32:33], v[176:177], v[52:53], v[32:33] op_sel_hi:[0,1,1]
	v_pk_fma_f32 v[30:31], v[176:177], v[54:55], v[30:31] op_sel_hi:[0,1,1]
	s_waitcnt lgkmcnt(12)
	v_pk_fma_f32 v[28:29], v[176:177], v[56:57], v[28:29] op_sel_hi:[0,1,1]
	v_pk_fma_f32 v[26:27], v[176:177], v[58:59], v[26:27] op_sel_hi:[0,1,1]
	s_waitcnt lgkmcnt(11)
	v_pk_fma_f32 v[24:25], v[176:177], v[60:61], v[24:25] op_sel_hi:[0,1,1]
	v_pk_fma_f32 v[22:23], v[176:177], v[62:63], v[22:23] op_sel_hi:[0,1,1]
	s_waitcnt lgkmcnt(10)
	v_pk_fma_f32 v[20:21], v[176:177], v[64:65], v[20:21] op_sel_hi:[0,1,1]
	v_pk_fma_f32 v[18:19], v[176:177], v[66:67], v[18:19] op_sel_hi:[0,1,1]
	s_waitcnt lgkmcnt(9)
	v_pk_fma_f32 v[14:15], v[176:177], v[68:69], v[14:15] op_sel_hi:[0,1,1]
	v_pk_fma_f32 v[12:13], v[176:177], v[70:71], v[12:13] op_sel_hi:[0,1,1]
	s_waitcnt lgkmcnt(8)
	v_pk_fma_f32 v[10:11], v[176:177], v[72:73], v[10:11] op_sel_hi:[0,1,1]
	v_pk_fma_f32 v[8:9], v[176:177], v[74:75], v[8:9] op_sel_hi:[0,1,1]
	s_waitcnt lgkmcnt(7)
	v_pk_fma_f32 v[42:43], v[178:179], v[76:77], v[42:43] op_sel_hi:[0,1,1]
	v_pk_fma_f32 v[38:39], v[178:179], v[78:79], v[38:39] op_sel_hi:[0,1,1]
	s_waitcnt lgkmcnt(6)
	v_pk_fma_f32 v[36:37], v[178:179], v[80:81], v[36:37] op_sel_hi:[0,1,1]
	v_pk_fma_f32 v[34:35], v[178:179], v[82:83], v[34:35] op_sel_hi:[0,1,1]
	s_waitcnt lgkmcnt(5)
	v_pk_fma_f32 v[32:33], v[178:179], v[84:85], v[32:33] op_sel_hi:[0,1,1]
	v_pk_fma_f32 v[30:31], v[178:179], v[86:87], v[30:31] op_sel_hi:[0,1,1]
	s_waitcnt lgkmcnt(4)
	v_pk_fma_f32 v[28:29], v[178:179], v[88:89], v[28:29] op_sel_hi:[0,1,1]
	v_pk_fma_f32 v[26:27], v[178:179], v[90:91], v[26:27] op_sel_hi:[0,1,1]
	s_waitcnt lgkmcnt(3)
	v_pk_fma_f32 v[24:25], v[178:179], v[92:93], v[24:25] op_sel_hi:[0,1,1]
	v_pk_fma_f32 v[22:23], v[178:179], v[94:95], v[22:23] op_sel_hi:[0,1,1]
	s_waitcnt lgkmcnt(2)
	v_pk_fma_f32 v[20:21], v[178:179], v[96:97], v[20:21] op_sel_hi:[0,1,1]
	v_pk_fma_f32 v[18:19], v[178:179], v[98:99], v[18:19] op_sel_hi:[0,1,1]
	s_waitcnt lgkmcnt(1)
	v_pk_fma_f32 v[14:15], v[178:179], v[100:101], v[14:15] op_sel_hi:[0,1,1]
	v_pk_fma_f32 v[12:13], v[178:179], v[102:103], v[12:13] op_sel_hi:[0,1,1]
	s_waitcnt lgkmcnt(0)
	v_pk_fma_f32 v[10:11], v[178:179], v[104:105], v[10:11] op_sel_hi:[0,1,1]
	v_pk_fma_f32 v[8:9], v[178:179], v[106:107], v[8:9] op_sel_hi:[0,1,1]
	global_load_dword v176, v[184:185], off
	v_add_co_u32_e32 v186, vcc, s6, v184
	s_nop 1
	v_addc_co_u32_e32 v187, vcc, 0, v185, vcc
	global_load_dword v178, v[186:187], off
	v_lshl_add_u64 v[184:185], v[184:185], 0, s[0:1]
	s_add_i32 s8, s5, s3
	v_mov_b32_e32 v17, s8
	ds_read_b128 v[44:47], v17
	ds_read_b128 v[48:51], v17 offset:16
	ds_read_b128 v[52:55], v17 offset:32
	ds_read_b128 v[56:59], v17 offset:48
	ds_read_b128 v[60:63], v17 offset:64
	ds_read_b128 v[64:67], v17 offset:80
	ds_read_b128 v[68:71], v17 offset:96
	ds_read_b128 v[72:75], v17 offset:112
	ds_read_b128 v[76:79], v17 offset:128
	ds_read_b128 v[80:83], v17 offset:144
	ds_read_b128 v[84:87], v17 offset:160
	ds_read_b128 v[88:91], v17 offset:176
	ds_read_b128 v[92:95], v17 offset:192
	ds_read_b128 v[96:99], v17 offset:208
	ds_read_b128 v[100:103], v17 offset:224
	ds_read_b128 v[104:107], v17 offset:240
	s_addk_i32 s3, 0x100
	v_lshl_add_u64 v[40:41], v[40:41], 0, s[0:1]
	s_waitcnt vmcnt(14) lgkmcnt(14)
	v_pk_fma_f32 v[42:43], v[180:181], v[44:45], v[42:43] op_sel_hi:[0,1,1]
	v_pk_fma_f32 v[38:39], v[180:181], v[46:47], v[38:39] op_sel_hi:[0,1,1]
	v_pk_fma_f32 v[36:37], v[180:181], v[48:49], v[36:37] op_sel_hi:[0,1,1]
	v_pk_fma_f32 v[34:35], v[180:181], v[50:51], v[34:35] op_sel_hi:[0,1,1]
	s_waitcnt lgkmcnt(13)
	v_pk_fma_f32 v[32:33], v[180:181], v[52:53], v[32:33] op_sel_hi:[0,1,1]
	v_pk_fma_f32 v[30:31], v[180:181], v[54:55], v[30:31] op_sel_hi:[0,1,1]
	s_waitcnt lgkmcnt(12)
	v_pk_fma_f32 v[28:29], v[180:181], v[56:57], v[28:29] op_sel_hi:[0,1,1]
	v_pk_fma_f32 v[26:27], v[180:181], v[58:59], v[26:27] op_sel_hi:[0,1,1]
	s_waitcnt lgkmcnt(11)
	v_pk_fma_f32 v[24:25], v[180:181], v[60:61], v[24:25] op_sel_hi:[0,1,1]
	v_pk_fma_f32 v[22:23], v[180:181], v[62:63], v[22:23] op_sel_hi:[0,1,1]
	s_waitcnt lgkmcnt(10)
	v_pk_fma_f32 v[20:21], v[180:181], v[64:65], v[20:21] op_sel_hi:[0,1,1]
	v_pk_fma_f32 v[18:19], v[180:181], v[66:67], v[18:19] op_sel_hi:[0,1,1]
	s_waitcnt lgkmcnt(9)
	v_pk_fma_f32 v[14:15], v[180:181], v[68:69], v[14:15] op_sel_hi:[0,1,1]
	v_pk_fma_f32 v[12:13], v[180:181], v[70:71], v[12:13] op_sel_hi:[0,1,1]
	s_waitcnt lgkmcnt(8)
	v_pk_fma_f32 v[10:11], v[180:181], v[72:73], v[10:11] op_sel_hi:[0,1,1]
	v_pk_fma_f32 v[8:9], v[180:181], v[74:75], v[8:9] op_sel_hi:[0,1,1]
	s_waitcnt lgkmcnt(7)
	v_pk_fma_f32 v[42:43], v[182:183], v[76:77], v[42:43] op_sel_hi:[0,1,1]
	v_pk_fma_f32 v[38:39], v[182:183], v[78:79], v[38:39] op_sel_hi:[0,1,1]
	s_waitcnt lgkmcnt(6)
	v_pk_fma_f32 v[36:37], v[182:183], v[80:81], v[36:37] op_sel_hi:[0,1,1]
	v_pk_fma_f32 v[34:35], v[182:183], v[82:83], v[34:35] op_sel_hi:[0,1,1]
	s_waitcnt lgkmcnt(5)
	v_pk_fma_f32 v[32:33], v[182:183], v[84:85], v[32:33] op_sel_hi:[0,1,1]
	v_pk_fma_f32 v[30:31], v[182:183], v[86:87], v[30:31] op_sel_hi:[0,1,1]
	s_waitcnt lgkmcnt(4)
	v_pk_fma_f32 v[28:29], v[182:183], v[88:89], v[28:29] op_sel_hi:[0,1,1]
	v_pk_fma_f32 v[26:27], v[182:183], v[90:91], v[26:27] op_sel_hi:[0,1,1]
	s_waitcnt lgkmcnt(3)
	v_pk_fma_f32 v[24:25], v[182:183], v[92:93], v[24:25] op_sel_hi:[0,1,1]
	v_pk_fma_f32 v[22:23], v[182:183], v[94:95], v[22:23] op_sel_hi:[0,1,1]
	s_waitcnt lgkmcnt(2)
	v_pk_fma_f32 v[20:21], v[182:183], v[96:97], v[20:21] op_sel_hi:[0,1,1]
	v_pk_fma_f32 v[18:19], v[182:183], v[98:99], v[18:19] op_sel_hi:[0,1,1]
	s_waitcnt lgkmcnt(1)
	v_pk_fma_f32 v[14:15], v[182:183], v[100:101], v[14:15] op_sel_hi:[0,1,1]
	v_pk_fma_f32 v[12:13], v[182:183], v[102:103], v[12:13] op_sel_hi:[0,1,1]
	s_waitcnt lgkmcnt(0)
	v_pk_fma_f32 v[10:11], v[182:183], v[104:105], v[10:11] op_sel_hi:[0,1,1]
	v_pk_fma_f32 v[8:9], v[182:183], v[106:107], v[8:9] op_sel_hi:[0,1,1]
	global_load_dword v180, v[184:185], off
	v_add_co_u32_e32 v186, vcc, s6, v184
	s_nop 1
	v_addc_co_u32_e32 v187, vcc, 0, v185, vcc
	global_load_dword v182, v[186:187], off
	v_lshl_add_u64 v[184:185], v[184:185], 0, s[0:1]
	s_cmpk_lg_i32 s3, 0x3800
	s_cbranch_scc1 .LBB0_81
; #define LAS __attribute__((address_space(3)))
; DI void bias2_item(const float* ada, const float* w1, float* bias2, LAS float* scr, int item, int lane) {
;     ...
;     for (int k = 0; k < 128; ++k) { const float w = wp[(size_t)k * 4096];
; #pragma unroll
;         for (int b4 = 0; b4 < 8; ++b4) { const f32x4 sv = *(const LAS f32x4*)(scr + k * 32 + b4 * 4);
;             acc[4 * b4] += sv[0] * w; acc[4 * b4 + 1] += sv[1] * w; acc[4 * b4 + 2] += sv[2] * w; acc[4 * b4 + 3] += sv[3] * w; } }
	s_add_i32 s8, s5, s3
	v_mov_b32_e32 v17, s8
	ds_read_b128 v[44:47], v17
	ds_read_b128 v[48:51], v17 offset:16
	ds_read_b128 v[52:55], v17 offset:32
	ds_read_b128 v[56:59], v17 offset:48
	ds_read_b128 v[60:63], v17 offset:64
	ds_read_b128 v[64:67], v17 offset:80
	ds_read_b128 v[68:71], v17 offset:96
	ds_read_b128 v[72:75], v17 offset:112
	ds_read_b128 v[76:79], v17 offset:128
	ds_read_b128 v[80:83], v17 offset:144
	ds_read_b128 v[84:87], v17 offset:160
	ds_read_b128 v[88:91], v17 offset:176
	ds_read_b128 v[92:95], v17 offset:192
	ds_read_b128 v[96:99], v17 offset:208
	ds_read_b128 v[100:103], v17 offset:224
	ds_read_b128 v[104:107], v17 offset:240
	s_addk_i32 s3, 0x100
	v_lshl_add_u64 v[40:41], v[40:41], 0, s[0:1]
	s_waitcnt vmcnt(14) lgkmcnt(14)
	v_pk_fma_f32 v[42:43], v[152:153], v[44:45], v[42:43] op_sel_hi:[0,1,1]
	v_pk_fma_f32 v[38:39], v[152:153], v[46:47], v[38:39] op_sel_hi:[0,1,1]
	v_pk_fma_f32 v[36:37], v[152:153], v[48:49], v[36:37] op_sel_hi:[0,1,1]
	v_pk_fma_f32 v[34:35], v[152:153], v[50:51], v[34:35] op_sel_hi:[0,1,1]
	s_waitcnt lgkmcnt(13)
	v_pk_fma_f32 v[32:33], v[152:153], v[52:53], v[32:33] op_sel_hi:[0,1,1]
	v_pk_fma_f32 v[30:31], v[152:153], v[54:55], v[30:31] op_sel_hi:[0,1,1]
	s_waitcnt lgkmcnt(12)
	v_pk_fma_f32 v[28:29], v[152:153], v[56:57], v[28:29] op_sel_hi:[0,1,1]
	v_pk_fma_f32 v[26:27], v[152:153], v[58:59], v[26:27] op_sel_hi:[0,1,1]
	s_waitcnt lgkmcnt(11)
	v_pk_fma_f32 v[24:25], v[152:153], v[60:61], v[24:25] op_sel_hi:[0,1,1]
	v_pk_fma_f32 v[22:23], v[152:153], v[62:63], v[22:23] op_sel_hi:[0,1,1]
	s_waitcnt lgkmcnt(10)
	v_pk_fma_f32 v[20:21], v[152:153], v[64:65], v[20:21] op_sel_hi:[0,1,1]
	v_pk_fma_f32 v[18:19], v[152:153], v[66:67], v[18:19] op_sel_hi:[0,1,1]
	s_waitcnt lgkmcnt(9)
	v_pk_fma_f32 v[14:15], v[152:153], v[68:69], v[14:15] op_sel_hi:[0,1,1]
	v_pk_fma_f32 v[12:13], v[152:153], v[70:71], v[12:13] op_sel_hi:[0,1,1]
	s_waitcnt lgkmcnt(8)
	v_pk_fma_f32 v[10:11], v[152:153], v[72:73], v[10:11] op_sel_hi:[0,1,1]
	v_pk_fma_f32 v[8:9], v[152:153], v[74:75], v[8:9] op_sel_hi:[0,1,1]
	s_waitcnt lgkmcnt(7)
	v_pk_fma_f32 v[42:43], v[154:155], v[76:77], v[42:43] op_sel_hi:[0,1,1]
	v_pk_fma_f32 v[38:39], v[154:155], v[78:79], v[38:39] op_sel_hi:[0,1,1]
	s_waitcnt lgkmcnt(6)
	v_pk_fma_f32 v[36:37], v[154:155], v[80:81], v[36:37] op_sel_hi:[0,1,1]
	v_pk_fma_f32 v[34:35], v[154:155], v[82:83], v[34:35] op_sel_hi:[0,1,1]
	s_waitcnt lgkmcnt(5)
	v_pk_fma_f32 v[32:33], v[154:155], v[84:85], v[32:33] op_sel_hi:[0,1,1]
	v_pk_fma_f32 v[30:31], v[154:155], v[86:87], v[30:31] op_sel_hi:[0,1,1]
	s_waitcnt lgkmcnt(4)
	v_pk_fma_f32 v[28:29], v[154:155], v[88:89], v[28:29] op_sel_hi:[0,1,1]
	v_pk_fma_f32 v[26:27], v[154:155], v[90:91], v[26:27] op_sel_hi:[0,1,1]
	s_waitcnt lgkmcnt(3)
	v_pk_fma_f32 v[24:25], v[154:155], v[92:93], v[24:25] op_sel_hi:[0,1,1]
	v_pk_fma_f32 v[22:23], v[154:155], v[94:95], v[22:23] op_sel_hi:[0,1,1]
	s_waitcnt lgkmcnt(2)
	v_pk_fma_f32 v[20:21], v[154:155], v[96:97], v[20:21] op_sel_hi:[0,1,1]
	v_pk_fma_f32 v[18:19], v[154:155], v[98:99], v[18:19] op_sel_hi:[0,1,1]
	s_waitcnt lgkmcnt(1)
	v_pk_fma_f32 v[14:15], v[154:155], v[100:101], v[14:15] op_sel_hi:[0,1,1]
	v_pk_fma_f32 v[12:13], v[154:155], v[102:103], v[12:13] op_sel_hi:[0,1,1]
	s_waitcnt lgkmcnt(0)
	v_pk_fma_f32 v[10:11], v[154:155], v[104:105], v[10:11] op_sel_hi:[0,1,1]
	v_pk_fma_f32 v[8:9], v[154:155], v[106:107], v[8:9] op_sel_hi:[0,1,1]
	s_add_i32 s8, s5, s3
	v_mov_b32_e32 v17, s8
	ds_read_b128 v[44:47], v17
	ds_read_b128 v[48:51], v17 offset:16
	ds_read_b128 v[52:55], v17 offset:32
	ds_read_b128 v[56:59], v17 offset:48
	ds_read_b128 v[60:63], v17 offset:64
	ds_read_b128 v[64:67], v17 offset:80
	ds_read_b128 v[68:71], v17 offset:96
	ds_read_b128 v[72:75], v17 offset:112
	ds_read_b128 v[76:79], v17 offset:128
	ds_read_b128 v[80:83], v17 offset:144
	ds_read_b128 v[84:87], v17 offset:160
	ds_read_b128 v[88:91], v17 offset:176
	ds_read_b128 v[92:95], v17 offset:192
	ds_read_b128 v[96:99], v17 offset:208
	ds_read_b128 v[100:103], v17 offset:224
	ds_read_b128 v[104:107], v17 offset:240
	s_addk_i32 s3, 0x100
	v_lshl_add_u64 v[40:41], v[40:41], 0, s[0:1]
	s_waitcnt vmcnt(12) lgkmcnt(14)
	v_pk_fma_f32 v[42:43], v[156:157], v[44:45], v[42:43] op_sel_hi:[0,1,1]
	v_pk_fma_f32 v[38:39], v[156:157], v[46:47], v[38:39] op_sel_hi:[0,1,1]
	v_pk_fma_f32 v[36:37], v[156:157], v[48:49], v[36:37] op_sel_hi:[0,1,1]
	v_pk_fma_f32 v[34:35], v[156:157], v[50:51], v[34:35] op_sel_hi:[0,1,1]
	s_waitcnt lgkmcnt(13)
	v_pk_fma_f32 v[32:33], v[156:157], v[52:53], v[32:33] op_sel_hi:[0,1,1]
	v_pk_fma_f32 v[30:31], v[156:157], v[54:55], v[30:31] op_sel_hi:[0,1,1]
	s_waitcnt lgkmcnt(12)
	v_pk_fma_f32 v[28:29], v[156:157], v[56:57], v[28:29] op_sel_hi:[0,1,1]
	v_pk_fma_f32 v[26:27], v[156:157], v[58:59], v[26:27] op_sel_hi:[0,1,1]
	s_waitcnt lgkmcnt(11)
	v_pk_fma_f32 v[24:25], v[156:157], v[60:61], v[24:25] op_sel_hi:[0,1,1]
	v_pk_fma_f32 v[22:23], v[156:157], v[62:63], v[22:23] op_sel_hi:[0,1,1]
	s_waitcnt lgkmcnt(10)
	v_pk_fma_f32 v[20:21], v[156:157], v[64:65], v[20:21] op_sel_hi:[0,1,1]
	v_pk_fma_f32 v[18:19], v[156:157], v[66:67], v[18:19] op_sel_hi:[0,1,1]
	s_waitcnt lgkmcnt(9)
	v_pk_fma_f32 v[14:15], v[156:157], v[68:69], v[14:15] op_sel_hi:[0,1,1]
	v_pk_fma_f32 v[12:13], v[156:157], v[70:71], v[12:13] op_sel_hi:[0,1,1]
	s_waitcnt lgkmcnt(8)
	v_pk_fma_f32 v[10:11], v[156:157], v[72:73], v[10:11] op_sel_hi:[0,1,1]
	v_pk_fma_f32 v[8:9], v[156:157], v[74:75], v[8:9] op_sel_hi:[0,1,1]
	s_waitcnt lgkmcnt(7)
	v_pk_fma_f32 v[42:43], v[158:159], v[76:77], v[42:43] op_sel_hi:[0,1,1]
	v_pk_fma_f32 v[38:39], v[158:159], v[78:79], v[38:39] op_sel_hi:[0,1,1]
	s_waitcnt lgkmcnt(6)
; #define LAS __attribute__((address_space(3)))
; DI void bias2_item(const float* ada, const float* w1, float* bias2, LAS float* scr, int item, int lane) {
;     ...
;     for (int k = 0; k < 128; ++k) { const float w = wp[(size_t)k * 4096];
; #pragma unroll
;         for (int b4 = 0; b4 < 8; ++b4) { const f32x4 sv = *(const LAS f32x4*)(scr + k * 32 + b4 * 4);
;             acc[4 * b4] += sv[0] * w; acc[4 * b4 + 1] += sv[1] * w; acc[4 * b4 + 2] += sv[2] * w; acc[4 * b4 + 3] += sv[3] * w; } }
	v_pk_fma_f32 v[36:37], v[158:159], v[80:81], v[36:37] op_sel_hi:[0,1,1]
	v_pk_fma_f32 v[34:35], v[158:159], v[82:83], v[34:35] op_sel_hi:[0,1,1]
	s_waitcnt lgkmcnt(5)
	v_pk_fma_f32 v[32:33], v[158:159], v[84:85], v[32:33] op_sel_hi:[0,1,1]
	v_pk_fma_f32 v[30:31], v[158:159], v[86:87], v[30:31] op_sel_hi:[0,1,1]
	s_waitcnt lgkmcnt(4)
	v_pk_fma_f32 v[28:29], v[158:159], v[88:89], v[28:29] op_sel_hi:[0,1,1]
	v_pk_fma_f32 v[26:27], v[158:159], v[90:91], v[26:27] op_sel_hi:[0,1,1]
	s_waitcnt lgkmcnt(3)
	v_pk_fma_f32 v[24:25], v[158:159], v[92:93], v[24:25] op_sel_hi:[0,1,1]
	v_pk_fma_f32 v[22:23], v[158:159], v[94:95], v[22:23] op_sel_hi:[0,1,1]
	s_waitcnt lgkmcnt(2)
	v_pk_fma_f32 v[20:21], v[158:159], v[96:97], v[20:21] op_sel_hi:[0,1,1]
	v_pk_fma_f32 v[18:19], v[158:159], v[98:99], v[18:19] op_sel_hi:[0,1,1]
	s_waitcnt lgkmcnt(1)
	v_pk_fma_f32 v[14:15], v[158:159], v[100:101], v[14:15] op_sel_hi:[0,1,1]
	v_pk_fma_f32 v[12:13], v[158:159], v[102:103], v[12:13] op_sel_hi:[0,1,1]
	s_waitcnt lgkmcnt(0)
	v_pk_fma_f32 v[10:11], v[158:159], v[104:105], v[10:11] op_sel_hi:[0,1,1]
	v_pk_fma_f32 v[8:9], v[158:159], v[106:107], v[8:9] op_sel_hi:[0,1,1]
	s_add_i32 s8, s5, s3
	v_mov_b32_e32 v17, s8
	ds_read_b128 v[44:47], v17
	ds_read_b128 v[48:51], v17 offset:16
	ds_read_b128 v[52:55], v17 offset:32
	ds_read_b128 v[56:59], v17 offset:48
	ds_read_b128 v[60:63], v17 offset:64
	ds_read_b128 v[64:67], v17 offset:80
	ds_read_b128 v[68:71], v17 offset:96
	ds_read_b128 v[72:75], v17 offset:112
	ds_read_b128 v[76:79], v17 offset:128
	ds_read_b128 v[80:83], v17 offset:144
	ds_read_b128 v[84:87], v17 offset:160
	ds_read_b128 v[88:91], v17 offset:176
	ds_read_b128 v[92:95], v17 offset:192
	ds_read_b128 v[96:99], v17 offset:208
	ds_read_b128 v[100:103], v17 offset:224
	ds_read_b128 v[104:107], v17 offset:240
	s_addk_i32 s3, 0x100
	v_lshl_add_u64 v[40:41], v[40:41], 0, s[0:1]
	s_waitcnt vmcnt(10) lgkmcnt(14)
	v_pk_fma_f32 v[42:43], v[160:161], v[44:45], v[42:43] op_sel_hi:[0,1,1]
	v_pk_fma_f32 v[38:39], v[160:161], v[46:47], v[38:39] op_sel_hi:[0,1,1]
	v_pk_fma_f32 v[36:37], v[160:161], v[48:49], v[36:37] op_sel_hi:[0,1,1]
	v_pk_fma_f32 v[34:35], v[160:161], v[50:51], v[34:35] op_sel_hi:[0,1,1]
	s_waitcnt lgkmcnt(13)
	v_pk_fma_f32 v[32:33], v[160:161], v[52:53], v[32:33] op_sel_hi:[0,1,1]
	v_pk_fma_f32 v[30:31], v[160:161], v[54:55], v[30:31] op_sel_hi:[0,1,1]
	s_waitcnt lgkmcnt(12)
	v_pk_fma_f32 v[28:29], v[160:161], v[56:57], v[28:29] op_sel_hi:[0,1,1]
	v_pk_fma_f32 v[26:27], v[160:161], v[58:59], v[26:27] op_sel_hi:[0,1,1]
	s_waitcnt lgkmcnt(11)
	v_pk_fma_f32 v[24:25], v[160:161], v[60:61], v[24:25] op_sel_hi:[0,1,1]
	v_pk_fma_f32 v[22:23], v[160:161], v[62:63], v[22:23] op_sel_hi:[0,1,1]
	s_waitcnt lgkmcnt(10)
	v_pk_fma_f32 v[20:21], v[160:161], v[64:65], v[20:21] op_sel_hi:[0,1,1]
	v_pk_fma_f32 v[18:19], v[160:161], v[66:67], v[18:19] op_sel_hi:[0,1,1]
	s_waitcnt lgkmcnt(9)
	v_pk_fma_f32 v[14:15], v[160:161], v[68:69], v[14:15] op_sel_hi:[0,1,1]
	v_pk_fma_f32 v[12:13], v[160:161], v[70:71], v[12:13] op_sel_hi:[0,1,1]
	s_waitcnt lgkmcnt(8)
	v_pk_fma_f32 v[10:11], v[160:161], v[72:73], v[10:11] op_sel_hi:[0,1,1]
	v_pk_fma_f32 v[8:9], v[160:161], v[74:75], v[8:9] op_sel_hi:[0,1,1]
	s_waitcnt lgkmcnt(7)
	v_pk_fma_f32 v[42:43], v[162:163], v[76:77], v[42:43] op_sel_hi:[0,1,1]
	v_pk_fma_f32 v[38:39], v[162:163], v[78:79], v[38:39] op_sel_hi:[0,1,1]
	s_waitcnt lgkmcnt(6)
	v_pk_fma_f32 v[36:37], v[162:163], v[80:81], v[36:37] op_sel_hi:[0,1,1]
	v_pk_fma_f32 v[34:35], v[162:163], v[82:83], v[34:35] op_sel_hi:[0,1,1]
	s_waitcnt lgkmcnt(5)
	v_pk_fma_f32 v[32:33], v[162:163], v[84:85], v[32:33] op_sel_hi:[0,1,1]
	v_pk_fma_f32 v[30:31], v[162:163], v[86:87], v[30:31] op_sel_hi:[0,1,1]
	s_waitcnt lgkmcnt(4)
	v_pk_fma_f32 v[28:29], v[162:163], v[88:89], v[28:29] op_sel_hi:[0,1,1]
	v_pk_fma_f32 v[26:27], v[162:163], v[90:91], v[26:27] op_sel_hi:[0,1,1]
	s_waitcnt lgkmcnt(3)
	v_pk_fma_f32 v[24:25], v[162:163], v[92:93], v[24:25] op_sel_hi:[0,1,1]
	v_pk_fma_f32 v[22:23], v[162:163], v[94:95], v[22:23] op_sel_hi:[0,1,1]
	s_waitcnt lgkmcnt(2)
	v_pk_fma_f32 v[20:21], v[162:163], v[96:97], v[20:21] op_sel_hi:[0,1,1]
	v_pk_fma_f32 v[18:19], v[162:163], v[98:99], v[18:19] op_sel_hi:[0,1,1]
	s_waitcnt lgkmcnt(1)
	v_pk_fma_f32 v[14:15], v[162:163], v[100:101], v[14:15] op_sel_hi:[0,1,1]
	v_pk_fma_f32 v[12:13], v[162:163], v[102:103], v[12:13] op_sel_hi:[0,1,1]
	s_waitcnt lgkmcnt(0)
	v_pk_fma_f32 v[10:11], v[162:163], v[104:105], v[10:11] op_sel_hi:[0,1,1]
	v_pk_fma_f32 v[8:9], v[162:163], v[106:107], v[8:9] op_sel_hi:[0,1,1]
	s_add_i32 s8, s5, s3
	v_mov_b32_e32 v17, s8
	ds_read_b128 v[44:47], v17
	ds_read_b128 v[48:51], v17 offset:16
	ds_read_b128 v[52:55], v17 offset:32
	ds_read_b128 v[56:59], v17 offset:48
	ds_read_b128 v[60:63], v17 offset:64
	ds_read_b128 v[64:67], v17 offset:80
	ds_read_b128 v[68:71], v17 offset:96
	ds_read_b128 v[72:75], v17 offset:112
	ds_read_b128 v[76:79], v17 offset:128
	ds_read_b128 v[80:83], v17 offset:144
	ds_read_b128 v[84:87], v17 offset:160
	ds_read_b128 v[88:91], v17 offset:176
	ds_read_b128 v[92:95], v17 offset:192
	ds_read_b128 v[96:99], v17 offset:208
	ds_read_b128 v[100:103], v17 offset:224
	ds_read_b128 v[104:107], v17 offset:240
	s_addk_i32 s3, 0x100
	v_lshl_add_u64 v[40:41], v[40:41], 0, s[0:1]
	s_waitcnt vmcnt(8) lgkmcnt(14)
	v_pk_fma_f32 v[42:43], v[164:165], v[44:45], v[42:43] op_sel_hi:[0,1,1]
	v_pk_fma_f32 v[38:39], v[164:165], v[46:47], v[38:39] op_sel_hi:[0,1,1]
	v_pk_fma_f32 v[36:37], v[164:165], v[48:49], v[36:37] op_sel_hi:[0,1,1]
	v_pk_fma_f32 v[34:35], v[164:165], v[50:51], v[34:35] op_sel_hi:[0,1,1]
	s_waitcnt lgkmcnt(13)
; #define LAS __attribute__((address_space(3)))
; DI void bias2_item(const float* ada, const float* w1, float* bias2, LAS float* scr, int item, int lane) {
;     ...
;     for (int k = 0; k < 128; ++k) { const float w = wp[(size_t)k * 4096];
; #pragma unroll
;         for (int b4 = 0; b4 < 8; ++b4) { const f32x4 sv = *(const LAS f32x4*)(scr + k * 32 + b4 * 4);
;             acc[4 * b4] += sv[0] * w; acc[4 * b4 + 1] += sv[1] * w; acc[4 * b4 + 2] += sv[2] * w; acc[4 * b4 + 3] += sv[3] * w; } }
	v_pk_fma_f32 v[32:33], v[164:165], v[52:53], v[32:33] op_sel_hi:[0,1,1]
	v_pk_fma_f32 v[30:31], v[164:165], v[54:55], v[30:31] op_sel_hi:[0,1,1]
	s_waitcnt lgkmcnt(12)
	v_pk_fma_f32 v[28:29], v[164:165], v[56:57], v[28:29] op_sel_hi:[0,1,1]
	v_pk_fma_f32 v[26:27], v[164:165], v[58:59], v[26:27] op_sel_hi:[0,1,1]
	s_waitcnt lgkmcnt(11)
	v_pk_fma_f32 v[24:25], v[164:165], v[60:61], v[24:25] op_sel_hi:[0,1,1]
	v_pk_fma_f32 v[22:23], v[164:165], v[62:63], v[22:23] op_sel_hi:[0,1,1]
	s_waitcnt lgkmcnt(10)
	v_pk_fma_f32 v[20:21], v[164:165], v[64:65], v[20:21] op_sel_hi:[0,1,1]
	v_pk_fma_f32 v[18:19], v[164:165], v[66:67], v[18:19] op_sel_hi:[0,1,1]
	s_waitcnt lgkmcnt(9)
	v_pk_fma_f32 v[14:15], v[164:165], v[68:69], v[14:15] op_sel_hi:[0,1,1]
	v_pk_fma_f32 v[12:13], v[164:165], v[70:71], v[12:13] op_sel_hi:[0,1,1]
	s_waitcnt lgkmcnt(8)
	v_pk_fma_f32 v[10:11], v[164:165], v[72:73], v[10:11] op_sel_hi:[0,1,1]
	v_pk_fma_f32 v[8:9], v[164:165], v[74:75], v[8:9] op_sel_hi:[0,1,1]
	s_waitcnt lgkmcnt(7)
	v_pk_fma_f32 v[42:43], v[166:167], v[76:77], v[42:43] op_sel_hi:[0,1,1]
	v_pk_fma_f32 v[38:39], v[166:167], v[78:79], v[38:39] op_sel_hi:[0,1,1]
	s_waitcnt lgkmcnt(6)
	v_pk_fma_f32 v[36:37], v[166:167], v[80:81], v[36:37] op_sel_hi:[0,1,1]
	v_pk_fma_f32 v[34:35], v[166:167], v[82:83], v[34:35] op_sel_hi:[0,1,1]
	s_waitcnt lgkmcnt(5)
	v_pk_fma_f32 v[32:33], v[166:167], v[84:85], v[32:33] op_sel_hi:[0,1,1]
	v_pk_fma_f32 v[30:31], v[166:167], v[86:87], v[30:31] op_sel_hi:[0,1,1]
	s_waitcnt lgkmcnt(4)
	v_pk_fma_f32 v[28:29], v[166:167], v[88:89], v[28:29] op_sel_hi:[0,1,1]
	v_pk_fma_f32 v[26:27], v[166:167], v[90:91], v[26:27] op_sel_hi:[0,1,1]
	s_waitcnt lgkmcnt(3)
	v_pk_fma_f32 v[24:25], v[166:167], v[92:93], v[24:25] op_sel_hi:[0,1,1]
	v_pk_fma_f32 v[22:23], v[166:167], v[94:95], v[22:23] op_sel_hi:[0,1,1]
	s_waitcnt lgkmcnt(2)
	v_pk_fma_f32 v[20:21], v[166:167], v[96:97], v[20:21] op_sel_hi:[0,1,1]
	v_pk_fma_f32 v[18:19], v[166:167], v[98:99], v[18:19] op_sel_hi:[0,1,1]
	s_waitcnt lgkmcnt(1)
	v_pk_fma_f32 v[14:15], v[166:167], v[100:101], v[14:15] op_sel_hi:[0,1,1]
	v_pk_fma_f32 v[12:13], v[166:167], v[102:103], v[12:13] op_sel_hi:[0,1,1]
	s_waitcnt lgkmcnt(0)
	v_pk_fma_f32 v[10:11], v[166:167], v[104:105], v[10:11] op_sel_hi:[0,1,1]
	v_pk_fma_f32 v[8:9], v[166:167], v[106:107], v[8:9] op_sel_hi:[0,1,1]
	s_add_i32 s8, s5, s3
	v_mov_b32_e32 v17, s8
	ds_read_b128 v[44:47], v17
	ds_read_b128 v[48:51], v17 offset:16
	ds_read_b128 v[52:55], v17 offset:32
	ds_read_b128 v[56:59], v17 offset:48
	ds_read_b128 v[60:63], v17 offset:64
	ds_read_b128 v[64:67], v17 offset:80
	ds_read_b128 v[68:71], v17 offset:96
	ds_read_b128 v[72:75], v17 offset:112
	ds_read_b128 v[76:79], v17 offset:128
	ds_read_b128 v[80:83], v17 offset:144
	ds_read_b128 v[84:87], v17 offset:160
	ds_read_b128 v[88:91], v17 offset:176
	ds_read_b128 v[92:95], v17 offset:192
	ds_read_b128 v[96:99], v17 offset:208
	ds_read_b128 v[100:103], v17 offset:224
	ds_read_b128 v[104:107], v17 offset:240
	s_addk_i32 s3, 0x100
	v_lshl_add_u64 v[40:41], v[40:41], 0, s[0:1]
	s_waitcnt vmcnt(6) lgkmcnt(14)
	v_pk_fma_f32 v[42:43], v[168:169], v[44:45], v[42:43] op_sel_hi:[0,1,1]
	v_pk_fma_f32 v[38:39], v[168:169], v[46:47], v[38:39] op_sel_hi:[0,1,1]
	v_pk_fma_f32 v[36:37], v[168:169], v[48:49], v[36:37] op_sel_hi:[0,1,1]
	v_pk_fma_f32 v[34:35], v[168:169], v[50:51], v[34:35] op_sel_hi:[0,1,1]
	s_waitcnt lgkmcnt(13)
	v_pk_fma_f32 v[32:33], v[168:169], v[52:53], v[32:33] op_sel_hi:[0,1,1]
	v_pk_fma_f32 v[30:31], v[168:169], v[54:55], v[30:31] op_sel_hi:[0,1,1]
	s_waitcnt lgkmcnt(12)
	v_pk_fma_f32 v[28:29], v[168:169], v[56:57], v[28:29] op_sel_hi:[0,1,1]
	v_pk_fma_f32 v[26:27], v[168:169], v[58:59], v[26:27] op_sel_hi:[0,1,1]
	s_waitcnt lgkmcnt(11)
	v_pk_fma_f32 v[24:25], v[168:169], v[60:61], v[24:25] op_sel_hi:[0,1,1]
	v_pk_fma_f32 v[22:23], v[168:169], v[62:63], v[22:23] op_sel_hi:[0,1,1]
	s_waitcnt lgkmcnt(10)
	v_pk_fma_f32 v[20:21], v[168:169], v[64:65], v[20:21] op_sel_hi:[0,1,1]
	v_pk_fma_f32 v[18:19], v[168:169], v[66:67], v[18:19] op_sel_hi:[0,1,1]
	s_waitcnt lgkmcnt(9)
	v_pk_fma_f32 v[14:15], v[168:169], v[68:69], v[14:15] op_sel_hi:[0,1,1]
	v_pk_fma_f32 v[12:13], v[168:169], v[70:71], v[12:13] op_sel_hi:[0,1,1]
	s_waitcnt lgkmcnt(8)
	v_pk_fma_f32 v[10:11], v[168:169], v[72:73], v[10:11] op_sel_hi:[0,1,1]
	v_pk_fma_f32 v[8:9], v[168:169], v[74:75], v[8:9] op_sel_hi:[0,1,1]
	s_waitcnt lgkmcnt(7)
	v_pk_fma_f32 v[42:43], v[170:171], v[76:77], v[42:43] op_sel_hi:[0,1,1]
	v_pk_fma_f32 v[38:39], v[170:171], v[78:79], v[38:39] op_sel_hi:[0,1,1]
	s_waitcnt lgkmcnt(6)
	v_pk_fma_f32 v[36:37], v[170:171], v[80:81], v[36:37] op_sel_hi:[0,1,1]
	v_pk_fma_f32 v[34:35], v[170:171], v[82:83], v[34:35] op_sel_hi:[0,1,1]
	s_waitcnt lgkmcnt(5)
	v_pk_fma_f32 v[32:33], v[170:171], v[84:85], v[32:33] op_sel_hi:[0,1,1]
	v_pk_fma_f32 v[30:31], v[170:171], v[86:87], v[30:31] op_sel_hi:[0,1,1]
	s_waitcnt lgkmcnt(4)
	v_pk_fma_f32 v[28:29], v[170:171], v[88:89], v[28:29] op_sel_hi:[0,1,1]
	v_pk_fma_f32 v[26:27], v[170:171], v[90:91], v[26:27] op_sel_hi:[0,1,1]
	s_waitcnt lgkmcnt(3)
	v_pk_fma_f32 v[24:25], v[170:171], v[92:93], v[24:25] op_sel_hi:[0,1,1]
	v_pk_fma_f32 v[22:23], v[170:171], v[94:95], v[22:23] op_sel_hi:[0,1,1]
	s_waitcnt lgkmcnt(2)
	v_pk_fma_f32 v[20:21], v[170:171], v[96:97], v[20:21] op_sel_hi:[0,1,1]
	v_pk_fma_f32 v[18:19], v[170:171], v[98:99], v[18:19] op_sel_hi:[0,1,1]
	s_waitcnt lgkmcnt(1)
	v_pk_fma_f32 v[14:15], v[170:171], v[100:101], v[14:15] op_sel_hi:[0,1,1]
	v_pk_fma_f32 v[12:13], v[170:171], v[102:103], v[12:13] op_sel_hi:[0,1,1]
	s_waitcnt lgkmcnt(0)
; #define LAS __attribute__((address_space(3)))
; DI void bias2_item(const float* ada, const float* w1, float* bias2, LAS float* scr, int item, int lane) {
;     ...
;     for (int k = 0; k < 128; ++k) { const float w = wp[(size_t)k * 4096];
; #pragma unroll
;         for (int b4 = 0; b4 < 8; ++b4) { const f32x4 sv = *(const LAS f32x4*)(scr + k * 32 + b4 * 4);
;             acc[4 * b4] += sv[0] * w; acc[4 * b4 + 1] += sv[1] * w; acc[4 * b4 + 2] += sv[2] * w; acc[4 * b4 + 3] += sv[3] * w; } }
	v_pk_fma_f32 v[10:11], v[170:171], v[104:105], v[10:11] op_sel_hi:[0,1,1]
	v_pk_fma_f32 v[8:9], v[170:171], v[106:107], v[8:9] op_sel_hi:[0,1,1]
	s_add_i32 s8, s5, s3
	v_mov_b32_e32 v17, s8
	ds_read_b128 v[44:47], v17
	ds_read_b128 v[48:51], v17 offset:16
	ds_read_b128 v[52:55], v17 offset:32
	ds_read_b128 v[56:59], v17 offset:48
	ds_read_b128 v[60:63], v17 offset:64
	ds_read_b128 v[64:67], v17 offset:80
	ds_read_b128 v[68:71], v17 offset:96
	ds_read_b128 v[72:75], v17 offset:112
	ds_read_b128 v[76:79], v17 offset:128
	ds_read_b128 v[80:83], v17 offset:144
	ds_read_b128 v[84:87], v17 offset:160
	ds_read_b128 v[88:91], v17 offset:176
	ds_read_b128 v[92:95], v17 offset:192
	ds_read_b128 v[96:99], v17 offset:208
	ds_read_b128 v[100:103], v17 offset:224
	ds_read_b128 v[104:107], v17 offset:240
	s_addk_i32 s3, 0x100
	v_lshl_add_u64 v[40:41], v[40:41], 0, s[0:1]
	s_waitcnt vmcnt(4) lgkmcnt(14)
	v_pk_fma_f32 v[42:43], v[172:173], v[44:45], v[42:43] op_sel_hi:[0,1,1]
	v_pk_fma_f32 v[38:39], v[172:173], v[46:47], v[38:39] op_sel_hi:[0,1,1]
	v_pk_fma_f32 v[36:37], v[172:173], v[48:49], v[36:37] op_sel_hi:[0,1,1]
	v_pk_fma_f32 v[34:35], v[172:173], v[50:51], v[34:35] op_sel_hi:[0,1,1]
	s_waitcnt lgkmcnt(13)
	v_pk_fma_f32 v[32:33], v[172:173], v[52:53], v[32:33] op_sel_hi:[0,1,1]
	v_pk_fma_f32 v[30:31], v[172:173], v[54:55], v[30:31] op_sel_hi:[0,1,1]
	s_waitcnt lgkmcnt(12)
	v_pk_fma_f32 v[28:29], v[172:173], v[56:57], v[28:29] op_sel_hi:[0,1,1]
	v_pk_fma_f32 v[26:27], v[172:173], v[58:59], v[26:27] op_sel_hi:[0,1,1]
	s_waitcnt lgkmcnt(11)
	v_pk_fma_f32 v[24:25], v[172:173], v[60:61], v[24:25] op_sel_hi:[0,1,1]
	v_pk_fma_f32 v[22:23], v[172:173], v[62:63], v[22:23] op_sel_hi:[0,1,1]
	s_waitcnt lgkmcnt(10)
	v_pk_fma_f32 v[20:21], v[172:173], v[64:65], v[20:21] op_sel_hi:[0,1,1]
	v_pk_fma_f32 v[18:19], v[172:173], v[66:67], v[18:19] op_sel_hi:[0,1,1]
	s_waitcnt lgkmcnt(9)
	v_pk_fma_f32 v[14:15], v[172:173], v[68:69], v[14:15] op_sel_hi:[0,1,1]
	v_pk_fma_f32 v[12:13], v[172:173], v[70:71], v[12:13] op_sel_hi:[0,1,1]
	s_waitcnt lgkmcnt(8)
	v_pk_fma_f32 v[10:11], v[172:173], v[72:73], v[10:11] op_sel_hi:[0,1,1]
	v_pk_fma_f32 v[8:9], v[172:173], v[74:75], v[8:9] op_sel_hi:[0,1,1]
	s_waitcnt lgkmcnt(7)
	v_pk_fma_f32 v[42:43], v[174:175], v[76:77], v[42:43] op_sel_hi:[0,1,1]
	v_pk_fma_f32 v[38:39], v[174:175], v[78:79], v[38:39] op_sel_hi:[0,1,1]
	s_waitcnt lgkmcnt(6)
	v_pk_fma_f32 v[36:37], v[174:175], v[80:81], v[36:37] op_sel_hi:[0,1,1]
	v_pk_fma_f32 v[34:35], v[174:175], v[82:83], v[34:35] op_sel_hi:[0,1,1]
	s_waitcnt lgkmcnt(5)
	v_pk_fma_f32 v[32:33], v[174:175], v[84:85], v[32:33] op_sel_hi:[0,1,1]
	v_pk_fma_f32 v[30:31], v[174:175], v[86:87], v[30:31] op_sel_hi:[0,1,1]
	s_waitcnt lgkmcnt(4)
	v_pk_fma_f32 v[28:29], v[174:175], v[88:89], v[28:29] op_sel_hi:[0,1,1]
	v_pk_fma_f32 v[26:27], v[174:175], v[90:91], v[26:27] op_sel_hi:[0,1,1]
	s_waitcnt lgkmcnt(3)
	v_pk_fma_f32 v[24:25], v[174:175], v[92:93], v[24:25] op_sel_hi:[0,1,1]
	v_pk_fma_f32 v[22:23], v[174:175], v[94:95], v[22:23] op_sel_hi:[0,1,1]
	s_waitcnt lgkmcnt(2)
	v_pk_fma_f32 v[20:21], v[174:175], v[96:97], v[20:21] op_sel_hi:[0,1,1]
	v_pk_fma_f32 v[18:19], v[174:175], v[98:99], v[18:19] op_sel_hi:[0,1,1]
	s_waitcnt lgkmcnt(1)
	v_pk_fma_f32 v[14:15], v[174:175], v[100:101], v[14:15] op_sel_hi:[0,1,1]
	v_pk_fma_f32 v[12:13], v[174:175], v[102:103], v[12:13] op_sel_hi:[0,1,1]
	s_waitcnt lgkmcnt(0)
	v_pk_fma_f32 v[10:11], v[174:175], v[104:105], v[10:11] op_sel_hi:[0,1,1]
	v_pk_fma_f32 v[8:9], v[174:175], v[106:107], v[8:9] op_sel_hi:[0,1,1]
	s_add_i32 s8, s5, s3
	v_mov_b32_e32 v17, s8
	ds_read_b128 v[44:47], v17
	ds_read_b128 v[48:51], v17 offset:16
	ds_read_b128 v[52:55], v17 offset:32
	ds_read_b128 v[56:59], v17 offset:48
	ds_read_b128 v[60:63], v17 offset:64
	ds_read_b128 v[64:67], v17 offset:80
	ds_read_b128 v[68:71], v17 offset:96
	ds_read_b128 v[72:75], v17 offset:112
	ds_read_b128 v[76:79], v17 offset:128
	ds_read_b128 v[80:83], v17 offset:144
	ds_read_b128 v[84:87], v17 offset:160
	ds_read_b128 v[88:91], v17 offset:176
	ds_read_b128 v[92:95], v17 offset:192
	ds_read_b128 v[96:99], v17 offset:208
	ds_read_b128 v[100:103], v17 offset:224
	ds_read_b128 v[104:107], v17 offset:240
	s_addk_i32 s3, 0x100
	v_lshl_add_u64 v[40:41], v[40:41], 0, s[0:1]
	s_waitcnt vmcnt(2) lgkmcnt(14)
	v_pk_fma_f32 v[42:43], v[176:177], v[44:45], v[42:43] op_sel_hi:[0,1,1]
	v_pk_fma_f32 v[38:39], v[176:177], v[46:47], v[38:39] op_sel_hi:[0,1,1]
	v_pk_fma_f32 v[36:37], v[176:177], v[48:49], v[36:37] op_sel_hi:[0,1,1]
	v_pk_fma_f32 v[34:35], v[176:177], v[50:51], v[34:35] op_sel_hi:[0,1,1]
	s_waitcnt lgkmcnt(13)
	v_pk_fma_f32 v[32:33], v[176:177], v[52:53], v[32:33] op_sel_hi:[0,1,1]
	v_pk_fma_f32 v[30:31], v[176:177], v[54:55], v[30:31] op_sel_hi:[0,1,1]
	s_waitcnt lgkmcnt(12)
	v_pk_fma_f32 v[28:29], v[176:177], v[56:57], v[28:29] op_sel_hi:[0,1,1]
	v_pk_fma_f32 v[26:27], v[176:177], v[58:59], v[26:27] op_sel_hi:[0,1,1]
	s_waitcnt lgkmcnt(11)
	v_pk_fma_f32 v[24:25], v[176:177], v[60:61], v[24:25] op_sel_hi:[0,1,1]
	v_pk_fma_f32 v[22:23], v[176:177], v[62:63], v[22:23] op_sel_hi:[0,1,1]
	s_waitcnt lgkmcnt(10)
	v_pk_fma_f32 v[20:21], v[176:177], v[64:65], v[20:21] op_sel_hi:[0,1,1]
	v_pk_fma_f32 v[18:19], v[176:177], v[66:67], v[18:19] op_sel_hi:[0,1,1]
	s_waitcnt lgkmcnt(9)
	v_pk_fma_f32 v[14:15], v[176:177], v[68:69], v[14:15] op_sel_hi:[0,1,1]
	v_pk_fma_f32 v[12:13], v[176:177], v[70:71], v[12:13] op_sel_hi:[0,1,1]
	s_waitcnt lgkmcnt(8)
	v_pk_fma_f32 v[10:11], v[176:177], v[72:73], v[10:11] op_sel_hi:[0,1,1]
	v_pk_fma_f32 v[8:9], v[176:177], v[74:75], v[8:9] op_sel_hi:[0,1,1]
	s_waitcnt lgkmcnt(7)
; #define LAS __attribute__((address_space(3)))
; DI void bias2_item(const float* ada, const float* w1, float* bias2, LAS float* scr, int item, int lane) {
;     ...
;     for (int k = 0; k < 128; ++k) { const float w = wp[(size_t)k * 4096];
; #pragma unroll
;         for (int b4 = 0; b4 < 8; ++b4) { const f32x4 sv = *(const LAS f32x4*)(scr + k * 32 + b4 * 4);
;             acc[4 * b4] += sv[0] * w; acc[4 * b4 + 1] += sv[1] * w; acc[4 * b4 + 2] += sv[2] * w; acc[4 * b4 + 3] += sv[3] * w; } }
	v_pk_fma_f32 v[42:43], v[178:179], v[76:77], v[42:43] op_sel_hi:[0,1,1]
	v_pk_fma_f32 v[38:39], v[178:179], v[78:79], v[38:39] op_sel_hi:[0,1,1]
	s_waitcnt lgkmcnt(6)
	v_pk_fma_f32 v[36:37], v[178:179], v[80:81], v[36:37] op_sel_hi:[0,1,1]
	v_pk_fma_f32 v[34:35], v[178:179], v[82:83], v[34:35] op_sel_hi:[0,1,1]
	s_waitcnt lgkmcnt(5)
	v_pk_fma_f32 v[32:33], v[178:179], v[84:85], v[32:33] op_sel_hi:[0,1,1]
	v_pk_fma_f32 v[30:31], v[178:179], v[86:87], v[30:31] op_sel_hi:[0,1,1]
	s_waitcnt lgkmcnt(4)
	v_pk_fma_f32 v[28:29], v[178:179], v[88:89], v[28:29] op_sel_hi:[0,1,1]
	v_pk_fma_f32 v[26:27], v[178:179], v[90:91], v[26:27] op_sel_hi:[0,1,1]
	s_waitcnt lgkmcnt(3)
	v_pk_fma_f32 v[24:25], v[178:179], v[92:93], v[24:25] op_sel_hi:[0,1,1]
	v_pk_fma_f32 v[22:23], v[178:179], v[94:95], v[22:23] op_sel_hi:[0,1,1]
	s_waitcnt lgkmcnt(2)
	v_pk_fma_f32 v[20:21], v[178:179], v[96:97], v[20:21] op_sel_hi:[0,1,1]
	v_pk_fma_f32 v[18:19], v[178:179], v[98:99], v[18:19] op_sel_hi:[0,1,1]
	s_waitcnt lgkmcnt(1)
	v_pk_fma_f32 v[14:15], v[178:179], v[100:101], v[14:15] op_sel_hi:[0,1,1]
	v_pk_fma_f32 v[12:13], v[178:179], v[102:103], v[12:13] op_sel_hi:[0,1,1]
	s_waitcnt lgkmcnt(0)
	v_pk_fma_f32 v[10:11], v[178:179], v[104:105], v[10:11] op_sel_hi:[0,1,1]
	v_pk_fma_f32 v[8:9], v[178:179], v[106:107], v[8:9] op_sel_hi:[0,1,1]
	s_add_i32 s8, s5, s3
	v_mov_b32_e32 v17, s8
	ds_read_b128 v[44:47], v17
	ds_read_b128 v[48:51], v17 offset:16
	ds_read_b128 v[52:55], v17 offset:32
	ds_read_b128 v[56:59], v17 offset:48
	ds_read_b128 v[60:63], v17 offset:64
	ds_read_b128 v[64:67], v17 offset:80
	ds_read_b128 v[68:71], v17 offset:96
	ds_read_b128 v[72:75], v17 offset:112
	ds_read_b128 v[76:79], v17 offset:128
	ds_read_b128 v[80:83], v17 offset:144
	ds_read_b128 v[84:87], v17 offset:160
	ds_read_b128 v[88:91], v17 offset:176
	ds_read_b128 v[92:95], v17 offset:192
	ds_read_b128 v[96:99], v17 offset:208
	ds_read_b128 v[100:103], v17 offset:224
	ds_read_b128 v[104:107], v17 offset:240
	s_addk_i32 s3, 0x100
	v_lshl_add_u64 v[40:41], v[40:41], 0, s[0:1]
	s_waitcnt vmcnt(0) lgkmcnt(14)
	v_pk_fma_f32 v[42:43], v[180:181], v[44:45], v[42:43] op_sel_hi:[0,1,1]
	v_pk_fma_f32 v[38:39], v[180:181], v[46:47], v[38:39] op_sel_hi:[0,1,1]
	v_pk_fma_f32 v[36:37], v[180:181], v[48:49], v[36:37] op_sel_hi:[0,1,1]
	v_pk_fma_f32 v[34:35], v[180:181], v[50:51], v[34:35] op_sel_hi:[0,1,1]
	s_waitcnt lgkmcnt(13)
	v_pk_fma_f32 v[32:33], v[180:181], v[52:53], v[32:33] op_sel_hi:[0,1,1]
	v_pk_fma_f32 v[30:31], v[180:181], v[54:55], v[30:31] op_sel_hi:[0,1,1]
	s_waitcnt lgkmcnt(12)
	v_pk_fma_f32 v[28:29], v[180:181], v[56:57], v[28:29] op_sel_hi:[0,1,1]
	v_pk_fma_f32 v[26:27], v[180:181], v[58:59], v[26:27] op_sel_hi:[0,1,1]
	s_waitcnt lgkmcnt(11)
	v_pk_fma_f32 v[24:25], v[180:181], v[60:61], v[24:25] op_sel_hi:[0,1,1]
	v_pk_fma_f32 v[22:23], v[180:181], v[62:63], v[22:23] op_sel_hi:[0,1,1]
	s_waitcnt lgkmcnt(10)
	v_pk_fma_f32 v[20:21], v[180:181], v[64:65], v[20:21] op_sel_hi:[0,1,1]
	v_pk_fma_f32 v[18:19], v[180:181], v[66:67], v[18:19] op_sel_hi:[0,1,1]
	s_waitcnt lgkmcnt(9)
	v_pk_fma_f32 v[14:15], v[180:181], v[68:69], v[14:15] op_sel_hi:[0,1,1]
	v_pk_fma_f32 v[12:13], v[180:181], v[70:71], v[12:13] op_sel_hi:[0,1,1]
	s_waitcnt lgkmcnt(8)
	v_pk_fma_f32 v[10:11], v[180:181], v[72:73], v[10:11] op_sel_hi:[0,1,1]
	v_pk_fma_f32 v[8:9], v[180:181], v[74:75], v[8:9] op_sel_hi:[0,1,1]
	s_waitcnt lgkmcnt(7)
	v_pk_fma_f32 v[42:43], v[182:183], v[76:77], v[42:43] op_sel_hi:[0,1,1]
	v_pk_fma_f32 v[38:39], v[182:183], v[78:79], v[38:39] op_sel_hi:[0,1,1]
	s_waitcnt lgkmcnt(6)
	v_pk_fma_f32 v[36:37], v[182:183], v[80:81], v[36:37] op_sel_hi:[0,1,1]
	v_pk_fma_f32 v[34:35], v[182:183], v[82:83], v[34:35] op_sel_hi:[0,1,1]
	s_waitcnt lgkmcnt(5)
	v_pk_fma_f32 v[32:33], v[182:183], v[84:85], v[32:33] op_sel_hi:[0,1,1]
	v_pk_fma_f32 v[30:31], v[182:183], v[86:87], v[30:31] op_sel_hi:[0,1,1]
	s_waitcnt lgkmcnt(4)
	v_pk_fma_f32 v[28:29], v[182:183], v[88:89], v[28:29] op_sel_hi:[0,1,1]
	v_pk_fma_f32 v[26:27], v[182:183], v[90:91], v[26:27] op_sel_hi:[0,1,1]
	s_waitcnt lgkmcnt(3)
	v_pk_fma_f32 v[24:25], v[182:183], v[92:93], v[24:25] op_sel_hi:[0,1,1]
	v_pk_fma_f32 v[22:23], v[182:183], v[94:95], v[22:23] op_sel_hi:[0,1,1]
	s_waitcnt lgkmcnt(2)
	v_pk_fma_f32 v[20:21], v[182:183], v[96:97], v[20:21] op_sel_hi:[0,1,1]
	v_pk_fma_f32 v[18:19], v[182:183], v[98:99], v[18:19] op_sel_hi:[0,1,1]
	s_waitcnt lgkmcnt(1)
	v_pk_fma_f32 v[14:15], v[182:183], v[100:101], v[14:15] op_sel_hi:[0,1,1]
	v_pk_fma_f32 v[12:13], v[182:183], v[102:103], v[12:13] op_sel_hi:[0,1,1]
	s_waitcnt lgkmcnt(0)
; DI void bias2_item(const float* ada, const float* w1, float* bias2, LAS float* scr, int item, int lane) {
;     ...
;     const int col = cb * 64 + lane;
; #pragma unroll
;     for (int b = 0; b < 32; ++b) atomicAdd(bias2 + b * 4096 + col, acc[b]);
	v_pk_fma_f32 v[10:11], v[182:183], v[104:105], v[10:11] op_sel_hi:[0,1,1]
	v_pk_fma_f32 v[8:9], v[182:183], v[106:107], v[8:9] op_sel_hi:[0,1,1]
	v_or_b32_e32 v40, s2, v16
	v_readlane_b32 s2, v251, 44
	v_ashrrev_i32_e32 v41, 31, v40
	v_readlane_b32 s3, v251, 45
	s_add_i32 s7, s7, s10
	s_cmpk_gt_i32 s7, 0x1ff
	v_lshl_add_u64 v[40:41], v[40:41], 2, s[2:3]
	v_add_co_u32_e32 v44, vcc, 0x4000, v40
	global_atomic_add_f32 v[40:41], v42, off
	s_nop 0
	v_addc_co_u32_e32 v45, vcc, 0, v41, vcc
	v_add_co_u32_e32 v42, vcc, 0x8000, v40
	global_atomic_add_f32 v[44:45], v43, off
	s_nop 0
	v_addc_co_u32_e32 v43, vcc, 0, v41, vcc
	global_atomic_add_f32 v[42:43], v38, off
	v_add_co_u32_e32 v42, vcc, 0xc000, v40
	s_nop 1
	v_addc_co_u32_e32 v43, vcc, 0, v41, vcc
	v_add_co_u32_e32 v38, vcc, 0x10000, v40
	global_atomic_add_f32 v[42:43], v39, off
	s_nop 0
	v_addc_co_u32_e32 v39, vcc, 0, v41, vcc
	global_atomic_add_f32 v[38:39], v36, off
	v_add_co_u32_e32 v38, vcc, 0x14000, v40
	s_nop 1
	v_addc_co_u32_e32 v39, vcc, 0, v41, vcc
	v_add_co_u32_e32 v36, vcc, 0x18000, v40
	global_atomic_add_f32 v[38:39], v37, off
	s_nop 0
	v_addc_co_u32_e32 v37, vcc, 0, v41, vcc
	global_atomic_add_f32 v[36:37], v34, off
	v_add_co_u32_e32 v36, vcc, 0x1c000, v40
	s_nop 1
	v_addc_co_u32_e32 v37, vcc, 0, v41, vcc
	v_add_co_u32_e32 v34, vcc, 0x20000, v40
	global_atomic_add_f32 v[36:37], v35, off
	s_nop 0
	v_addc_co_u32_e32 v35, vcc, 0, v41, vcc
	global_atomic_add_f32 v[34:35], v32, off
	v_add_co_u32_e32 v34, vcc, 0x24000, v40
	s_nop 1
	v_addc_co_u32_e32 v35, vcc, 0, v41, vcc
	v_add_co_u32_e32 v32, vcc, 0x28000, v40
	global_atomic_add_f32 v[34:35], v33, off
	s_nop 0
	v_addc_co_u32_e32 v33, vcc, 0, v41, vcc
	global_atomic_add_f32 v[32:33], v30, off
	v_add_co_u32_e32 v32, vcc, 0x2c000, v40
	s_nop 1
	v_addc_co_u32_e32 v33, vcc, 0, v41, vcc
	v_add_co_u32_e32 v30, vcc, 0x30000, v40
	global_atomic_add_f32 v[32:33], v31, off
	s_nop 0
	v_addc_co_u32_e32 v31, vcc, 0, v41, vcc
	global_atomic_add_f32 v[30:31], v28, off
	v_add_co_u32_e32 v30, vcc, 0x34000, v40
	s_nop 1
	v_addc_co_u32_e32 v31, vcc, 0, v41, vcc
	v_add_co_u32_e32 v28, vcc, 0x38000, v40
	global_atomic_add_f32 v[30:31], v29, off
	s_nop 0
	v_addc_co_u32_e32 v29, vcc, 0, v41, vcc
	global_atomic_add_f32 v[28:29], v26, off
	v_add_co_u32_e32 v28, vcc, 0x3c000, v40
	s_nop 1
	v_addc_co_u32_e32 v29, vcc, 0, v41, vcc
	v_add_co_u32_e32 v26, vcc, 0x40000, v40
	global_atomic_add_f32 v[28:29], v27, off
	s_nop 0
	v_addc_co_u32_e32 v27, vcc, 0, v41, vcc
	global_atomic_add_f32 v[26:27], v24, off
	v_add_co_u32_e32 v26, vcc, 0x44000, v40
	s_nop 1
	v_addc_co_u32_e32 v27, vcc, 0, v41, vcc
	v_add_co_u32_e32 v24, vcc, 0x48000, v40
	global_atomic_add_f32 v[26:27], v25, off
	s_nop 0
	v_addc_co_u32_e32 v25, vcc, 0, v41, vcc
	global_atomic_add_f32 v[24:25], v22, off
	v_add_co_u32_e32 v24, vcc, 0x4c000, v40
	s_nop 1
	v_addc_co_u32_e32 v25, vcc, 0, v41, vcc
	v_add_co_u32_e32 v22, vcc, 0x50000, v40
	global_atomic_add_f32 v[24:25], v23, off
	s_nop 0
	v_addc_co_u32_e32 v23, vcc, 0, v41, vcc
	global_atomic_add_f32 v[22:23], v20, off
	v_add_co_u32_e32 v22, vcc, 0x54000, v40
	s_nop 1
	v_addc_co_u32_e32 v23, vcc, 0, v41, vcc
	v_add_co_u32_e32 v20, vcc, 0x58000, v40
	global_atomic_add_f32 v[22:23], v21, off
	s_nop 0
	v_addc_co_u32_e32 v21, vcc, 0, v41, vcc
	global_atomic_add_f32 v[20:21], v18, off
	v_add_co_u32_e32 v20, vcc, 0x5c000, v40
	s_nop 1
	v_addc_co_u32_e32 v21, vcc, 0, v41, vcc
	v_add_co_u32_e32 v18, vcc, 0x60000, v40
	global_atomic_add_f32 v[20:21], v19, off
	s_nop 0
	v_addc_co_u32_e32 v19, vcc, 0, v41, vcc
	global_atomic_add_f32 v[18:19], v14, off
	v_add_co_u32_e32 v18, vcc, 0x64000, v40
	s_nop 1
	v_addc_co_u32_e32 v19, vcc, 0, v41, vcc
	v_add_co_u32_e32 v14, vcc, 0x68000, v40
	global_atomic_add_f32 v[18:19], v15, off
	s_nop 0
	v_addc_co_u32_e32 v15, vcc, 0, v41, vcc
	global_atomic_add_f32 v[14:15], v12, off
	v_add_co_u32_e32 v14, vcc, 0x6c000, v40
	s_nop 1
	v_addc_co_u32_e32 v15, vcc, 0, v41, vcc
	v_add_co_u32_e32 v12, vcc, 0x70000, v40
	global_atomic_add_f32 v[14:15], v13, off
	s_nop 0
	v_addc_co_u32_e32 v13, vcc, 0, v41, vcc
	global_atomic_add_f32 v[12:13], v10, off
	v_add_co_u32_e32 v12, vcc, 0x74000, v40
	s_nop 1
	v_addc_co_u32_e32 v13, vcc, 0, v41, vcc
	v_add_co_u32_e32 v10, vcc, 0x78000, v40
	global_atomic_add_f32 v[12:13], v11, off
	s_nop 0
	v_addc_co_u32_e32 v11, vcc, 0, v41, vcc
	global_atomic_add_f32 v[10:11], v8, off
	v_add_co_u32_e32 v10, vcc, 0x7c000, v40
	s_nop 1
	v_addc_co_u32_e32 v11, vcc, 0, v41, vcc
	global_atomic_add_f32 v[10:11], v9, off
	s_waitcnt lgkmcnt(0)
	s_cbranch_scc0 .LBB0_78
